# v71 plus LDS-DMA loads in GEMM K-loops use the SGPR-base + 32-bit lane-offset form, dropping 220 64-bit VALU address adds
# baseline (speedup 1.0000x reference)
.LBB0_187:
	s_add_u32 s24, s78, 0x4b400000
	s_addc_u32 s25, s79, 0
	s_bfe_u32 s1, s88, 0x20006
	s_lshl_b32 s33, s0, 6
	s_lshl_b32 s49, s1, 5
	s_add_u32 s6, s4, 0x8000
	s_addc_u32 s7, s5, 0
	s_add_i32 m0, s18, 0x18000
	s_waitcnt vmcnt(2)
	s_barrier
	global_load_lds_dwordx4 v134, s[6:7]
	s_add_i32 m0, s18, 0x1a000
	s_mov_b64 s[30:31], 0x80
	s_add_i32 s51, s18, 0x8000
	s_add_i32 s56, s18, 0xa000
	global_load_lds_dwordx4 v138, s[6:7]
	v_lshl_add_u64 v[2:3], v[2:3], 0, s[30:31]
	s_mov_b32 m0, s51
	s_add_u32 s6, s4, 0xc000
	global_load_lds_dwordx4 v[2:3], off
	v_lshl_add_u64 v[2:3], v[4:5], 0, s[30:31]
	s_mov_b32 m0, s56
	s_addc_u32 s7, s5, 0
	global_load_lds_dwordx4 v[2:3], off
	s_add_i32 m0, s18, 0x1c000
	s_nop 0
	global_load_lds_dwordx4 v134, s[6:7]
	v_lshl_add_u64 v[2:3], s[6:7], 0, v[138:139]
	s_add_i32 m0, s18, 0x1e000
	v_and_b32_e32 v158, 15, v1
	global_load_lds_dwordx4 v[2:3], off
	v_ashrrev_i32_e32 v159, 4, v1
	v_and_b32_e32 v2, 48, v1
	v_and_b32_e32 v3, 0xfffffc00, v9
	v_lshlrev_b32_e32 v1, 2, v1
	v_lshl_add_u32 v4, s0, 13, v3
	v_lshl_or_b32 v2, v158, 6, v2
	v_and_b32_e32 v1, 32, v1
	v_lshl_add_u32 v3, s1, 12, v3
	v_bitop3_b32 v4, v2, v4, v1 bitop3:0xde
	v_bitop3_b32 v160, v2, v3, v1 bitop3:0xde
	v_lshlrev_b32_e32 v1, 16, v6
	v_and_b32_e32 v1, 0xfffe0000, v1
	v_lshl_add_u32 v1, v7, 13, v1
	v_and_b32_e32 v2, 1, v6
	v_lshl_or_b32 v1, v2, 6, v1
	s_cmpk_lt_u32 s88, 0x100
	v_lshl_add_u32 v2, v8, 1, v1
	v_lshlrev_b32_e32 v1, 16, v10
	s_cselect_b64 s[34:35], -1, 0
	s_lshl_b32 s57, s1, 4
	v_mov_b32_e32 v3, v0
	s_mov_b64 s[0:1], 0x100080
	v_and_b32_e32 v1, 0xfffe0000, v1
	v_lshl_add_u64 v[140:141], v[2:3], 0, s[0:1]
	v_lshl_add_u32 v1, v11, 13, v1
	v_and_b32_e32 v2, 1, v10
	s_waitcnt vmcnt(6)
	v_lshl_or_b32 v1, v2, 6, v1
	v_lshl_add_u32 v2, v12, 1, v1
	s_add_i32 s60, 0, 0x10000
	s_add_i32 s61, 0, 0x14000
	s_ashr_i32 s58, s77, 31
	s_ashr_i32 s59, s90, 31
	v_lshl_add_u64 v[142:143], v[2:3], 0, s[0:1]
	v_mov_b64_e32 v[146:147], 0xfff
	v_add_u32_e32 v161, s60, v160
	v_add_u32_e32 v162, s61, v160
	v_add_u32_e32 v163, 0, v4
	s_mov_b64 s[36:37], 0x100
	s_mov_b64 s[38:39], 0x180
	v_mov_b32_e32 v164, 0x3d800000
	s_mov_b32 s22, 0
	s_barrier
	s_branch .LBB0_190

.LBB0_196:
	s_cmp_lg_u32 s22, 0
	s_mov_b32 s22, 0
	s_cbranch_scc0 .LBB0_198
	ds_read_b128 v[2:5], v161
	ds_read_b128 v[6:9], v161 offset:1024
	ds_read_b128 v[10:13], v161 offset:2048
	ds_read_b128 v[14:17], v161 offset:3072
	ds_read_b128 v[18:21], v162
	ds_read_b128 v[22:25], v162 offset:1024
	ds_read_b128 v[26:29], v162 offset:2048
	ds_read_b128 v[30:33], v162 offset:3072
	s_add_u32 s0, s4, 0x10000
	s_addc_u32 s1, s5, 0
	ds_read_b128 v[34:37], v163
	ds_read_b128 v[38:41], v163 offset:1024
	ds_read_b128 v[42:45], v163 offset:2048
	ds_read_b128 v[46:49], v163 offset:3072
	ds_read_b128 v[50:53], v163 offset:4096
	ds_read_b128 v[54:57], v163 offset:5120
	ds_read_b128 v[58:61], v163 offset:6144
	ds_read_b128 v[62:65], v163 offset:7168
	s_waitcnt vmcnt(24) lgkmcnt(0)
	s_barrier
	v_mfma_f32_16x16x32_bf16 v[90:93], v[2:5], v[58:61], 0
	v_mfma_f32_16x16x32_bf16 v[66:69], v[2:5], v[34:37], 0
	v_mfma_f32_16x16x32_bf16 v[70:73], v[10:13], v[34:37], 0
	v_mfma_f32_16x16x32_bf16 v[74:77], v[2:5], v[42:45], 0
	v_mfma_f32_16x16x32_bf16 v[78:81], v[10:13], v[42:45], 0
	v_mfma_f32_16x16x32_bf16 v[82:85], v[2:5], v[50:53], 0
	v_mfma_f32_16x16x32_bf16 v[86:89], v[10:13], v[50:53], 0
	v_mfma_f32_16x16x32_bf16 v[100:103], v[6:9], v[62:65], v[90:93]
	v_mfma_f32_16x16x32_bf16 v[90:93], v[10:13], v[58:61], 0
	v_mfma_f32_16x16x32_bf16 v[66:69], v[6:9], v[38:41], v[66:69]
	v_mfma_f32_16x16x32_bf16 v[70:73], v[14:17], v[38:41], v[70:73]
	v_mfma_f32_16x16x32_bf16 v[74:77], v[6:9], v[46:49], v[74:77]
	v_mfma_f32_16x16x32_bf16 v[78:81], v[14:17], v[46:49], v[78:81]
	v_mfma_f32_16x16x32_bf16 v[82:85], v[6:9], v[54:57], v[82:85]
	v_mfma_f32_16x16x32_bf16 v[86:89], v[14:17], v[54:57], v[86:89]
	v_mfma_f32_16x16x32_bf16 v[104:107], v[14:17], v[62:65], v[90:93]
	v_mfma_f32_16x16x32_bf16 v[90:93], v[18:21], v[34:37], 0
	v_mfma_f32_16x16x32_bf16 v[34:37], v[26:29], v[34:37], 0
	v_mfma_f32_16x16x32_bf16 v[116:119], v[22:25], v[38:41], v[90:93]
	v_mfma_f32_16x16x32_bf16 v[34:37], v[30:33], v[38:41], v[34:37]
	v_mfma_f32_16x16x32_bf16 v[38:41], v[18:21], v[42:45], 0
	v_mfma_f32_16x16x32_bf16 v[42:45], v[26:29], v[42:45], 0
	v_mfma_f32_16x16x32_bf16 v[38:41], v[22:25], v[46:49], v[38:41]
	v_mfma_f32_16x16x32_bf16 v[42:45], v[30:33], v[46:49], v[42:45]
	v_mfma_f32_16x16x32_bf16 v[46:49], v[18:21], v[50:53], 0
	v_mfma_f32_16x16x32_bf16 v[50:53], v[26:29], v[50:53], 0
	v_mfma_f32_16x16x32_bf16 v[46:49], v[22:25], v[54:57], v[46:49]
	v_mfma_f32_16x16x32_bf16 v[50:53], v[30:33], v[54:57], v[50:53]
	v_mfma_f32_16x16x32_bf16 v[54:57], v[18:21], v[58:61], 0
	v_mfma_f32_16x16x32_bf16 v[58:61], v[26:29], v[58:61], 0
	v_mfma_f32_16x16x32_bf16 v[54:57], v[22:25], v[62:65], v[54:57]
	v_mfma_f32_16x16x32_bf16 v[58:61], v[30:33], v[62:65], v[58:61]
	s_barrier
	s_add_i32 s12, s60, s17
	s_mov_b32 m0, s12
	ds_read_b128 v[62:65], v163 offset:16384
	ds_read_b128 v[90:93], v163 offset:17408
	ds_read_b128 v[94:97], v163 offset:18432
	ds_read_b128 v[108:111], v163 offset:19456
	ds_read_b128 v[112:115], v163 offset:20480
	ds_read_b128 v[120:123], v163 offset:21504
	ds_read_b128 v[124:127], v163 offset:22528
	ds_read_b128 v[128:131], v163 offset:23552
	global_load_lds_dwordx4 v134, s[0:1]
	s_add_i32 m0, s12, 0x2000
	v_lshl_add_u64 v[98:99], s[0:1], 0, v[138:139]
	s_add_u32 s0, s4, 0x14000
	s_addc_u32 s1, s5, 0
	s_add_i32 s12, s61, s17
	global_load_lds_dwordx4 v[98:99], off
	s_mov_b32 m0, s12
	v_lshl_add_u64 v[156:157], s[8:9], 0, v[132:133]
	global_load_lds_dwordx4 v134, s[0:1]
	s_add_i32 m0, s12, 0x2000
	v_lshl_add_u64 v[144:145], s[8:9], 0, v[136:137]
	global_load_lds_dwordx4 v138, s[0:1]
	s_mov_b32 m0, s18
	v_lshl_add_u64 v[98:99], v[156:157], 0, s[36:37]
	global_load_lds_dwordx4 v[98:99], off
	s_mov_b32 m0, s19
	v_lshl_add_u64 v[98:99], v[144:145], 0, s[36:37]
	global_load_lds_dwordx4 v[98:99], off
	s_waitcnt vmcnt(24) lgkmcnt(0)
	s_barrier
	v_mfma_f32_16x16x32_bf16 v[148:151], v[2:5], v[62:65], 0
	v_mfma_f32_16x16x32_bf16 v[166:169], v[2:5], v[94:97], 0
	v_mfma_f32_16x16x32_bf16 v[174:177], v[2:5], v[112:115], 0
	v_mfma_f32_16x16x32_bf16 v[2:5], v[2:5], v[124:127], 0
	v_mfma_f32_16x16x32_bf16 v[148:151], v[6:9], v[90:93], v[148:151]
	v_mfma_f32_16x16x32_bf16 v[166:169], v[6:9], v[108:111], v[166:169]
	v_mfma_f32_16x16x32_bf16 v[174:177], v[6:9], v[120:123], v[174:177]
	v_mfma_f32_16x16x32_bf16 v[2:5], v[6:9], v[128:131], v[2:5]
	v_mfma_f32_16x16x32_bf16 v[6:9], v[10:13], v[124:127], 0
	v_mfma_f32_16x16x32_bf16 v[152:155], v[10:13], v[62:65], 0
	v_mfma_f32_16x16x32_bf16 v[170:173], v[10:13], v[94:97], 0
	v_mfma_f32_16x16x32_bf16 v[178:181], v[10:13], v[112:115], 0
	v_mfma_f32_16x16x32_bf16 v[6:9], v[14:17], v[128:131], v[6:9]
	v_mfma_f32_16x16x32_bf16 v[152:155], v[14:17], v[90:93], v[152:155]
	v_mfma_f32_16x16x32_bf16 v[170:173], v[14:17], v[108:111], v[170:173]
	v_mfma_f32_16x16x32_bf16 v[178:181], v[14:17], v[120:123], v[178:181]
	v_mfma_f32_16x16x32_bf16 v[10:13], v[18:21], v[62:65], 0
	v_mfma_f32_16x16x32_bf16 v[182:185], v[22:25], v[90:93], v[10:13]
	v_mfma_f32_16x16x32_bf16 v[10:13], v[26:29], v[62:65], 0
	v_mfma_f32_16x16x32_bf16 v[186:189], v[30:33], v[90:93], v[10:13]
	v_mfma_f32_16x16x32_bf16 v[10:13], v[18:21], v[94:97], 0
	v_mfma_f32_16x16x32_bf16 v[190:193], v[22:25], v[108:111], v[10:13]
	v_mfma_f32_16x16x32_bf16 v[10:13], v[26:29], v[94:97], 0
	v_mfma_f32_16x16x32_bf16 v[194:197], v[30:33], v[108:111], v[10:13]
	v_mfma_f32_16x16x32_bf16 v[10:13], v[18:21], v[112:115], 0
	v_mfma_f32_16x16x32_bf16 v[198:201], v[22:25], v[120:123], v[10:13]
	v_mfma_f32_16x16x32_bf16 v[10:13], v[26:29], v[112:115], 0
	v_mfma_f32_16x16x32_bf16 v[202:205], v[30:33], v[120:123], v[10:13]
	v_mfma_f32_16x16x32_bf16 v[10:13], v[18:21], v[124:127], 0
	v_mfma_f32_16x16x32_bf16 v[206:209], v[22:25], v[128:131], v[10:13]
	v_mfma_f32_16x16x32_bf16 v[10:13], v[26:29], v[124:127], 0
	v_mfma_f32_16x16x32_bf16 v[210:213], v[30:33], v[128:131], v[10:13]
	s_barrier
	s_add_i32 s12, 0, 0x18000
	v_add_u32_e32 v1, s12, v160
	s_add_i32 s13, 0, 0x1c000
	s_nop 1
	ds_read_b128 v[10:13], v1
	ds_read_b128 v[14:17], v1 offset:1024
	ds_read_b128 v[20:23], v1 offset:2048
	ds_read_b128 v[24:27], v1 offset:3072
	v_add_u32_e32 v1, s13, v160
	ds_read_b128 v[214:217], v1
	ds_read_b128 v[218:221], v1 offset:1024
	ds_read_b128 v[222:225], v1 offset:2048
	ds_read_b128 v[226:229], v1 offset:3072
	s_add_u32 s0, s8, 0x100100
	s_addc_u32 s1, s9, 0
	s_mov_b32 m0, s20
	ds_read_b128 v[28:31], v163 offset:32768
	ds_read_b128 v[62:65], v163 offset:33792
	ds_read_b128 v[230:233], v163 offset:34816
	ds_read_b128 v[234:237], v163 offset:35840
	ds_read_b128 v[238:241], v163 offset:36864
	ds_read_b128 v[242:245], v163 offset:37888
	ds_read_b128 v[246:249], v163 offset:38912
	ds_read_b128 v[250:253], v163 offset:39936
	global_load_lds_dwordx4 v132, s[0:1]
	s_mov_b32 m0, s21
	s_nop 0
	global_load_lds_dwordx4 v136, s[0:1]
	s_waitcnt vmcnt(24) lgkmcnt(0)
	s_barrier
	v_mfma_f32_16x16x32_bf16 v[66:69], v[10:13], v[28:31], v[66:69]
	v_mfma_f32_16x16x32_bf16 v[128:131], v[14:17], v[62:65], v[66:69]
	v_mfma_f32_16x16x32_bf16 v[66:69], v[20:23], v[28:31], v[70:73]
	v_mfma_f32_16x16x32_bf16 v[124:127], v[24:27], v[62:65], v[66:69]
	v_mfma_f32_16x16x32_bf16 v[66:69], v[10:13], v[230:233], v[74:77]
	v_mfma_f32_16x16x32_bf16 v[112:115], v[14:17], v[234:237], v[66:69]
	v_mfma_f32_16x16x32_bf16 v[66:69], v[20:23], v[230:233], v[78:81]
	v_mfma_f32_16x16x32_bf16 v[108:111], v[24:27], v[234:237], v[66:69]
	v_mfma_f32_16x16x32_bf16 v[66:69], v[10:13], v[238:241], v[82:85]
	v_mfma_f32_16x16x32_bf16 v[96:99], v[14:17], v[242:245], v[66:69]
	v_mfma_f32_16x16x32_bf16 v[66:69], v[20:23], v[238:241], v[86:89]
	v_mfma_f32_16x16x32_bf16 v[92:95], v[24:27], v[242:245], v[66:69]
	v_mfma_f32_16x16x32_bf16 v[66:69], v[10:13], v[246:249], v[100:103]
	v_mfma_f32_16x16x32_bf16 v[80:83], v[14:17], v[250:253], v[66:69]
	v_mfma_f32_16x16x32_bf16 v[66:69], v[20:23], v[246:249], v[104:107]
	v_mfma_f32_16x16x32_bf16 v[76:79], v[24:27], v[250:253], v[66:69]
	v_mfma_f32_16x16x32_bf16 v[66:69], v[214:217], v[28:31], v[116:119]
	v_mfma_f32_16x16x32_bf16 v[28:31], v[222:225], v[28:31], v[34:37]
	v_mfma_f32_16x16x32_bf16 v[116:119], v[226:229], v[62:65], v[28:31]
	v_mfma_f32_16x16x32_bf16 v[28:31], v[214:217], v[230:233], v[38:41]
	v_mfma_f32_16x16x32_bf16 v[104:107], v[218:221], v[234:237], v[28:31]
	v_mfma_f32_16x16x32_bf16 v[28:31], v[222:225], v[230:233], v[42:45]
	v_mfma_f32_16x16x32_bf16 v[100:103], v[226:229], v[234:237], v[28:31]
	v_mfma_f32_16x16x32_bf16 v[28:31], v[214:217], v[238:241], v[46:49]
	v_mfma_f32_16x16x32_bf16 v[88:91], v[218:221], v[242:245], v[28:31]
	v_mfma_f32_16x16x32_bf16 v[28:31], v[222:225], v[238:241], v[50:53]
	v_mfma_f32_16x16x32_bf16 v[84:87], v[226:229], v[242:245], v[28:31]
	v_mfma_f32_16x16x32_bf16 v[28:31], v[214:217], v[246:249], v[54:57]
	v_mfma_f32_16x16x32_bf16 v[72:75], v[218:221], v[250:253], v[28:31]
	v_mfma_f32_16x16x32_bf16 v[28:31], v[222:225], v[246:249], v[58:61]
	v_mfma_f32_16x16x32_bf16 v[120:123], v[218:221], v[62:65], v[66:69]
	v_mfma_f32_16x16x32_bf16 v[68:71], v[226:229], v[250:253], v[28:31]
	s_barrier
	s_add_u32 s0, s4, 0x18000
	s_addc_u32 s1, s5, 0
	s_add_i32 s12, s12, s17
	s_mov_b32 m0, s12
	ds_read_b128 v[36:39], v163 offset:49152
	ds_read_b128 v[40:43], v163 offset:50176
	ds_read_b128 v[230:233], v163 offset:51200
	ds_read_b128 v[234:237], v163 offset:52224
	ds_read_b128 v[238:241], v163 offset:53248
	ds_read_b128 v[242:245], v163 offset:54272
	ds_read_b128 v[246:249], v163 offset:55296
	ds_read_b128 v[250:253], v163 offset:56320
	global_load_lds_dwordx4 v134, s[0:1]
	s_add_i32 m0, s12, 0x2000
	v_lshl_add_u64 v[18:19], s[0:1], 0, v[138:139]
	s_add_u32 s0, s4, 0x1c000
	s_addc_u32 s1, s5, 0
	s_add_i32 s12, s13, s17
	global_load_lds_dwordx4 v[18:19], off
	s_mov_b32 m0, s12
	s_nop 0
	global_load_lds_dwordx4 v134, s[0:1]
	s_add_i32 m0, s12, 0x2000
	s_nop 0
	global_load_lds_dwordx4 v138, s[0:1]
	s_mov_b32 m0, s51
	v_lshl_add_u64 v[18:19], v[156:157], 0, s[38:39]
	global_load_lds_dwordx4 v[18:19], off
	s_mov_b32 m0, s56
	v_lshl_add_u64 v[18:19], v[144:145], 0, s[38:39]
	global_load_lds_dwordx4 v[18:19], off
	s_waitcnt vmcnt(8) lgkmcnt(0)
	s_barrier
	v_mfma_f32_16x16x32_bf16 v[28:31], v[10:13], v[36:39], v[148:151]
	v_mfma_f32_16x16x32_bf16 v[64:67], v[14:17], v[40:43], v[28:31]
	v_mfma_f32_16x16x32_bf16 v[28:31], v[20:23], v[36:39], v[152:155]
	v_mfma_f32_16x16x32_bf16 v[60:63], v[24:27], v[40:43], v[28:31]
	v_mfma_f32_16x16x32_bf16 v[28:31], v[10:13], v[230:233], v[166:169]
	v_mfma_f32_16x16x32_bf16 v[48:51], v[14:17], v[234:237], v[28:31]
	v_mfma_f32_16x16x32_bf16 v[28:31], v[20:23], v[230:233], v[170:173]
	v_mfma_f32_16x16x32_bf16 v[44:47], v[24:27], v[234:237], v[28:31]
	v_mfma_f32_16x16x32_bf16 v[28:31], v[10:13], v[238:241], v[174:177]
	v_mfma_f32_16x16x32_bf16 v[2:5], v[10:13], v[246:249], v[2:5]
	v_mfma_f32_16x16x32_bf16 v[32:35], v[14:17], v[242:245], v[28:31]
	v_mfma_f32_16x16x32_bf16 v[28:31], v[20:23], v[238:241], v[178:181]
	v_mfma_f32_16x16x32_bf16 v[16:19], v[14:17], v[250:253], v[2:5]
	v_mfma_f32_16x16x32_bf16 v[2:5], v[20:23], v[246:249], v[6:9]
	v_mfma_f32_16x16x32_bf16 v[28:31], v[24:27], v[242:245], v[28:31]
	v_mfma_f32_16x16x32_bf16 v[12:15], v[24:27], v[250:253], v[2:5]
	v_mfma_f32_16x16x32_bf16 v[2:5], v[214:217], v[36:39], v[182:185]
	v_mfma_f32_16x16x32_bf16 v[56:59], v[218:221], v[40:43], v[2:5]
	v_mfma_f32_16x16x32_bf16 v[2:5], v[222:225], v[36:39], v[186:189]
	v_mfma_f32_16x16x32_bf16 v[52:55], v[226:229], v[40:43], v[2:5]
	v_mfma_f32_16x16x32_bf16 v[2:5], v[214:217], v[230:233], v[190:193]
	v_mfma_f32_16x16x32_bf16 v[40:43], v[218:221], v[234:237], v[2:5]
	v_mfma_f32_16x16x32_bf16 v[2:5], v[222:225], v[230:233], v[194:197]
	v_mfma_f32_16x16x32_bf16 v[36:39], v[226:229], v[234:237], v[2:5]
	v_mfma_f32_16x16x32_bf16 v[2:5], v[214:217], v[238:241], v[198:201]
	v_mfma_f32_16x16x32_bf16 v[24:27], v[218:221], v[242:245], v[2:5]
	v_mfma_f32_16x16x32_bf16 v[2:5], v[222:225], v[238:241], v[202:205]
	v_mfma_f32_16x16x32_bf16 v[20:23], v[226:229], v[242:245], v[2:5]
	v_mfma_f32_16x16x32_bf16 v[2:5], v[214:217], v[246:249], v[206:209]
	v_mfma_f32_16x16x32_bf16 v[8:11], v[218:221], v[250:253], v[2:5]
	v_mfma_f32_16x16x32_bf16 v[2:5], v[222:225], v[246:249], v[210:213]
	v_mfma_f32_16x16x32_bf16 v[4:7], v[226:229], v[250:253], v[2:5]
	s_barrier
	s_mov_b32 s22, 2
	s_branch .LBB0_199

.LBB0_200:
	ds_read_b128 v[150:153], v161
	ds_read_b128 v[154:157], v161 offset:1024
	ds_read_b128 v[166:169], v161 offset:2048
	ds_read_b128 v[170:173], v161 offset:3072
	ds_read_b128 v[174:177], v162
	ds_read_b128 v[178:181], v162 offset:1024
	ds_read_b128 v[182:185], v162 offset:2048
	ds_read_b128 v[186:189], v162 offset:3072
	s_add_u32 s8, s55, s26
	s_addc_u32 s9, s63, 0
	s_cmp_eq_u32 s26, s4
	s_cselect_b32 s23, s0, s9
	s_cselect_b32 s22, s1, s8
	s_cselect_b32 s9, s41, s54
	s_cselect_b32 s8, s43, s53
	s_add_i32 s65, s18, 0xc000
	v_lshl_add_u64 v[144:145], v[2:3], 0, s[26:27]
	s_mov_b32 m0, s65
	s_add_i32 s64, s18, 0xe000
	ds_read_b128 v[190:193], v163
	ds_read_b128 v[194:197], v163 offset:1024
	ds_read_b128 v[198:201], v163 offset:2048
	ds_read_b128 v[202:205], v163 offset:3072
	ds_read_b128 v[206:209], v163 offset:4096
	ds_read_b128 v[210:213], v163 offset:5120
	ds_read_b128 v[214:217], v163 offset:6144
	ds_read_b128 v[218:221], v163 offset:7168
	global_load_lds_dwordx4 v[144:145], off
	s_mov_b32 m0, s64
	v_lshl_add_u64 v[144:145], v[148:149], 0, s[26:27]
	global_load_lds_dwordx4 v[144:145], off
	s_waitcnt vmcnt(8) lgkmcnt(0)
	s_barrier
	v_mfma_f32_16x16x32_bf16 v[128:131], v[150:153], v[190:193], v[128:131]
	v_mfma_f32_16x16x32_bf16 v[128:131], v[154:157], v[194:197], v[128:131]
	v_mfma_f32_16x16x32_bf16 v[124:127], v[166:169], v[190:193], v[124:127]
	v_mfma_f32_16x16x32_bf16 v[124:127], v[170:173], v[194:197], v[124:127]
	v_mfma_f32_16x16x32_bf16 v[108:111], v[166:169], v[198:201], v[108:111]
	v_mfma_f32_16x16x32_bf16 v[108:111], v[170:173], v[202:205], v[108:111]
	v_mfma_f32_16x16x32_bf16 v[112:115], v[150:153], v[198:201], v[112:115]
	v_mfma_f32_16x16x32_bf16 v[112:115], v[154:157], v[202:205], v[112:115]
	v_mfma_f32_16x16x32_bf16 v[96:99], v[150:153], v[206:209], v[96:99]
	v_mfma_f32_16x16x32_bf16 v[96:99], v[154:157], v[210:213], v[96:99]
	v_mfma_f32_16x16x32_bf16 v[92:95], v[166:169], v[206:209], v[92:95]
	v_mfma_f32_16x16x32_bf16 v[92:95], v[170:173], v[210:213], v[92:95]
	v_mfma_f32_16x16x32_bf16 v[76:79], v[166:169], v[214:217], v[76:79]
	v_mfma_f32_16x16x32_bf16 v[76:79], v[170:173], v[218:221], v[76:79]
	v_mfma_f32_16x16x32_bf16 v[80:83], v[150:153], v[214:217], v[80:83]
	v_mfma_f32_16x16x32_bf16 v[80:83], v[154:157], v[218:221], v[80:83]
	v_mfma_f32_16x16x32_bf16 v[72:75], v[174:177], v[214:217], v[72:75]
	v_mfma_f32_16x16x32_bf16 v[72:75], v[178:181], v[218:221], v[72:75]
	v_mfma_f32_16x16x32_bf16 v[68:71], v[182:185], v[214:217], v[68:71]
	v_mfma_f32_16x16x32_bf16 v[68:71], v[186:189], v[218:221], v[68:71]
	v_mfma_f32_16x16x32_bf16 v[84:87], v[182:185], v[206:209], v[84:87]
	v_mfma_f32_16x16x32_bf16 v[84:87], v[186:189], v[210:213], v[84:87]
	v_mfma_f32_16x16x32_bf16 v[88:91], v[174:177], v[206:209], v[88:91]
	v_mfma_f32_16x16x32_bf16 v[88:91], v[178:181], v[210:213], v[88:91]
	v_mfma_f32_16x16x32_bf16 v[104:107], v[174:177], v[198:201], v[104:107]
	v_mfma_f32_16x16x32_bf16 v[104:107], v[178:181], v[202:205], v[104:107]
	v_mfma_f32_16x16x32_bf16 v[100:103], v[182:185], v[198:201], v[100:103]
	v_mfma_f32_16x16x32_bf16 v[100:103], v[186:189], v[202:205], v[100:103]
	v_mfma_f32_16x16x32_bf16 v[116:119], v[182:185], v[190:193], v[116:119]
	v_mfma_f32_16x16x32_bf16 v[116:119], v[186:189], v[194:197], v[116:119]
	v_mfma_f32_16x16x32_bf16 v[120:123], v[174:177], v[190:193], v[120:123]
	v_mfma_f32_16x16x32_bf16 v[120:123], v[178:181], v[194:197], v[120:123]
	s_barrier
	s_add_i32 s12, s60, s17
	s_mov_b32 m0, s12
	ds_read_b128 v[190:193], v163 offset:16384
	ds_read_b128 v[194:197], v163 offset:17408
	ds_read_b128 v[198:201], v163 offset:18432
	ds_read_b128 v[202:205], v163 offset:19456
	ds_read_b128 v[206:209], v163 offset:20480
	ds_read_b128 v[210:213], v163 offset:21504
	ds_read_b128 v[214:217], v163 offset:22528
	ds_read_b128 v[218:221], v163 offset:23552
	global_load_lds_dwordx4 v134, s[8:9]
	s_add_i32 m0, s12, 0x2000
	s_add_u32 s12, s8, 0x4000
	s_addc_u32 s13, s9, 0
	s_add_i32 s14, s61, s17
	global_load_lds_dwordx4 v138, s[8:9]
	s_mov_b32 m0, s14
	v_lshl_add_u64 v[222:223], s[22:23], 0, v[136:137]
	global_load_lds_dwordx4 v134, s[12:13]
	s_add_i32 m0, s14, 0x2000
	s_nop 0
	global_load_lds_dwordx4 v138, s[12:13]
	s_mov_b32 m0, s18
	v_lshl_add_u64 v[144:145], s[22:23], 0, v[132:133]
	global_load_lds_dwordx4 v[144:145], off
	s_mov_b32 m0, s19
	s_nop 0
	global_load_lds_dwordx4 v[222:223], off
	s_waitcnt vmcnt(8) lgkmcnt(0)
	s_barrier
	v_mfma_f32_16x16x32_bf16 v[64:67], v[150:153], v[190:193], v[64:67]
	v_mfma_f32_16x16x32_bf16 v[64:67], v[154:157], v[194:197], v[64:67]
	v_mfma_f32_16x16x32_bf16 v[60:63], v[166:169], v[190:193], v[60:63]
	v_mfma_f32_16x16x32_bf16 v[60:63], v[170:173], v[194:197], v[60:63]
	v_mfma_f32_16x16x32_bf16 v[44:47], v[166:169], v[198:201], v[44:47]
	v_mfma_f32_16x16x32_bf16 v[44:47], v[170:173], v[202:205], v[44:47]
	v_mfma_f32_16x16x32_bf16 v[48:51], v[150:153], v[198:201], v[48:51]
	v_mfma_f32_16x16x32_bf16 v[48:51], v[154:157], v[202:205], v[48:51]
	v_mfma_f32_16x16x32_bf16 v[32:35], v[150:153], v[206:209], v[32:35]
	v_mfma_f32_16x16x32_bf16 v[32:35], v[154:157], v[210:213], v[32:35]
	v_mfma_f32_16x16x32_bf16 v[28:31], v[166:169], v[206:209], v[28:31]
	v_mfma_f32_16x16x32_bf16 v[28:31], v[170:173], v[210:213], v[28:31]
	v_mfma_f32_16x16x32_bf16 v[12:15], v[166:169], v[214:217], v[12:15]
	v_mfma_f32_16x16x32_bf16 v[12:15], v[170:173], v[218:221], v[12:15]
	v_mfma_f32_16x16x32_bf16 v[16:19], v[150:153], v[214:217], v[16:19]
	v_mfma_f32_16x16x32_bf16 v[16:19], v[154:157], v[218:221], v[16:19]
	v_mfma_f32_16x16x32_bf16 v[8:11], v[174:177], v[214:217], v[8:11]
	v_mfma_f32_16x16x32_bf16 v[8:11], v[178:181], v[218:221], v[8:11]
	v_mfma_f32_16x16x32_bf16 v[4:7], v[182:185], v[214:217], v[4:7]
	v_mfma_f32_16x16x32_bf16 v[4:7], v[186:189], v[218:221], v[4:7]
	v_mfma_f32_16x16x32_bf16 v[20:23], v[182:185], v[206:209], v[20:23]
	v_mfma_f32_16x16x32_bf16 v[20:23], v[186:189], v[210:213], v[20:23]
	v_mfma_f32_16x16x32_bf16 v[24:27], v[174:177], v[206:209], v[24:27]
	v_mfma_f32_16x16x32_bf16 v[24:27], v[178:181], v[210:213], v[24:27]
	v_mfma_f32_16x16x32_bf16 v[40:43], v[174:177], v[198:201], v[40:43]
	v_mfma_f32_16x16x32_bf16 v[40:43], v[178:181], v[202:205], v[40:43]
	v_mfma_f32_16x16x32_bf16 v[36:39], v[182:185], v[198:201], v[36:39]
	v_mfma_f32_16x16x32_bf16 v[36:39], v[186:189], v[202:205], v[36:39]
	v_mfma_f32_16x16x32_bf16 v[52:55], v[182:185], v[190:193], v[52:55]
	v_mfma_f32_16x16x32_bf16 v[52:55], v[186:189], v[194:197], v[52:55]
	v_mfma_f32_16x16x32_bf16 v[56:59], v[174:177], v[190:193], v[56:59]
	v_mfma_f32_16x16x32_bf16 v[56:59], v[178:181], v[194:197], v[56:59]
	s_barrier
	s_add_i32 s14, 0, 0x18000
	v_add_u32_e32 v1, s14, v160
	s_add_i32 s66, 0, 0x1c000
	ds_read_b128 v[150:153], v1
	ds_read_b128 v[154:157], v1 offset:1024
	ds_read_b128 v[166:169], v1 offset:2048
	ds_read_b128 v[170:173], v1 offset:3072
	v_add_u32_e32 v1, s66, v160
	ds_read_b128 v[174:177], v1
	ds_read_b128 v[178:181], v1 offset:1024
	ds_read_b128 v[182:185], v1 offset:2048
	ds_read_b128 v[186:189], v1 offset:3072
	s_add_u32 s12, s22, 0x100000
	s_addc_u32 s13, s23, 0
	s_mov_b32 m0, s20
	ds_read_b128 v[190:193], v163 offset:32768
	ds_read_b128 v[194:197], v163 offset:33792
	ds_read_b128 v[198:201], v163 offset:34816
	ds_read_b128 v[202:205], v163 offset:35840
	ds_read_b128 v[206:209], v163 offset:36864
	ds_read_b128 v[210:213], v163 offset:37888
	ds_read_b128 v[214:217], v163 offset:38912
	ds_read_b128 v[218:221], v163 offset:39936
	global_load_lds_dwordx4 v132, s[12:13]
	s_mov_b32 m0, s21
	s_nop 0
	global_load_lds_dwordx4 v136, s[12:13]
	s_waitcnt vmcnt(8) lgkmcnt(0)
	s_barrier
	v_mfma_f32_16x16x32_bf16 v[128:131], v[150:153], v[190:193], v[128:131]
	v_mfma_f32_16x16x32_bf16 v[128:131], v[154:157], v[194:197], v[128:131]
	v_mfma_f32_16x16x32_bf16 v[124:127], v[166:169], v[190:193], v[124:127]
	v_mfma_f32_16x16x32_bf16 v[124:127], v[170:173], v[194:197], v[124:127]
	v_mfma_f32_16x16x32_bf16 v[108:111], v[166:169], v[198:201], v[108:111]
	v_mfma_f32_16x16x32_bf16 v[108:111], v[170:173], v[202:205], v[108:111]
	v_mfma_f32_16x16x32_bf16 v[112:115], v[150:153], v[198:201], v[112:115]
	v_mfma_f32_16x16x32_bf16 v[112:115], v[154:157], v[202:205], v[112:115]
	v_mfma_f32_16x16x32_bf16 v[96:99], v[150:153], v[206:209], v[96:99]
	v_mfma_f32_16x16x32_bf16 v[96:99], v[154:157], v[210:213], v[96:99]
	v_mfma_f32_16x16x32_bf16 v[92:95], v[166:169], v[206:209], v[92:95]
	v_mfma_f32_16x16x32_bf16 v[92:95], v[170:173], v[210:213], v[92:95]
	v_mfma_f32_16x16x32_bf16 v[76:79], v[166:169], v[214:217], v[76:79]
	v_mfma_f32_16x16x32_bf16 v[76:79], v[170:173], v[218:221], v[76:79]
	v_mfma_f32_16x16x32_bf16 v[80:83], v[150:153], v[214:217], v[80:83]
	v_mfma_f32_16x16x32_bf16 v[80:83], v[154:157], v[218:221], v[80:83]
	v_mfma_f32_16x16x32_bf16 v[72:75], v[174:177], v[214:217], v[72:75]
	v_mfma_f32_16x16x32_bf16 v[72:75], v[178:181], v[218:221], v[72:75]
	v_mfma_f32_16x16x32_bf16 v[68:71], v[182:185], v[214:217], v[68:71]
	v_mfma_f32_16x16x32_bf16 v[68:71], v[186:189], v[218:221], v[68:71]
	v_mfma_f32_16x16x32_bf16 v[84:87], v[182:185], v[206:209], v[84:87]
	v_mfma_f32_16x16x32_bf16 v[84:87], v[186:189], v[210:213], v[84:87]
	v_mfma_f32_16x16x32_bf16 v[88:91], v[174:177], v[206:209], v[88:91]
	v_mfma_f32_16x16x32_bf16 v[88:91], v[178:181], v[210:213], v[88:91]
	v_mfma_f32_16x16x32_bf16 v[104:107], v[174:177], v[198:201], v[104:107]
	v_mfma_f32_16x16x32_bf16 v[104:107], v[178:181], v[202:205], v[104:107]
	v_mfma_f32_16x16x32_bf16 v[100:103], v[182:185], v[198:201], v[100:103]
	v_mfma_f32_16x16x32_bf16 v[100:103], v[186:189], v[202:205], v[100:103]
	v_mfma_f32_16x16x32_bf16 v[116:119], v[182:185], v[190:193], v[116:119]
	v_mfma_f32_16x16x32_bf16 v[116:119], v[186:189], v[194:197], v[116:119]
	v_mfma_f32_16x16x32_bf16 v[120:123], v[174:177], v[190:193], v[120:123]
	v_mfma_f32_16x16x32_bf16 v[120:123], v[178:181], v[194:197], v[120:123]
	s_barrier
	s_add_u32 s12, s8, 0x8000
	s_addc_u32 s13, s9, 0
	s_add_i32 s14, s14, s17
	s_mov_b32 m0, s14
	ds_read_b128 v[190:193], v163 offset:49152
	ds_read_b128 v[194:197], v163 offset:50176
	ds_read_b128 v[198:201], v163 offset:51200
	ds_read_b128 v[202:205], v163 offset:52224
	ds_read_b128 v[206:209], v163 offset:53248
	ds_read_b128 v[210:213], v163 offset:54272
	ds_read_b128 v[214:217], v163 offset:55296
	ds_read_b128 v[218:221], v163 offset:56320
	global_load_lds_dwordx4 v134, s[12:13]
	s_add_i32 m0, s14, 0x2000
	s_add_u32 s8, s8, 0xc000
	v_lshl_add_u64 v[224:225], s[12:13], 0, v[138:139]
	s_addc_u32 s9, s9, 0
	s_add_i32 s12, s66, s17
	global_load_lds_dwordx4 v[224:225], off
	s_mov_b32 m0, s12
	v_lshl_add_u64 v[144:145], v[144:145], 0, s[30:31]
	global_load_lds_dwordx4 v134, s[8:9]
	s_add_i32 m0, s12, 0x2000
	v_lshl_add_u64 v[224:225], s[8:9], 0, v[138:139]
	global_load_lds_dwordx4 v[224:225], off
	s_mov_b32 m0, s51
	s_nop 0
	global_load_lds_dwordx4 v[144:145], off
	s_mov_b32 m0, s56
	v_lshl_add_u64 v[144:145], v[222:223], 0, s[30:31]
	global_load_lds_dwordx4 v[144:145], off
	s_waitcnt vmcnt(8) lgkmcnt(0)
	s_barrier
	v_mfma_f32_16x16x32_bf16 v[64:67], v[150:153], v[190:193], v[64:67]
	v_mfma_f32_16x16x32_bf16 v[64:67], v[154:157], v[194:197], v[64:67]
	v_mfma_f32_16x16x32_bf16 v[60:63], v[166:169], v[190:193], v[60:63]
	v_mfma_f32_16x16x32_bf16 v[60:63], v[170:173], v[194:197], v[60:63]
	v_mfma_f32_16x16x32_bf16 v[44:47], v[166:169], v[198:201], v[44:47]
	v_mfma_f32_16x16x32_bf16 v[44:47], v[170:173], v[202:205], v[44:47]
	v_mfma_f32_16x16x32_bf16 v[48:51], v[150:153], v[198:201], v[48:51]
	v_mfma_f32_16x16x32_bf16 v[48:51], v[154:157], v[202:205], v[48:51]
	v_mfma_f32_16x16x32_bf16 v[32:35], v[150:153], v[206:209], v[32:35]
	v_mfma_f32_16x16x32_bf16 v[32:35], v[154:157], v[210:213], v[32:35]
	v_mfma_f32_16x16x32_bf16 v[28:31], v[166:169], v[206:209], v[28:31]
	v_mfma_f32_16x16x32_bf16 v[28:31], v[170:173], v[210:213], v[28:31]
	v_mfma_f32_16x16x32_bf16 v[12:15], v[166:169], v[214:217], v[12:15]
	v_mfma_f32_16x16x32_bf16 v[12:15], v[170:173], v[218:221], v[12:15]
	v_mfma_f32_16x16x32_bf16 v[16:19], v[150:153], v[214:217], v[16:19]
	v_mfma_f32_16x16x32_bf16 v[16:19], v[154:157], v[218:221], v[16:19]
	v_mfma_f32_16x16x32_bf16 v[8:11], v[174:177], v[214:217], v[8:11]
	v_mfma_f32_16x16x32_bf16 v[8:11], v[178:181], v[218:221], v[8:11]
	v_mfma_f32_16x16x32_bf16 v[4:7], v[182:185], v[214:217], v[4:7]
	v_mfma_f32_16x16x32_bf16 v[4:7], v[186:189], v[218:221], v[4:7]
	v_mfma_f32_16x16x32_bf16 v[20:23], v[182:185], v[206:209], v[20:23]
	v_mfma_f32_16x16x32_bf16 v[20:23], v[186:189], v[210:213], v[20:23]
	v_mfma_f32_16x16x32_bf16 v[24:27], v[174:177], v[206:209], v[24:27]
	v_mfma_f32_16x16x32_bf16 v[24:27], v[178:181], v[210:213], v[24:27]
	v_mfma_f32_16x16x32_bf16 v[40:43], v[174:177], v[198:201], v[40:43]
	v_mfma_f32_16x16x32_bf16 v[40:43], v[178:181], v[202:205], v[40:43]
	v_mfma_f32_16x16x32_bf16 v[36:39], v[182:185], v[198:201], v[36:39]
	v_mfma_f32_16x16x32_bf16 v[36:39], v[186:189], v[202:205], v[36:39]
	v_mfma_f32_16x16x32_bf16 v[52:55], v[182:185], v[190:193], v[52:55]
	v_mfma_f32_16x16x32_bf16 v[52:55], v[186:189], v[194:197], v[52:55]
	v_mfma_f32_16x16x32_bf16 v[56:59], v[174:177], v[190:193], v[56:59]
	v_mfma_f32_16x16x32_bf16 v[56:59], v[178:181], v[194:197], v[56:59]
	s_barrier
	s_add_i32 s52, s52, 2
	s_add_u32 s53, s53, 0x10000
	s_addc_u32 s54, s54, 0
	s_add_u32 s55, s55, 0x100
	s_addc_u32 s63, s63, 0
	s_add_u32 s4, s4, 0xffffff00
	s_addc_u32 s5, s5, -1
	v_lshl_add_u64 v[2:3], v[2:3], 0, s[36:37]
	s_cmp_gt_u32 s52, 61
	v_lshl_add_u64 v[148:149], v[148:149], 0, s[36:37]
	s_cbranch_scc0 .LBB0_200
	s_and_b64 vcc, exec, s[34:35]
	s_cbranch_vccz .LBB0_203
	s_barrier

.LBB0_497:
	s_add_u32 s30, s78, 0x43400000
	s_addc_u32 s31, s79, 0
	s_add_u32 s34, s78, 0x900000
	s_addc_u32 s35, s79, 0
	s_bfe_u32 s24, s88, 0x20006
	s_add_u32 s4, s8, 0x8000
	s_addc_u32 s5, s9, 0
	s_add_i32 m0, s18, 0x18000
	s_waitcnt vmcnt(2)
	s_barrier
	global_load_lds_dwordx4 v134, s[4:5]
	s_add_i32 m0, s18, 0x1a000
	s_mov_b64 s[36:37], 0x80
	s_add_i32 s25, s18, 0x8000
	s_add_i32 s33, s18, 0xa000
	global_load_lds_dwordx4 v138, s[4:5]
	v_lshl_add_u64 v[2:3], v[2:3], 0, s[36:37]
	s_mov_b32 m0, s25
	s_add_u32 s4, s8, 0xc000
	global_load_lds_dwordx4 v[2:3], off
	v_lshl_add_u64 v[2:3], v[4:5], 0, s[36:37]
	s_mov_b32 m0, s33
	s_addc_u32 s5, s9, 0
	global_load_lds_dwordx4 v[2:3], off
	s_add_i32 m0, s18, 0x1c000
	s_nop 0
	global_load_lds_dwordx4 v134, s[4:5]
	v_lshl_add_u64 v[2:3], s[4:5], 0, v[138:139]
	s_add_i32 m0, s18, 0x1e000
	v_and_b32_e32 v4, 48, v1
	global_load_lds_dwordx4 v[2:3], off
	v_and_b32_e32 v2, 15, v1
	v_lshl_or_b32 v150, s0, 6, v2
	v_ashrrev_i32_e32 v3, 1, v1
	v_and_b32_e32 v5, 0xfffffc00, v9
	v_lshl_or_b32 v2, v2, 6, v4
	v_lshlrev_b32_e32 v4, 2, v1
	v_cmp_gt_u32_e64 s[4:5], 16, v1
	v_lshlrev_b32_e32 v1, 16, v6
	v_lshl_add_u32 v9, s0, 13, v5
	v_and_b32_e32 v4, 32, v4
	v_lshl_add_u32 v5, s24, 12, v5
	v_and_b32_e32 v1, 0xfffe0000, v1
	v_bitop3_b32 v9, v2, v9, v4 bitop3:0xde
	v_bitop3_b32 v151, v2, v5, v4 bitop3:0xde
	v_lshl_add_u32 v1, v7, 13, v1
	v_and_b32_e32 v2, 1, v6
	v_lshl_or_b32 v1, v2, 6, v1
	v_and_b32_e32 v3, -8, v3
	v_lshl_add_u32 v2, v8, 1, v1
	v_lshlrev_b32_e32 v1, 16, v10
	v_lshl_add_u32 v152, s24, 5, v3
	v_mov_b32_e32 v3, v0
	s_mov_b64 s[0:1], 0x100080
	v_and_b32_e32 v1, 0xfffe0000, v1
	v_lshl_add_u64 v[140:141], v[2:3], 0, s[0:1]
	v_lshl_add_u32 v1, v11, 13, v1
	v_and_b32_e32 v2, 1, v10
	s_waitcnt vmcnt(6)
	s_cmpk_lt_u32 s88, 0x100
	v_lshl_or_b32 v1, v2, 6, v1
	s_cselect_b64 s[38:39], -1, 0
	v_lshl_add_u32 v2, v12, 1, v1
	s_add_i32 s58, 0, 0x10000
	s_add_i32 s59, 0, 0x14000
	v_mbcnt_lo_u32_b32 v1, -1, 0
	s_ashr_i32 s53, s77, 31
	s_ashr_i32 s55, s90, 31
	v_lshl_add_u64 v[142:143], v[2:3], 0, s[0:1]
	v_mov_b64_e32 v[146:147], 0x3ff
	v_add_u32_e32 v153, s58, v151
	v_add_u32_e32 v154, s59, v151
	v_add_u32_e32 v155, 0, v9
	s_mov_b64 s[40:41], 0x100
	s_mov_b64 s[42:43], 0x180
	v_mbcnt_hi_u32_b32 v156, -1, v1
	s_mov_b32 s22, 0
	s_barrier
	s_waitcnt vmcnt(0)
	s_branch .LBB0_500

.LBB0_506:
	s_cmp_eq_u32 s22, 0
	s_mov_b32 s22, 0
	s_cbranch_scc1 .LBB0_508
	ds_read_b128 v[2:5], v153
	ds_read_b128 v[6:9], v153 offset:1024
	ds_read_b128 v[10:13], v153 offset:2048
	ds_read_b128 v[14:17], v153 offset:3072
	ds_read_b128 v[18:21], v154
	ds_read_b128 v[22:25], v154 offset:1024
	ds_read_b128 v[26:29], v154 offset:2048
	ds_read_b128 v[30:33], v154 offset:3072
	s_add_u32 s0, s8, 0x10000
	s_addc_u32 s1, s9, 0
	ds_read_b128 v[34:37], v155
	ds_read_b128 v[38:41], v155 offset:1024
	ds_read_b128 v[42:45], v155 offset:2048
	ds_read_b128 v[46:49], v155 offset:3072
	ds_read_b128 v[50:53], v155 offset:4096
	ds_read_b128 v[54:57], v155 offset:5120
	ds_read_b128 v[58:61], v155 offset:6144
	ds_read_b128 v[62:65], v155 offset:7168
	s_waitcnt vmcnt(24) lgkmcnt(0)
	s_barrier
	v_mfma_f32_16x16x32_bf16 v[66:69], v[2:5], v[34:37], 0
	v_mfma_f32_16x16x32_bf16 v[70:73], v[10:13], v[34:37], 0
	v_mfma_f32_16x16x32_bf16 v[74:77], v[2:5], v[42:45], 0
	v_mfma_f32_16x16x32_bf16 v[78:81], v[10:13], v[42:45], 0
	v_mfma_f32_16x16x32_bf16 v[82:85], v[2:5], v[50:53], 0
	v_mfma_f32_16x16x32_bf16 v[86:89], v[10:13], v[50:53], 0
	v_mfma_f32_16x16x32_bf16 v[90:93], v[2:5], v[58:61], 0
	v_mfma_f32_16x16x32_bf16 v[94:97], v[10:13], v[58:61], 0
	v_mfma_f32_16x16x32_bf16 v[66:69], v[6:9], v[38:41], v[66:69]
	v_mfma_f32_16x16x32_bf16 v[70:73], v[14:17], v[38:41], v[70:73]
	v_mfma_f32_16x16x32_bf16 v[74:77], v[6:9], v[46:49], v[74:77]
	v_mfma_f32_16x16x32_bf16 v[78:81], v[14:17], v[46:49], v[78:81]
	v_mfma_f32_16x16x32_bf16 v[82:85], v[6:9], v[54:57], v[82:85]
	v_mfma_f32_16x16x32_bf16 v[86:89], v[14:17], v[54:57], v[86:89]
	v_mfma_f32_16x16x32_bf16 v[90:93], v[6:9], v[62:65], v[90:93]
	v_mfma_f32_16x16x32_bf16 v[104:107], v[14:17], v[62:65], v[94:97]
	v_mfma_f32_16x16x32_bf16 v[94:97], v[18:21], v[34:37], 0
	v_mfma_f32_16x16x32_bf16 v[34:37], v[26:29], v[34:37], 0
	v_mfma_f32_16x16x32_bf16 v[108:111], v[22:25], v[38:41], v[94:97]
	v_mfma_f32_16x16x32_bf16 v[34:37], v[30:33], v[38:41], v[34:37]
	v_mfma_f32_16x16x32_bf16 v[38:41], v[18:21], v[42:45], 0
	v_mfma_f32_16x16x32_bf16 v[42:45], v[26:29], v[42:45], 0
	v_mfma_f32_16x16x32_bf16 v[38:41], v[22:25], v[46:49], v[38:41]
	v_mfma_f32_16x16x32_bf16 v[42:45], v[30:33], v[46:49], v[42:45]
	v_mfma_f32_16x16x32_bf16 v[46:49], v[18:21], v[50:53], 0
	v_mfma_f32_16x16x32_bf16 v[50:53], v[26:29], v[50:53], 0
	v_mfma_f32_16x16x32_bf16 v[46:49], v[22:25], v[54:57], v[46:49]
	v_mfma_f32_16x16x32_bf16 v[50:53], v[30:33], v[54:57], v[50:53]
	v_mfma_f32_16x16x32_bf16 v[54:57], v[18:21], v[58:61], 0
	v_mfma_f32_16x16x32_bf16 v[58:61], v[26:29], v[58:61], 0
	v_mfma_f32_16x16x32_bf16 v[54:57], v[22:25], v[62:65], v[54:57]
	v_mfma_f32_16x16x32_bf16 v[58:61], v[30:33], v[62:65], v[58:61]
	s_barrier
	s_add_i32 s12, s58, s17
	s_mov_b32 m0, s12
	ds_read_b128 v[62:65], v155 offset:16384
	ds_read_b128 v[94:97], v155 offset:17408
	ds_read_b128 v[98:101], v155 offset:18432
	ds_read_b128 v[112:115], v155 offset:19456
	ds_read_b128 v[116:119], v155 offset:20480
	ds_read_b128 v[120:123], v155 offset:21504
	ds_read_b128 v[124:127], v155 offset:22528
	ds_read_b128 v[128:131], v155 offset:23552
	global_load_lds_dwordx4 v134, s[0:1]
	s_add_i32 m0, s12, 0x2000
	v_lshl_add_u64 v[102:103], s[0:1], 0, v[138:139]
	s_add_u32 s0, s8, 0x14000
	s_addc_u32 s1, s9, 0
	s_add_i32 s12, s59, s17
	global_load_lds_dwordx4 v[102:103], off
	s_mov_b32 m0, s12
	v_lshl_add_u64 v[148:149], s[56:57], 0, v[132:133]
	global_load_lds_dwordx4 v134, s[0:1]
	s_add_i32 m0, s12, 0x2000
	v_lshl_add_u64 v[144:145], s[56:57], 0, v[136:137]
	global_load_lds_dwordx4 v138, s[0:1]
	s_mov_b32 m0, s18
	v_lshl_add_u64 v[102:103], v[148:149], 0, s[40:41]
	global_load_lds_dwordx4 v[102:103], off
	s_mov_b32 m0, s19
	v_lshl_add_u64 v[102:103], v[144:145], 0, s[40:41]
	global_load_lds_dwordx4 v[102:103], off
	s_waitcnt vmcnt(24) lgkmcnt(0)
	s_barrier
	v_mfma_f32_16x16x32_bf16 v[158:161], v[2:5], v[62:65], 0
	v_mfma_f32_16x16x32_bf16 v[166:169], v[2:5], v[98:101], 0
	v_mfma_f32_16x16x32_bf16 v[174:177], v[2:5], v[116:119], 0
	v_mfma_f32_16x16x32_bf16 v[2:5], v[2:5], v[124:127], 0
	v_mfma_f32_16x16x32_bf16 v[158:161], v[6:9], v[94:97], v[158:161]
	v_mfma_f32_16x16x32_bf16 v[166:169], v[6:9], v[112:115], v[166:169]
	v_mfma_f32_16x16x32_bf16 v[174:177], v[6:9], v[120:123], v[174:177]
	v_mfma_f32_16x16x32_bf16 v[2:5], v[6:9], v[128:131], v[2:5]
	v_mfma_f32_16x16x32_bf16 v[6:9], v[10:13], v[124:127], 0
	v_mfma_f32_16x16x32_bf16 v[162:165], v[10:13], v[62:65], 0
	v_mfma_f32_16x16x32_bf16 v[170:173], v[10:13], v[98:101], 0
	v_mfma_f32_16x16x32_bf16 v[178:181], v[10:13], v[116:119], 0
	v_mfma_f32_16x16x32_bf16 v[6:9], v[14:17], v[128:131], v[6:9]
	v_mfma_f32_16x16x32_bf16 v[162:165], v[14:17], v[94:97], v[162:165]
	v_mfma_f32_16x16x32_bf16 v[170:173], v[14:17], v[112:115], v[170:173]
	v_mfma_f32_16x16x32_bf16 v[178:181], v[14:17], v[120:123], v[178:181]
	v_mfma_f32_16x16x32_bf16 v[14:17], v[26:29], v[62:65], 0
	v_mfma_f32_16x16x32_bf16 v[182:185], v[30:33], v[94:97], v[14:17]
	v_mfma_f32_16x16x32_bf16 v[14:17], v[18:21], v[98:101], 0
	v_mfma_f32_16x16x32_bf16 v[186:189], v[22:25], v[112:115], v[14:17]
	v_mfma_f32_16x16x32_bf16 v[14:17], v[26:29], v[98:101], 0
	v_mfma_f32_16x16x32_bf16 v[190:193], v[30:33], v[112:115], v[14:17]
	v_mfma_f32_16x16x32_bf16 v[14:17], v[18:21], v[116:119], 0
	v_mfma_f32_16x16x32_bf16 v[194:197], v[22:25], v[120:123], v[14:17]
	v_mfma_f32_16x16x32_bf16 v[14:17], v[26:29], v[116:119], 0
	v_mfma_f32_16x16x32_bf16 v[10:13], v[18:21], v[62:65], 0
	v_mfma_f32_16x16x32_bf16 v[198:201], v[30:33], v[120:123], v[14:17]
	v_mfma_f32_16x16x32_bf16 v[14:17], v[18:21], v[124:127], 0
	v_mfma_f32_16x16x32_bf16 v[10:13], v[22:25], v[94:97], v[10:13]
	v_mfma_f32_16x16x32_bf16 v[202:205], v[22:25], v[128:131], v[14:17]
	v_mfma_f32_16x16x32_bf16 v[14:17], v[26:29], v[124:127], 0
	v_mfma_f32_16x16x32_bf16 v[206:209], v[30:33], v[128:131], v[14:17]
	s_barrier
	s_add_i32 s12, 0, 0x18000
	v_add_u32_e32 v1, s12, v151
	s_add_i32 s13, 0, 0x1c000
	s_nop 1
	ds_read_b128 v[14:17], v1
	ds_read_b128 v[24:27], v1 offset:1024
	ds_read_b128 v[28:31], v1 offset:2048
	ds_read_b128 v[210:213], v1 offset:3072
	v_add_u32_e32 v1, s13, v151
	ds_read_b128 v[214:217], v1
	ds_read_b128 v[218:221], v1 offset:1024
	ds_read_b128 v[222:225], v1 offset:2048
	ds_read_b128 v[226:229], v1 offset:3072
	s_add_u32 s0, s56, 0x100100
	s_addc_u32 s1, s57, 0
	s_mov_b32 m0, s20
	ds_read_b128 v[18:21], v155 offset:32768
	ds_read_b128 v[120:123], v155 offset:33792
	ds_read_b128 v[230:233], v155 offset:34816
	ds_read_b128 v[234:237], v155 offset:35840
	ds_read_b128 v[238:241], v155 offset:36864
	ds_read_b128 v[242:245], v155 offset:37888
	ds_read_b128 v[246:249], v155 offset:38912
	ds_read_b128 v[250:253], v155 offset:39936
	global_load_lds_dwordx4 v132, s[0:1]
	s_mov_b32 m0, s21
	s_nop 0
	global_load_lds_dwordx4 v136, s[0:1]
	s_waitcnt vmcnt(24) lgkmcnt(0)
	s_barrier
	v_mfma_f32_16x16x32_bf16 v[62:65], v[14:17], v[18:21], v[66:69]
	v_mfma_f32_16x16x32_bf16 v[128:131], v[24:27], v[120:123], v[62:65]
	v_mfma_f32_16x16x32_bf16 v[62:65], v[28:31], v[18:21], v[70:73]
	v_mfma_f32_16x16x32_bf16 v[116:119], v[210:213], v[120:123], v[62:65]
	v_mfma_f32_16x16x32_bf16 v[62:65], v[14:17], v[230:233], v[74:77]
	v_mfma_f32_16x16x32_bf16 v[112:115], v[24:27], v[234:237], v[62:65]
	v_mfma_f32_16x16x32_bf16 v[62:65], v[28:31], v[230:233], v[78:81]
	v_mfma_f32_16x16x32_bf16 v[100:103], v[210:213], v[234:237], v[62:65]
	v_mfma_f32_16x16x32_bf16 v[62:65], v[14:17], v[238:241], v[82:85]
	v_mfma_f32_16x16x32_bf16 v[96:99], v[24:27], v[242:245], v[62:65]
	v_mfma_f32_16x16x32_bf16 v[62:65], v[28:31], v[238:241], v[86:89]
	v_mfma_f32_16x16x32_bf16 v[84:87], v[210:213], v[242:245], v[62:65]
	v_mfma_f32_16x16x32_bf16 v[62:65], v[14:17], v[246:249], v[90:93]
	v_mfma_f32_16x16x32_bf16 v[80:83], v[24:27], v[250:253], v[62:65]
	v_mfma_f32_16x16x32_bf16 v[62:65], v[28:31], v[246:249], v[104:107]
	v_mfma_f32_16x16x32_bf16 v[64:67], v[210:213], v[250:253], v[62:65]
	v_mfma_f32_16x16x32_bf16 v[68:71], v[214:217], v[18:21], v[108:111]
	v_mfma_f32_16x16x32_bf16 v[18:21], v[222:225], v[18:21], v[34:37]
	v_mfma_f32_16x16x32_bf16 v[124:127], v[218:221], v[120:123], v[68:71]
	v_mfma_f32_16x16x32_bf16 v[120:123], v[226:229], v[120:123], v[18:21]
	v_mfma_f32_16x16x32_bf16 v[18:21], v[214:217], v[230:233], v[38:41]
	v_mfma_f32_16x16x32_bf16 v[108:111], v[218:221], v[234:237], v[18:21]
	v_mfma_f32_16x16x32_bf16 v[18:21], v[222:225], v[230:233], v[42:45]
	v_mfma_f32_16x16x32_bf16 v[104:107], v[226:229], v[234:237], v[18:21]
	v_mfma_f32_16x16x32_bf16 v[18:21], v[214:217], v[238:241], v[46:49]
	v_mfma_f32_16x16x32_bf16 v[92:95], v[218:221], v[242:245], v[18:21]
	v_mfma_f32_16x16x32_bf16 v[18:21], v[222:225], v[238:241], v[50:53]
	v_mfma_f32_16x16x32_bf16 v[88:91], v[226:229], v[242:245], v[18:21]
	v_mfma_f32_16x16x32_bf16 v[18:21], v[214:217], v[246:249], v[54:57]
	v_mfma_f32_16x16x32_bf16 v[72:75], v[218:221], v[250:253], v[18:21]
	v_mfma_f32_16x16x32_bf16 v[18:21], v[222:225], v[246:249], v[58:61]
	v_mfma_f32_16x16x32_bf16 v[68:71], v[226:229], v[250:253], v[18:21]
	s_barrier
	s_add_u32 s0, s8, 0x18000
	s_addc_u32 s1, s9, 0
	s_add_i32 s12, s12, s17
	s_nop 1
	s_mov_b32 m0, s12
	ds_read_b128 v[40:43], v155 offset:49152
	ds_read_b128 v[44:47], v155 offset:50176
	ds_read_b128 v[230:233], v155 offset:51200
	ds_read_b128 v[234:237], v155 offset:52224
	ds_read_b128 v[238:241], v155 offset:53248
	ds_read_b128 v[242:245], v155 offset:54272
	ds_read_b128 v[246:249], v155 offset:55296
	ds_read_b128 v[250:253], v155 offset:56320
	global_load_lds_dwordx4 v134, s[0:1]
	s_add_i32 m0, s12, 0x2000
	v_lshl_add_u64 v[18:19], s[0:1], 0, v[138:139]
	s_add_u32 s0, s8, 0x1c000
	s_addc_u32 s1, s9, 0
	s_add_i32 s12, s13, s17
	global_load_lds_dwordx4 v[18:19], off
	s_mov_b32 m0, s12
	s_nop 0
	global_load_lds_dwordx4 v134, s[0:1]
	s_add_i32 m0, s12, 0x2000
	s_nop 0
	global_load_lds_dwordx4 v138, s[0:1]
	s_mov_b32 m0, s25
	v_lshl_add_u64 v[18:19], v[148:149], 0, s[42:43]
	global_load_lds_dwordx4 v[18:19], off
	s_mov_b32 m0, s33
	v_lshl_add_u64 v[18:19], v[144:145], 0, s[42:43]
	global_load_lds_dwordx4 v[18:19], off
	s_waitcnt vmcnt(8) lgkmcnt(0)
	s_barrier
	v_mfma_f32_16x16x32_bf16 v[18:21], v[14:17], v[40:43], v[158:161]
	v_mfma_f32_16x16x32_bf16 v[76:79], v[24:27], v[44:47], v[18:21]
	v_mfma_f32_16x16x32_bf16 v[18:21], v[28:31], v[40:43], v[162:165]
	v_mfma_f32_16x16x32_bf16 v[52:55], v[210:213], v[44:47], v[18:21]
	v_mfma_f32_16x16x32_bf16 v[18:21], v[14:17], v[230:233], v[166:169]
	v_mfma_f32_16x16x32_bf16 v[48:51], v[24:27], v[234:237], v[18:21]
	v_mfma_f32_16x16x32_bf16 v[18:21], v[28:31], v[230:233], v[170:173]
	v_mfma_f32_16x16x32_bf16 v[36:39], v[210:213], v[234:237], v[18:21]
	v_mfma_f32_16x16x32_bf16 v[18:21], v[14:17], v[238:241], v[174:177]
	v_mfma_f32_16x16x32_bf16 v[32:35], v[24:27], v[242:245], v[18:21]
	v_mfma_f32_16x16x32_bf16 v[18:21], v[28:31], v[238:241], v[178:181]
	v_mfma_f32_16x16x32_bf16 v[2:5], v[14:17], v[246:249], v[2:5]
	v_mfma_f32_16x16x32_bf16 v[20:23], v[210:213], v[242:245], v[18:21]
	v_mfma_f32_16x16x32_bf16 v[16:19], v[24:27], v[250:253], v[2:5]
	v_mfma_f32_16x16x32_bf16 v[2:5], v[28:31], v[246:249], v[6:9]
	v_mfma_f32_16x16x32_bf16 v[4:7], v[210:213], v[250:253], v[2:5]
	v_mfma_f32_16x16x32_bf16 v[8:11], v[214:217], v[40:43], v[10:13]
	v_mfma_f32_16x16x32_bf16 v[60:63], v[218:221], v[44:47], v[8:11]
	v_mfma_f32_16x16x32_bf16 v[8:11], v[222:225], v[40:43], v[182:185]
	v_mfma_f32_16x16x32_bf16 v[56:59], v[226:229], v[44:47], v[8:11]
	v_mfma_f32_16x16x32_bf16 v[8:11], v[214:217], v[230:233], v[186:189]
	v_mfma_f32_16x16x32_bf16 v[44:47], v[218:221], v[234:237], v[8:11]
	v_mfma_f32_16x16x32_bf16 v[8:11], v[222:225], v[230:233], v[190:193]
	v_mfma_f32_16x16x32_bf16 v[40:43], v[226:229], v[234:237], v[8:11]
	v_mfma_f32_16x16x32_bf16 v[8:11], v[214:217], v[238:241], v[194:197]
	v_mfma_f32_16x16x32_bf16 v[28:31], v[218:221], v[242:245], v[8:11]
	v_mfma_f32_16x16x32_bf16 v[8:11], v[222:225], v[238:241], v[198:201]
	v_mfma_f32_16x16x32_bf16 v[24:27], v[226:229], v[242:245], v[8:11]
	v_mfma_f32_16x16x32_bf16 v[8:11], v[214:217], v[246:249], v[202:205]
	v_mfma_f32_16x16x32_bf16 v[12:15], v[218:221], v[250:253], v[8:11]
	v_mfma_f32_16x16x32_bf16 v[8:11], v[222:225], v[246:249], v[206:209]
	v_mfma_f32_16x16x32_bf16 v[8:11], v[226:229], v[250:253], v[8:11]
	s_barrier
	s_mov_b32 s22, 2
	s_branch .LBB0_509

.LBB0_510:
	ds_read_b128 v[158:161], v153
	ds_read_b128 v[162:165], v153 offset:1024
	ds_read_b128 v[166:169], v153 offset:2048
	ds_read_b128 v[170:173], v153 offset:3072
	ds_read_b128 v[174:177], v154
	ds_read_b128 v[178:181], v154 offset:1024
	ds_read_b128 v[182:185], v154 offset:2048
	ds_read_b128 v[186:189], v154 offset:3072
	s_add_u32 s12, s64, s26
	s_addc_u32 s13, s65, 0
	s_cmp_eq_u32 s26, s8
	s_cselect_b32 s23, s0, s13
	s_cselect_b32 s22, s1, s12
	s_cselect_b32 s57, s45, s63
	s_cselect_b32 s56, s47, s62
	s_add_i32 s67, s18, 0xc000
	v_lshl_add_u64 v[144:145], v[2:3], 0, s[26:27]
	s_mov_b32 m0, s67
	s_add_i32 s66, s18, 0xe000
	ds_read_b128 v[190:193], v155
	ds_read_b128 v[194:197], v155 offset:1024
	ds_read_b128 v[198:201], v155 offset:2048
	ds_read_b128 v[202:205], v155 offset:3072
	ds_read_b128 v[206:209], v155 offset:4096
	ds_read_b128 v[210:213], v155 offset:5120
	ds_read_b128 v[214:217], v155 offset:6144
	ds_read_b128 v[218:221], v155 offset:7168
	global_load_lds_dwordx4 v[144:145], off
	s_mov_b32 m0, s66
	v_lshl_add_u64 v[144:145], v[148:149], 0, s[26:27]
	global_load_lds_dwordx4 v[144:145], off
	s_waitcnt vmcnt(8) lgkmcnt(0)
	s_barrier
	v_mfma_f32_16x16x32_bf16 v[128:131], v[158:161], v[190:193], v[128:131]
	v_mfma_f32_16x16x32_bf16 v[128:131], v[162:165], v[194:197], v[128:131]
	v_mfma_f32_16x16x32_bf16 v[116:119], v[166:169], v[190:193], v[116:119]
	v_mfma_f32_16x16x32_bf16 v[116:119], v[170:173], v[194:197], v[116:119]
	v_mfma_f32_16x16x32_bf16 v[100:103], v[166:169], v[198:201], v[100:103]
	v_mfma_f32_16x16x32_bf16 v[100:103], v[170:173], v[202:205], v[100:103]
	v_mfma_f32_16x16x32_bf16 v[112:115], v[158:161], v[198:201], v[112:115]
	v_mfma_f32_16x16x32_bf16 v[112:115], v[162:165], v[202:205], v[112:115]
	v_mfma_f32_16x16x32_bf16 v[96:99], v[158:161], v[206:209], v[96:99]
	v_mfma_f32_16x16x32_bf16 v[96:99], v[162:165], v[210:213], v[96:99]
	v_mfma_f32_16x16x32_bf16 v[84:87], v[166:169], v[206:209], v[84:87]
	v_mfma_f32_16x16x32_bf16 v[84:87], v[170:173], v[210:213], v[84:87]
	v_mfma_f32_16x16x32_bf16 v[64:67], v[166:169], v[214:217], v[64:67]
	v_mfma_f32_16x16x32_bf16 v[64:67], v[170:173], v[218:221], v[64:67]
	v_mfma_f32_16x16x32_bf16 v[80:83], v[158:161], v[214:217], v[80:83]
	v_mfma_f32_16x16x32_bf16 v[80:83], v[162:165], v[218:221], v[80:83]
	v_mfma_f32_16x16x32_bf16 v[72:75], v[174:177], v[214:217], v[72:75]
	v_mfma_f32_16x16x32_bf16 v[72:75], v[178:181], v[218:221], v[72:75]
	v_mfma_f32_16x16x32_bf16 v[68:71], v[182:185], v[214:217], v[68:71]
	v_mfma_f32_16x16x32_bf16 v[68:71], v[186:189], v[218:221], v[68:71]
	v_mfma_f32_16x16x32_bf16 v[88:91], v[182:185], v[206:209], v[88:91]
	v_mfma_f32_16x16x32_bf16 v[88:91], v[186:189], v[210:213], v[88:91]
	v_mfma_f32_16x16x32_bf16 v[92:95], v[174:177], v[206:209], v[92:95]
	v_mfma_f32_16x16x32_bf16 v[92:95], v[178:181], v[210:213], v[92:95]
	v_mfma_f32_16x16x32_bf16 v[108:111], v[174:177], v[198:201], v[108:111]
	v_mfma_f32_16x16x32_bf16 v[108:111], v[178:181], v[202:205], v[108:111]
	v_mfma_f32_16x16x32_bf16 v[104:107], v[182:185], v[198:201], v[104:107]
	v_mfma_f32_16x16x32_bf16 v[104:107], v[186:189], v[202:205], v[104:107]
	v_mfma_f32_16x16x32_bf16 v[120:123], v[182:185], v[190:193], v[120:123]
	v_mfma_f32_16x16x32_bf16 v[120:123], v[186:189], v[194:197], v[120:123]
	v_mfma_f32_16x16x32_bf16 v[124:127], v[174:177], v[190:193], v[124:127]
	v_mfma_f32_16x16x32_bf16 v[124:127], v[178:181], v[194:197], v[124:127]
	s_barrier
	s_add_i32 s12, s58, s17
	s_mov_b32 m0, s12
	ds_read_b128 v[190:193], v155 offset:16384
	ds_read_b128 v[194:197], v155 offset:17408
	ds_read_b128 v[198:201], v155 offset:18432
	ds_read_b128 v[202:205], v155 offset:19456
	ds_read_b128 v[206:209], v155 offset:20480
	ds_read_b128 v[210:213], v155 offset:21504
	ds_read_b128 v[214:217], v155 offset:22528
	ds_read_b128 v[218:221], v155 offset:23552
	global_load_lds_dwordx4 v134, s[56:57]
	s_add_i32 m0, s12, 0x2000
	s_add_u32 s12, s56, 0x4000
	s_addc_u32 s13, s57, 0
	s_add_i32 s14, s59, s17
	global_load_lds_dwordx4 v138, s[56:57]
	s_mov_b32 m0, s14
	v_lshl_add_u64 v[222:223], s[22:23], 0, v[136:137]
	global_load_lds_dwordx4 v134, s[12:13]
	s_add_i32 m0, s14, 0x2000
	s_nop 0
	global_load_lds_dwordx4 v138, s[12:13]
	s_mov_b32 m0, s18
	v_lshl_add_u64 v[144:145], s[22:23], 0, v[132:133]
	global_load_lds_dwordx4 v[144:145], off
	s_mov_b32 m0, s19
	s_nop 0
	global_load_lds_dwordx4 v[222:223], off
	s_waitcnt vmcnt(8) lgkmcnt(0)
	s_barrier
	v_mfma_f32_16x16x32_bf16 v[76:79], v[158:161], v[190:193], v[76:79]
	v_mfma_f32_16x16x32_bf16 v[76:79], v[162:165], v[194:197], v[76:79]
	v_mfma_f32_16x16x32_bf16 v[52:55], v[166:169], v[190:193], v[52:55]
	v_mfma_f32_16x16x32_bf16 v[52:55], v[170:173], v[194:197], v[52:55]
	v_mfma_f32_16x16x32_bf16 v[36:39], v[166:169], v[198:201], v[36:39]
	v_mfma_f32_16x16x32_bf16 v[36:39], v[170:173], v[202:205], v[36:39]
	v_mfma_f32_16x16x32_bf16 v[48:51], v[158:161], v[198:201], v[48:51]
	v_mfma_f32_16x16x32_bf16 v[48:51], v[162:165], v[202:205], v[48:51]
	v_mfma_f32_16x16x32_bf16 v[32:35], v[158:161], v[206:209], v[32:35]
	v_mfma_f32_16x16x32_bf16 v[32:35], v[162:165], v[210:213], v[32:35]
	v_mfma_f32_16x16x32_bf16 v[20:23], v[166:169], v[206:209], v[20:23]
	v_mfma_f32_16x16x32_bf16 v[20:23], v[170:173], v[210:213], v[20:23]
	v_mfma_f32_16x16x32_bf16 v[4:7], v[166:169], v[214:217], v[4:7]
	v_mfma_f32_16x16x32_bf16 v[4:7], v[170:173], v[218:221], v[4:7]
	v_mfma_f32_16x16x32_bf16 v[16:19], v[158:161], v[214:217], v[16:19]
	v_mfma_f32_16x16x32_bf16 v[16:19], v[162:165], v[218:221], v[16:19]
	v_mfma_f32_16x16x32_bf16 v[12:15], v[174:177], v[214:217], v[12:15]
	v_mfma_f32_16x16x32_bf16 v[12:15], v[178:181], v[218:221], v[12:15]
	v_mfma_f32_16x16x32_bf16 v[8:11], v[182:185], v[214:217], v[8:11]
	v_mfma_f32_16x16x32_bf16 v[8:11], v[186:189], v[218:221], v[8:11]
	v_mfma_f32_16x16x32_bf16 v[24:27], v[182:185], v[206:209], v[24:27]
	v_mfma_f32_16x16x32_bf16 v[24:27], v[186:189], v[210:213], v[24:27]
	v_mfma_f32_16x16x32_bf16 v[28:31], v[174:177], v[206:209], v[28:31]
	v_mfma_f32_16x16x32_bf16 v[28:31], v[178:181], v[210:213], v[28:31]
	v_mfma_f32_16x16x32_bf16 v[44:47], v[174:177], v[198:201], v[44:47]
	v_mfma_f32_16x16x32_bf16 v[44:47], v[178:181], v[202:205], v[44:47]
	v_mfma_f32_16x16x32_bf16 v[40:43], v[182:185], v[198:201], v[40:43]
	v_mfma_f32_16x16x32_bf16 v[40:43], v[186:189], v[202:205], v[40:43]
	v_mfma_f32_16x16x32_bf16 v[56:59], v[182:185], v[190:193], v[56:59]
	v_mfma_f32_16x16x32_bf16 v[56:59], v[186:189], v[194:197], v[56:59]
	v_mfma_f32_16x16x32_bf16 v[60:63], v[174:177], v[190:193], v[60:63]
	v_mfma_f32_16x16x32_bf16 v[60:63], v[178:181], v[194:197], v[60:63]
	s_barrier
	s_add_i32 s14, 0, 0x18000
	v_add_u32_e32 v1, s14, v151
	s_add_i32 s68, 0, 0x1c000
	ds_read_b128 v[158:161], v1
	ds_read_b128 v[162:165], v1 offset:1024
	ds_read_b128 v[166:169], v1 offset:2048
	ds_read_b128 v[170:173], v1 offset:3072
	v_add_u32_e32 v1, s68, v151
	ds_read_b128 v[174:177], v1
	ds_read_b128 v[178:181], v1 offset:1024
	ds_read_b128 v[182:185], v1 offset:2048
	ds_read_b128 v[186:189], v1 offset:3072
	s_add_u32 s12, s22, 0x100000
	s_addc_u32 s13, s23, 0
	s_mov_b32 m0, s20
	ds_read_b128 v[190:193], v155 offset:32768
	ds_read_b128 v[194:197], v155 offset:33792
	ds_read_b128 v[198:201], v155 offset:34816
	ds_read_b128 v[202:205], v155 offset:35840
	ds_read_b128 v[206:209], v155 offset:36864
	ds_read_b128 v[210:213], v155 offset:37888
	ds_read_b128 v[214:217], v155 offset:38912
	ds_read_b128 v[218:221], v155 offset:39936
	global_load_lds_dwordx4 v132, s[12:13]
	s_mov_b32 m0, s21
	s_nop 0
	global_load_lds_dwordx4 v136, s[12:13]
	s_waitcnt vmcnt(8) lgkmcnt(0)
	s_barrier
	v_mfma_f32_16x16x32_bf16 v[128:131], v[158:161], v[190:193], v[128:131]
	v_mfma_f32_16x16x32_bf16 v[128:131], v[162:165], v[194:197], v[128:131]
	v_mfma_f32_16x16x32_bf16 v[116:119], v[166:169], v[190:193], v[116:119]
	v_mfma_f32_16x16x32_bf16 v[116:119], v[170:173], v[194:197], v[116:119]
	v_mfma_f32_16x16x32_bf16 v[100:103], v[166:169], v[198:201], v[100:103]
	v_mfma_f32_16x16x32_bf16 v[100:103], v[170:173], v[202:205], v[100:103]
	v_mfma_f32_16x16x32_bf16 v[112:115], v[158:161], v[198:201], v[112:115]
	v_mfma_f32_16x16x32_bf16 v[112:115], v[162:165], v[202:205], v[112:115]
	v_mfma_f32_16x16x32_bf16 v[96:99], v[158:161], v[206:209], v[96:99]
	v_mfma_f32_16x16x32_bf16 v[96:99], v[162:165], v[210:213], v[96:99]
	v_mfma_f32_16x16x32_bf16 v[84:87], v[166:169], v[206:209], v[84:87]
	v_mfma_f32_16x16x32_bf16 v[84:87], v[170:173], v[210:213], v[84:87]
	v_mfma_f32_16x16x32_bf16 v[64:67], v[166:169], v[214:217], v[64:67]
	v_mfma_f32_16x16x32_bf16 v[64:67], v[170:173], v[218:221], v[64:67]
	v_mfma_f32_16x16x32_bf16 v[80:83], v[158:161], v[214:217], v[80:83]
	v_mfma_f32_16x16x32_bf16 v[80:83], v[162:165], v[218:221], v[80:83]
	v_mfma_f32_16x16x32_bf16 v[72:75], v[174:177], v[214:217], v[72:75]
	v_mfma_f32_16x16x32_bf16 v[72:75], v[178:181], v[218:221], v[72:75]
	v_mfma_f32_16x16x32_bf16 v[68:71], v[182:185], v[214:217], v[68:71]
	v_mfma_f32_16x16x32_bf16 v[68:71], v[186:189], v[218:221], v[68:71]
	v_mfma_f32_16x16x32_bf16 v[88:91], v[182:185], v[206:209], v[88:91]
	v_mfma_f32_16x16x32_bf16 v[88:91], v[186:189], v[210:213], v[88:91]
	v_mfma_f32_16x16x32_bf16 v[92:95], v[174:177], v[206:209], v[92:95]
	v_mfma_f32_16x16x32_bf16 v[92:95], v[178:181], v[210:213], v[92:95]
	v_mfma_f32_16x16x32_bf16 v[108:111], v[174:177], v[198:201], v[108:111]
	v_mfma_f32_16x16x32_bf16 v[108:111], v[178:181], v[202:205], v[108:111]
	v_mfma_f32_16x16x32_bf16 v[104:107], v[182:185], v[198:201], v[104:107]
	v_mfma_f32_16x16x32_bf16 v[104:107], v[186:189], v[202:205], v[104:107]
	v_mfma_f32_16x16x32_bf16 v[120:123], v[182:185], v[190:193], v[120:123]
	v_mfma_f32_16x16x32_bf16 v[120:123], v[186:189], v[194:197], v[120:123]
	v_mfma_f32_16x16x32_bf16 v[124:127], v[174:177], v[190:193], v[124:127]
	v_mfma_f32_16x16x32_bf16 v[124:127], v[178:181], v[194:197], v[124:127]
	s_barrier
	s_add_u32 s12, s56, 0x8000
	s_addc_u32 s13, s57, 0
	s_add_i32 s14, s14, s17
	s_mov_b32 m0, s14
	ds_read_b128 v[190:193], v155 offset:49152
	ds_read_b128 v[194:197], v155 offset:50176
	ds_read_b128 v[198:201], v155 offset:51200
	ds_read_b128 v[202:205], v155 offset:52224
	ds_read_b128 v[206:209], v155 offset:53248
	ds_read_b128 v[210:213], v155 offset:54272
	ds_read_b128 v[214:217], v155 offset:55296
	ds_read_b128 v[218:221], v155 offset:56320
	global_load_lds_dwordx4 v134, s[12:13]
	s_add_i32 m0, s14, 0x2000
	v_lshl_add_u64 v[224:225], s[12:13], 0, v[138:139]
	s_add_u32 s12, s56, 0xc000
	s_addc_u32 s13, s57, 0
	s_add_i32 s14, s68, s17
	global_load_lds_dwordx4 v[224:225], off
	s_mov_b32 m0, s14
	v_lshl_add_u64 v[144:145], v[144:145], 0, s[36:37]
	global_load_lds_dwordx4 v134, s[12:13]
	s_add_i32 m0, s14, 0x2000
	v_lshl_add_u64 v[224:225], s[12:13], 0, v[138:139]
	global_load_lds_dwordx4 v[224:225], off
	s_mov_b32 m0, s25
	s_nop 0
	global_load_lds_dwordx4 v[144:145], off
	s_mov_b32 m0, s33
	v_lshl_add_u64 v[144:145], v[222:223], 0, s[36:37]
	global_load_lds_dwordx4 v[144:145], off
	s_waitcnt vmcnt(8) lgkmcnt(0)
	s_barrier
	v_mfma_f32_16x16x32_bf16 v[76:79], v[158:161], v[190:193], v[76:79]
	v_mfma_f32_16x16x32_bf16 v[76:79], v[162:165], v[194:197], v[76:79]
	v_mfma_f32_16x16x32_bf16 v[52:55], v[166:169], v[190:193], v[52:55]
	v_mfma_f32_16x16x32_bf16 v[52:55], v[170:173], v[194:197], v[52:55]
	v_mfma_f32_16x16x32_bf16 v[36:39], v[166:169], v[198:201], v[36:39]
	v_mfma_f32_16x16x32_bf16 v[36:39], v[170:173], v[202:205], v[36:39]
	v_mfma_f32_16x16x32_bf16 v[48:51], v[158:161], v[198:201], v[48:51]
	v_mfma_f32_16x16x32_bf16 v[48:51], v[162:165], v[202:205], v[48:51]
	v_mfma_f32_16x16x32_bf16 v[32:35], v[158:161], v[206:209], v[32:35]
	v_mfma_f32_16x16x32_bf16 v[32:35], v[162:165], v[210:213], v[32:35]
	v_mfma_f32_16x16x32_bf16 v[20:23], v[166:169], v[206:209], v[20:23]
	v_mfma_f32_16x16x32_bf16 v[20:23], v[170:173], v[210:213], v[20:23]
	v_mfma_f32_16x16x32_bf16 v[4:7], v[166:169], v[214:217], v[4:7]
	v_mfma_f32_16x16x32_bf16 v[4:7], v[170:173], v[218:221], v[4:7]
	v_mfma_f32_16x16x32_bf16 v[16:19], v[158:161], v[214:217], v[16:19]
	v_mfma_f32_16x16x32_bf16 v[16:19], v[162:165], v[218:221], v[16:19]
	v_mfma_f32_16x16x32_bf16 v[12:15], v[174:177], v[214:217], v[12:15]
	v_mfma_f32_16x16x32_bf16 v[12:15], v[178:181], v[218:221], v[12:15]
	v_mfma_f32_16x16x32_bf16 v[8:11], v[182:185], v[214:217], v[8:11]
	v_mfma_f32_16x16x32_bf16 v[8:11], v[186:189], v[218:221], v[8:11]
	v_mfma_f32_16x16x32_bf16 v[24:27], v[182:185], v[206:209], v[24:27]
	v_mfma_f32_16x16x32_bf16 v[24:27], v[186:189], v[210:213], v[24:27]
	v_mfma_f32_16x16x32_bf16 v[28:31], v[174:177], v[206:209], v[28:31]
	v_mfma_f32_16x16x32_bf16 v[28:31], v[178:181], v[210:213], v[28:31]
	v_mfma_f32_16x16x32_bf16 v[44:47], v[174:177], v[198:201], v[44:47]
	v_mfma_f32_16x16x32_bf16 v[44:47], v[178:181], v[202:205], v[44:47]
	v_mfma_f32_16x16x32_bf16 v[40:43], v[182:185], v[198:201], v[40:43]
	v_mfma_f32_16x16x32_bf16 v[40:43], v[186:189], v[202:205], v[40:43]
	v_mfma_f32_16x16x32_bf16 v[56:59], v[182:185], v[190:193], v[56:59]
	v_mfma_f32_16x16x32_bf16 v[56:59], v[186:189], v[194:197], v[56:59]
	v_mfma_f32_16x16x32_bf16 v[60:63], v[174:177], v[190:193], v[60:63]
	v_mfma_f32_16x16x32_bf16 v[60:63], v[178:181], v[194:197], v[60:63]
	s_barrier
	s_add_i32 s61, s61, 2
	s_add_u32 s62, s62, 0x10000
	s_addc_u32 s63, s63, 0
	s_add_u32 s64, s64, 0x100
	s_addc_u32 s65, s65, 0
	s_add_u32 s8, s8, 0xffffff00
	s_addc_u32 s9, s9, -1
	v_lshl_add_u64 v[2:3], v[2:3], 0, s[40:41]
	s_cmp_gt_u32 s61, 61
	v_lshl_add_u64 v[148:149], v[148:149], 0, s[40:41]
	s_cbranch_scc0 .LBB0_510
	s_and_b64 vcc, exec, s[38:39]
	s_cbranch_vccz .LBB0_513
	s_barrier
.LBB0_513:
	v_cndmask_b32_e64 v1, 0, 1, s[6:7]
	v_cmp_ne_u32_e64 s[8:9], 1, v1
	s_andn2_b64 vcc, exec, s[6:7]
	s_cbranch_vccnz .LBB0_515
	s_add_u32 s0, s48, 0x100080
	s_addc_u32 s1, s49, 0
	s_mov_b32 m0, s67
	v_lshl_add_u64 v[2:3], s[0:1], 0, v[132:133]
	global_load_lds_dwordx4 v[2:3], off
	s_mov_b32 m0, s66
	s_nop 0
	global_load_lds_dwordx4 v136, s[0:1]

.LBB0_659:
	s_add_u32 s28, s78, 0x6b400000
	s_addc_u32 s29, s79, 0
	s_lshl_b32 s4, s0, 6
	s_lshl_b32 s5, s0, 13
	v_readlane_b32 s0, v254, 5
	s_lshl_b32 s0, s0, 5
	s_and_b32 s12, s0, 0x60
	s_lshr_b32 s13, s12, 3
	v_readlane_b32 s1, v254, 6
	s_add_u32 s0, s54, 0x8000
	s_addc_u32 s1, s55, 0
	s_add_i32 m0, s21, 0x18000
	s_waitcnt vmcnt(2)
	s_barrier
	global_load_lds_dwordx4 v134, s[0:1]
	v_lshl_add_u64 v[12:13], s[0:1], 0, v[138:139]
	s_add_i32 m0, s21, 0x1a000
	s_mov_b64 s[30:31], 0x80
	s_add_i32 s51, s21, 0x8000
	s_add_i32 s53, s21, 0xa000
	global_load_lds_dwordx4 v[12:13], off
	v_lshl_add_u64 v[2:3], v[2:3], 0, s[30:31]
	s_mov_b32 m0, s51
	s_add_u32 s0, s54, 0xc000
	global_load_lds_dwordx4 v[2:3], off
	v_lshl_add_u64 v[2:3], v[4:5], 0, s[30:31]
	s_mov_b32 m0, s53
	s_addc_u32 s1, s55, 0
	global_load_lds_dwordx4 v[2:3], off
	s_add_i32 m0, s21, 0x1c000
	s_nop 0
	global_load_lds_dwordx4 v134, s[0:1]
	v_lshl_add_u64 v[2:3], s[0:1], 0, v[138:139]
	s_add_i32 m0, s21, 0x1e000
	v_ashrrev_i32_e32 v4, 6, v1
	global_load_lds_dwordx4 v[2:3], off
	v_and_b32_e32 v2, 15, v1
	v_ashrrev_i32_e32 v3, 1, v1
	v_and_b32_e32 v5, 48, v1
	v_lshlrev_b32_e32 v1, 2, v1
	v_lshl_add_u32 v12, v4, 10, s5
	v_lshl_or_b32 v5, v2, 6, v5
	v_and_b32_e32 v1, 32, v1
	v_add_lshl_u32 v4, v4, s13, 10
	v_bitop3_b32 v12, v5, v12, v1 bitop3:0xde
	v_bitop3_b32 v152, v5, v4, v1 bitop3:0xde
	s_movk_i32 s0, 0xcf
	v_mov_b32_e32 v1, s4
	v_bitop3_b32 v154, v2, s0, v1 bitop3:0xc8
	v_lshlrev_b32_e32 v1, 16, v6
	v_and_b32_e32 v1, 0xfffe0000, v1
	v_or_b32_e32 v151, s4, v2
	v_lshl_add_u32 v1, v7, 13, v1
	v_and_b32_e32 v2, 1, v6
	v_lshl_or_b32 v1, v2, 6, v1
	v_and_b32_e32 v3, -8, v3
	v_lshl_add_u32 v2, v8, 1, v1
	v_lshlrev_b32_e32 v1, 16, v9
	v_add_u32_e32 v153, s12, v3
	v_mov_b32_e32 v3, v0
	s_mov_b64 s[0:1], 0x100080
	v_and_b32_e32 v1, 0xfffe0000, v1
	v_lshl_add_u64 v[140:141], v[2:3], 0, s[0:1]
	v_lshl_add_u32 v1, v10, 13, v1
	v_and_b32_e32 v2, 1, v9
	s_waitcnt vmcnt(6)
	s_cmpk_lt_u32 s88, 0x100
	v_lshl_or_b32 v1, v2, 6, v1
	s_cselect_b64 s[36:37], -1, 0
	v_lshl_add_u32 v2, v11, 1, v1
	s_add_i32 s58, 0, 0x10000
	s_add_i32 s59, 0, 0x14000
	s_mov_b32 s35, 0
	s_ashr_i32 s56, s77, 31
	v_lshl_add_u64 v[142:143], v[2:3], 0, s[0:1]
	v_mov_b64_e32 v[146:147], 0xabf
	s_movk_i32 s57, 0x159
	v_add_u32_e32 v155, s58, v152
	v_add_u32_e32 v156, s59, v152
	v_add_u32_e32 v157, 0, v12
	s_mov_b64 s[38:39], 0x100
	s_mov_b64 s[40:41], 0x180
	s_movk_i32 s60, 0x5600
	s_movk_i32 s61, 0xdf
	s_movk_i32 s62, 0xef
	s_movk_i32 s63, 0xff
	s_mov_b32 s65, 0
	s_barrier
	s_waitcnt vmcnt(0)
	s_branch .LBB0_662

.LBB0_664:
	s_cmp_lg_u32 s65, 0
	s_mov_b32 s22, 0
	s_cbranch_scc0 .LBB0_666
	ds_read_b128 v[2:5], v155
	ds_read_b128 v[6:9], v155 offset:1024
	ds_read_b128 v[10:13], v155 offset:2048
	ds_read_b128 v[14:17], v155 offset:3072
	ds_read_b128 v[18:21], v156
	ds_read_b128 v[22:25], v156 offset:1024
	ds_read_b128 v[26:29], v156 offset:2048
	ds_read_b128 v[30:33], v156 offset:3072
	s_add_u32 s0, s54, 0x10000
	s_addc_u32 s1, s55, 0
	ds_read_b128 v[34:37], v157
	ds_read_b128 v[38:41], v157 offset:1024
	ds_read_b128 v[42:45], v157 offset:2048
	ds_read_b128 v[46:49], v157 offset:3072
	ds_read_b128 v[50:53], v157 offset:4096
	ds_read_b128 v[54:57], v157 offset:5120
	ds_read_b128 v[58:61], v157 offset:6144
	ds_read_b128 v[62:65], v157 offset:7168
	s_waitcnt vmcnt(16) lgkmcnt(0)
	s_barrier
	v_mfma_f32_16x16x32_bf16 v[86:89], v[10:13], v[50:53], 0
	v_mfma_f32_16x16x32_bf16 v[92:95], v[14:17], v[54:57], v[86:89]
	v_mfma_f32_16x16x32_bf16 v[86:89], v[2:5], v[58:61], 0
	v_mfma_f32_16x16x32_bf16 v[66:69], v[2:5], v[34:37], 0
	v_mfma_f32_16x16x32_bf16 v[70:73], v[10:13], v[34:37], 0
	v_mfma_f32_16x16x32_bf16 v[74:77], v[2:5], v[42:45], 0
	v_mfma_f32_16x16x32_bf16 v[78:81], v[10:13], v[42:45], 0
	v_mfma_f32_16x16x32_bf16 v[82:85], v[2:5], v[50:53], 0
	v_mfma_f32_16x16x32_bf16 v[96:99], v[6:9], v[62:65], v[86:89]
	v_mfma_f32_16x16x32_bf16 v[86:89], v[10:13], v[58:61], 0
	v_mfma_f32_16x16x32_bf16 v[66:69], v[6:9], v[38:41], v[66:69]
	v_mfma_f32_16x16x32_bf16 v[70:73], v[14:17], v[38:41], v[70:73]
	v_mfma_f32_16x16x32_bf16 v[74:77], v[6:9], v[46:49], v[74:77]
	v_mfma_f32_16x16x32_bf16 v[78:81], v[14:17], v[46:49], v[78:81]
	v_mfma_f32_16x16x32_bf16 v[82:85], v[6:9], v[54:57], v[82:85]
	v_mfma_f32_16x16x32_bf16 v[108:111], v[14:17], v[62:65], v[86:89]
	v_mfma_f32_16x16x32_bf16 v[86:89], v[18:21], v[34:37], 0
	v_mfma_f32_16x16x32_bf16 v[34:37], v[26:29], v[34:37], 0
	v_mfma_f32_16x16x32_bf16 v[112:115], v[22:25], v[38:41], v[86:89]
	v_mfma_f32_16x16x32_bf16 v[34:37], v[30:33], v[38:41], v[34:37]
	v_mfma_f32_16x16x32_bf16 v[38:41], v[18:21], v[42:45], 0
	v_mfma_f32_16x16x32_bf16 v[42:45], v[26:29], v[42:45], 0
	v_mfma_f32_16x16x32_bf16 v[38:41], v[22:25], v[46:49], v[38:41]
	v_mfma_f32_16x16x32_bf16 v[42:45], v[30:33], v[46:49], v[42:45]
	v_mfma_f32_16x16x32_bf16 v[46:49], v[18:21], v[50:53], 0
	v_mfma_f32_16x16x32_bf16 v[50:53], v[26:29], v[50:53], 0
	v_mfma_f32_16x16x32_bf16 v[46:49], v[22:25], v[54:57], v[46:49]
	v_mfma_f32_16x16x32_bf16 v[50:53], v[30:33], v[54:57], v[50:53]
	v_mfma_f32_16x16x32_bf16 v[54:57], v[18:21], v[58:61], 0
	v_mfma_f32_16x16x32_bf16 v[58:61], v[26:29], v[58:61], 0
	v_mfma_f32_16x16x32_bf16 v[54:57], v[22:25], v[62:65], v[54:57]
	v_mfma_f32_16x16x32_bf16 v[58:61], v[30:33], v[62:65], v[58:61]
	s_barrier
	s_add_i32 s12, s58, s20
	s_mov_b32 m0, s12
	ds_read_b128 v[62:65], v157 offset:16384
	ds_read_b128 v[86:89], v157 offset:17408
	ds_read_b128 v[100:103], v157 offset:18432
	ds_read_b128 v[104:107], v157 offset:19456
	ds_read_b128 v[116:119], v157 offset:20480
	ds_read_b128 v[120:123], v157 offset:21504
	ds_read_b128 v[124:127], v157 offset:22528
	ds_read_b128 v[128:131], v157 offset:23552
	global_load_lds_dwordx4 v134, s[0:1]
	s_add_i32 m0, s12, 0x2000
	v_lshl_add_u64 v[90:91], s[0:1], 0, v[138:139]
	s_add_u32 s0, s54, 0x14000
	s_addc_u32 s1, s55, 0
	s_add_i32 s12, s59, s20
	global_load_lds_dwordx4 v[90:91], off
	s_mov_b32 m0, s12
	v_lshl_add_u64 v[148:149], s[6:7], 0, v[132:133]
	global_load_lds_dwordx4 v134, s[0:1]
	s_add_i32 m0, s12, 0x2000
	v_lshl_add_u64 v[144:145], s[6:7], 0, v[136:137]
	global_load_lds_dwordx4 v138, s[0:1]
	s_mov_b32 m0, s21
	v_lshl_add_u64 v[90:91], v[148:149], 0, s[38:39]
	global_load_lds_dwordx4 v[90:91], off
	s_mov_b32 m0, s24
	v_lshl_add_u64 v[90:91], v[144:145], 0, s[38:39]
	global_load_lds_dwordx4 v[90:91], off
	s_waitcnt vmcnt(16) lgkmcnt(0)
	s_barrier
	v_mfma_f32_16x16x32_bf16 v[158:161], v[2:5], v[62:65], 0
	v_mfma_f32_16x16x32_bf16 v[166:169], v[2:5], v[100:103], 0
	v_mfma_f32_16x16x32_bf16 v[174:177], v[2:5], v[116:119], 0
	v_mfma_f32_16x16x32_bf16 v[2:5], v[2:5], v[124:127], 0
	v_mfma_f32_16x16x32_bf16 v[158:161], v[6:9], v[86:89], v[158:161]
	v_mfma_f32_16x16x32_bf16 v[162:165], v[10:13], v[62:65], 0
	v_mfma_f32_16x16x32_bf16 v[166:169], v[6:9], v[104:107], v[166:169]
	v_mfma_f32_16x16x32_bf16 v[170:173], v[10:13], v[100:103], 0
	v_mfma_f32_16x16x32_bf16 v[174:177], v[6:9], v[120:123], v[174:177]
	v_mfma_f32_16x16x32_bf16 v[178:181], v[10:13], v[116:119], 0
	v_mfma_f32_16x16x32_bf16 v[2:5], v[6:9], v[128:131], v[2:5]
	v_mfma_f32_16x16x32_bf16 v[6:9], v[10:13], v[124:127], 0
	v_mfma_f32_16x16x32_bf16 v[162:165], v[14:17], v[86:89], v[162:165]
	v_mfma_f32_16x16x32_bf16 v[170:173], v[14:17], v[104:107], v[170:173]
	v_mfma_f32_16x16x32_bf16 v[178:181], v[14:17], v[120:123], v[178:181]
	v_mfma_f32_16x16x32_bf16 v[12:15], v[14:17], v[128:131], v[6:9]
	v_mfma_f32_16x16x32_bf16 v[6:9], v[18:21], v[62:65], 0
	v_mfma_f32_16x16x32_bf16 v[182:185], v[22:25], v[86:89], v[6:9]
	v_mfma_f32_16x16x32_bf16 v[6:9], v[26:29], v[62:65], 0
	v_mfma_f32_16x16x32_bf16 v[186:189], v[30:33], v[86:89], v[6:9]
	v_mfma_f32_16x16x32_bf16 v[6:9], v[18:21], v[100:103], 0
	v_mfma_f32_16x16x32_bf16 v[190:193], v[22:25], v[104:107], v[6:9]
	v_mfma_f32_16x16x32_bf16 v[6:9], v[26:29], v[100:103], 0
	v_mfma_f32_16x16x32_bf16 v[194:197], v[30:33], v[104:107], v[6:9]
	v_mfma_f32_16x16x32_bf16 v[6:9], v[18:21], v[116:119], 0
	v_mfma_f32_16x16x32_bf16 v[198:201], v[22:25], v[120:123], v[6:9]
	v_mfma_f32_16x16x32_bf16 v[6:9], v[26:29], v[116:119], 0
	v_mfma_f32_16x16x32_bf16 v[202:205], v[30:33], v[120:123], v[6:9]
	v_mfma_f32_16x16x32_bf16 v[6:9], v[18:21], v[124:127], 0
	v_mfma_f32_16x16x32_bf16 v[16:19], v[22:25], v[128:131], v[6:9]
	v_mfma_f32_16x16x32_bf16 v[6:9], v[26:29], v[124:127], 0
	v_mfma_f32_16x16x32_bf16 v[206:209], v[30:33], v[128:131], v[6:9]
	s_barrier
	s_add_i32 s12, 0, 0x18000
	v_add_u32_e32 v1, s12, v152
	s_add_i32 s13, 0, 0x1c000
	s_nop 1
	ds_read_b128 v[6:9], v1
	ds_read_b128 v[28:31], v1 offset:1024
	ds_read_b128 v[62:65], v1 offset:2048
	ds_read_b128 v[210:213], v1 offset:3072
	v_add_u32_e32 v1, s13, v152
	ds_read_b128 v[214:217], v1
	ds_read_b128 v[218:221], v1 offset:1024
	ds_read_b128 v[222:225], v1 offset:2048
	ds_read_b128 v[226:229], v1 offset:3072
	s_add_u32 s0, s6, 0x100100
	s_addc_u32 s1, s7, 0
	s_mov_b32 m0, s25
	ds_read_b128 v[20:23], v157 offset:32768
	ds_read_b128 v[24:27], v157 offset:33792
	ds_read_b128 v[230:233], v157 offset:34816
	ds_read_b128 v[234:237], v157 offset:35840
	ds_read_b128 v[238:241], v157 offset:36864
	ds_read_b128 v[242:245], v157 offset:37888
	ds_read_b128 v[246:249], v157 offset:38912
	ds_read_b128 v[250:253], v157 offset:39936
	global_load_lds_dwordx4 v132, s[0:1]
	s_mov_b32 m0, s33
	s_nop 0
	global_load_lds_dwordx4 v136, s[0:1]
	s_waitcnt vmcnt(16) lgkmcnt(0)
	s_barrier
	v_mfma_f32_16x16x32_bf16 v[66:69], v[6:9], v[20:23], v[66:69]
	v_mfma_f32_16x16x32_bf16 v[120:123], v[28:31], v[24:27], v[66:69]
	v_mfma_f32_16x16x32_bf16 v[66:69], v[62:65], v[20:23], v[70:73]
	v_mfma_f32_16x16x32_bf16 v[116:119], v[210:213], v[24:27], v[66:69]
	v_mfma_f32_16x16x32_bf16 v[66:69], v[6:9], v[230:233], v[74:77]
	v_mfma_f32_16x16x32_bf16 v[104:107], v[28:31], v[234:237], v[66:69]
	v_mfma_f32_16x16x32_bf16 v[66:69], v[62:65], v[230:233], v[78:81]
	v_mfma_f32_16x16x32_bf16 v[100:103], v[210:213], v[234:237], v[66:69]
	v_mfma_f32_16x16x32_bf16 v[66:69], v[6:9], v[238:241], v[82:85]
	v_mfma_f32_16x16x32_bf16 v[88:91], v[28:31], v[242:245], v[66:69]
	v_mfma_f32_16x16x32_bf16 v[66:69], v[62:65], v[238:241], v[92:95]
	v_mfma_f32_16x16x32_bf16 v[84:87], v[210:213], v[242:245], v[66:69]
	v_mfma_f32_16x16x32_bf16 v[66:69], v[6:9], v[246:249], v[96:99]
	v_mfma_f32_16x16x32_bf16 v[72:75], v[28:31], v[250:253], v[66:69]
	v_mfma_f32_16x16x32_bf16 v[66:69], v[62:65], v[246:249], v[108:111]
	v_mfma_f32_16x16x32_bf16 v[68:71], v[210:213], v[250:253], v[66:69]
	v_mfma_f32_16x16x32_bf16 v[76:79], v[214:217], v[20:23], v[112:115]
	v_mfma_f32_16x16x32_bf16 v[20:23], v[222:225], v[20:23], v[34:37]
	v_mfma_f32_16x16x32_bf16 v[124:127], v[226:229], v[24:27], v[20:23]
	v_mfma_f32_16x16x32_bf16 v[20:23], v[214:217], v[230:233], v[38:41]
	v_mfma_f32_16x16x32_bf16 v[112:115], v[218:221], v[234:237], v[20:23]
	v_mfma_f32_16x16x32_bf16 v[20:23], v[222:225], v[230:233], v[42:45]
	v_mfma_f32_16x16x32_bf16 v[108:111], v[226:229], v[234:237], v[20:23]
	v_mfma_f32_16x16x32_bf16 v[20:23], v[214:217], v[238:241], v[46:49]
	v_mfma_f32_16x16x32_bf16 v[96:99], v[218:221], v[242:245], v[20:23]
	v_mfma_f32_16x16x32_bf16 v[20:23], v[222:225], v[238:241], v[50:53]
	v_mfma_f32_16x16x32_bf16 v[92:95], v[226:229], v[242:245], v[20:23]
	v_mfma_f32_16x16x32_bf16 v[20:23], v[214:217], v[246:249], v[54:57]
	v_mfma_f32_16x16x32_bf16 v[80:83], v[218:221], v[250:253], v[20:23]
	v_mfma_f32_16x16x32_bf16 v[20:23], v[222:225], v[246:249], v[58:61]
	v_mfma_f32_16x16x32_bf16 v[128:131], v[218:221], v[24:27], v[76:79]
	v_mfma_f32_16x16x32_bf16 v[76:79], v[226:229], v[250:253], v[20:23]
	s_barrier
	s_add_u32 s0, s54, 0x18000
	s_addc_u32 s1, s55, 0
	s_add_i32 s12, s12, s20
	s_mov_b32 m0, s12
	ds_read_b128 v[32:35], v157 offset:49152
	ds_read_b128 v[44:47], v157 offset:50176
	ds_read_b128 v[230:233], v157 offset:51200
	ds_read_b128 v[234:237], v157 offset:52224
	ds_read_b128 v[238:241], v157 offset:53248
	ds_read_b128 v[242:245], v157 offset:54272
	ds_read_b128 v[246:249], v157 offset:55296
	ds_read_b128 v[250:253], v157 offset:56320
	global_load_lds_dwordx4 v134, s[0:1]
	s_add_i32 m0, s12, 0x2000
	v_lshl_add_u64 v[10:11], s[0:1], 0, v[138:139]
	s_add_u32 s0, s54, 0x1c000
	s_addc_u32 s1, s55, 0
	s_add_i32 s12, s13, s20
	global_load_lds_dwordx4 v[10:11], off
	s_mov_b32 m0, s12
	s_nop 0
	global_load_lds_dwordx4 v134, s[0:1]
	s_add_i32 m0, s12, 0x2000
	s_nop 0
	global_load_lds_dwordx4 v138, s[0:1]
	s_mov_b32 m0, s51
	v_lshl_add_u64 v[10:11], v[148:149], 0, s[40:41]
	global_load_lds_dwordx4 v[10:11], off
	s_mov_b32 m0, s53
	v_lshl_add_u64 v[10:11], v[144:145], 0, s[40:41]
	global_load_lds_dwordx4 v[10:11], off
	s_waitcnt vmcnt(8) lgkmcnt(0)
	s_barrier
	v_mfma_f32_16x16x32_bf16 v[20:23], v[6:9], v[32:35], v[158:161]
	v_mfma_f32_16x16x32_bf16 v[56:59], v[28:31], v[44:47], v[20:23]
	v_mfma_f32_16x16x32_bf16 v[20:23], v[62:65], v[32:35], v[162:165]
	v_mfma_f32_16x16x32_bf16 v[52:55], v[210:213], v[44:47], v[20:23]
	v_mfma_f32_16x16x32_bf16 v[20:23], v[6:9], v[230:233], v[166:169]
	v_mfma_f32_16x16x32_bf16 v[40:43], v[28:31], v[234:237], v[20:23]
	v_mfma_f32_16x16x32_bf16 v[20:23], v[62:65], v[230:233], v[170:173]
	v_mfma_f32_16x16x32_bf16 v[36:39], v[210:213], v[234:237], v[20:23]
	v_mfma_f32_16x16x32_bf16 v[20:23], v[6:9], v[238:241], v[174:177]
	v_mfma_f32_16x16x32_bf16 v[2:5], v[6:9], v[246:249], v[2:5]
	v_mfma_f32_16x16x32_bf16 v[24:27], v[28:31], v[242:245], v[20:23]
	v_mfma_f32_16x16x32_bf16 v[20:23], v[62:65], v[238:241], v[178:181]
	v_mfma_f32_16x16x32_bf16 v[8:11], v[28:31], v[250:253], v[2:5]
	v_mfma_f32_16x16x32_bf16 v[2:5], v[62:65], v[246:249], v[12:15]
	v_mfma_f32_16x16x32_bf16 v[20:23], v[210:213], v[242:245], v[20:23]
	v_mfma_f32_16x16x32_bf16 v[4:7], v[210:213], v[250:253], v[2:5]
	v_mfma_f32_16x16x32_bf16 v[12:15], v[214:217], v[32:35], v[182:185]
	v_mfma_f32_16x16x32_bf16 v[64:67], v[218:221], v[44:47], v[12:15]
	v_mfma_f32_16x16x32_bf16 v[12:15], v[222:225], v[32:35], v[186:189]
	v_mfma_f32_16x16x32_bf16 v[60:63], v[226:229], v[44:47], v[12:15]
	v_mfma_f32_16x16x32_bf16 v[12:15], v[214:217], v[230:233], v[190:193]
	v_mfma_f32_16x16x32_bf16 v[48:51], v[218:221], v[234:237], v[12:15]
	v_mfma_f32_16x16x32_bf16 v[12:15], v[222:225], v[230:233], v[194:197]
	v_mfma_f32_16x16x32_bf16 v[44:47], v[226:229], v[234:237], v[12:15]
	v_mfma_f32_16x16x32_bf16 v[12:15], v[214:217], v[238:241], v[198:201]
	v_mfma_f32_16x16x32_bf16 v[32:35], v[218:221], v[242:245], v[12:15]
	v_mfma_f32_16x16x32_bf16 v[12:15], v[222:225], v[238:241], v[202:205]
	v_mfma_f32_16x16x32_bf16 v[28:31], v[226:229], v[242:245], v[12:15]
	v_mfma_f32_16x16x32_bf16 v[12:15], v[214:217], v[246:249], v[16:19]
	v_mfma_f32_16x16x32_bf16 v[16:19], v[218:221], v[250:253], v[12:15]
	v_mfma_f32_16x16x32_bf16 v[12:15], v[222:225], v[246:249], v[206:209]
	v_mfma_f32_16x16x32_bf16 v[12:15], v[226:229], v[250:253], v[12:15]
	s_barrier
	s_mov_b32 s22, 2
	s_branch .LBB0_667

.LBB0_668:
	ds_read_b128 v[158:161], v155
	ds_read_b128 v[162:165], v155 offset:1024
	ds_read_b128 v[166:169], v155 offset:2048
	ds_read_b128 v[170:173], v155 offset:3072
	ds_read_b128 v[174:177], v156
	ds_read_b128 v[178:181], v156 offset:1024
	ds_read_b128 v[182:185], v156 offset:2048
	ds_read_b128 v[186:189], v156 offset:3072
	s_add_u32 s12, s70, s34
	s_addc_u32 s13, s71, 0
	s_cmp_eq_u32 s34, s6
	s_cselect_b32 s23, s0, s13
	s_cselect_b32 s22, s1, s12
	s_cselect_b32 s55, s43, s69
	s_cselect_b32 s54, s66, s68
	s_add_i32 s73, s21, 0xc000
	v_lshl_add_u64 v[144:145], v[2:3], 0, s[34:35]
	s_mov_b32 m0, s73
	s_add_i32 s72, s21, 0xe000
	ds_read_b128 v[190:193], v157
	ds_read_b128 v[194:197], v157 offset:1024
	ds_read_b128 v[198:201], v157 offset:2048
	ds_read_b128 v[202:205], v157 offset:3072
	ds_read_b128 v[206:209], v157 offset:4096
	ds_read_b128 v[210:213], v157 offset:5120
	ds_read_b128 v[214:217], v157 offset:6144
	ds_read_b128 v[218:221], v157 offset:7168
	global_load_lds_dwordx4 v[144:145], off
	s_mov_b32 m0, s72
	v_lshl_add_u64 v[144:145], v[148:149], 0, s[34:35]
	global_load_lds_dwordx4 v[144:145], off
	s_waitcnt vmcnt(8) lgkmcnt(0)
	s_barrier
	v_mfma_f32_16x16x32_bf16 v[120:123], v[158:161], v[190:193], v[120:123]
	v_mfma_f32_16x16x32_bf16 v[120:123], v[162:165], v[194:197], v[120:123]
	v_mfma_f32_16x16x32_bf16 v[116:119], v[166:169], v[190:193], v[116:119]
	v_mfma_f32_16x16x32_bf16 v[116:119], v[170:173], v[194:197], v[116:119]
	v_mfma_f32_16x16x32_bf16 v[100:103], v[166:169], v[198:201], v[100:103]
	v_mfma_f32_16x16x32_bf16 v[100:103], v[170:173], v[202:205], v[100:103]
	v_mfma_f32_16x16x32_bf16 v[104:107], v[158:161], v[198:201], v[104:107]
	v_mfma_f32_16x16x32_bf16 v[104:107], v[162:165], v[202:205], v[104:107]
	v_mfma_f32_16x16x32_bf16 v[88:91], v[158:161], v[206:209], v[88:91]
	v_mfma_f32_16x16x32_bf16 v[88:91], v[162:165], v[210:213], v[88:91]
	v_mfma_f32_16x16x32_bf16 v[84:87], v[166:169], v[206:209], v[84:87]
	v_mfma_f32_16x16x32_bf16 v[84:87], v[170:173], v[210:213], v[84:87]
	v_mfma_f32_16x16x32_bf16 v[68:71], v[166:169], v[214:217], v[68:71]
	v_mfma_f32_16x16x32_bf16 v[68:71], v[170:173], v[218:221], v[68:71]
	v_mfma_f32_16x16x32_bf16 v[72:75], v[158:161], v[214:217], v[72:75]
	v_mfma_f32_16x16x32_bf16 v[72:75], v[162:165], v[218:221], v[72:75]
	v_mfma_f32_16x16x32_bf16 v[80:83], v[174:177], v[214:217], v[80:83]
	v_mfma_f32_16x16x32_bf16 v[80:83], v[178:181], v[218:221], v[80:83]
	v_mfma_f32_16x16x32_bf16 v[76:79], v[182:185], v[214:217], v[76:79]
	v_mfma_f32_16x16x32_bf16 v[76:79], v[186:189], v[218:221], v[76:79]
	v_mfma_f32_16x16x32_bf16 v[92:95], v[182:185], v[206:209], v[92:95]
	v_mfma_f32_16x16x32_bf16 v[92:95], v[186:189], v[210:213], v[92:95]
	v_mfma_f32_16x16x32_bf16 v[96:99], v[174:177], v[206:209], v[96:99]
	v_mfma_f32_16x16x32_bf16 v[96:99], v[178:181], v[210:213], v[96:99]
	v_mfma_f32_16x16x32_bf16 v[112:115], v[174:177], v[198:201], v[112:115]
	v_mfma_f32_16x16x32_bf16 v[112:115], v[178:181], v[202:205], v[112:115]
	v_mfma_f32_16x16x32_bf16 v[108:111], v[182:185], v[198:201], v[108:111]
	v_mfma_f32_16x16x32_bf16 v[108:111], v[186:189], v[202:205], v[108:111]
	v_mfma_f32_16x16x32_bf16 v[124:127], v[182:185], v[190:193], v[124:127]
	v_mfma_f32_16x16x32_bf16 v[124:127], v[186:189], v[194:197], v[124:127]
	v_mfma_f32_16x16x32_bf16 v[128:131], v[174:177], v[190:193], v[128:131]
	v_mfma_f32_16x16x32_bf16 v[128:131], v[178:181], v[194:197], v[128:131]
	s_barrier
	s_add_i32 s12, s58, s20
	s_mov_b32 m0, s12
	ds_read_b128 v[190:193], v157 offset:16384
	ds_read_b128 v[194:197], v157 offset:17408
	ds_read_b128 v[198:201], v157 offset:18432
	ds_read_b128 v[202:205], v157 offset:19456
	ds_read_b128 v[206:209], v157 offset:20480
	ds_read_b128 v[210:213], v157 offset:21504
	ds_read_b128 v[214:217], v157 offset:22528
	ds_read_b128 v[218:221], v157 offset:23552
	global_load_lds_dwordx4 v134, s[54:55]
	s_add_i32 m0, s12, 0x2000
	s_add_u32 s12, s54, 0x4000
	s_addc_u32 s13, s55, 0
	s_add_i32 s14, s59, s20
	global_load_lds_dwordx4 v138, s[54:55]
	s_mov_b32 m0, s14
	v_lshl_add_u64 v[222:223], s[22:23], 0, v[136:137]
	global_load_lds_dwordx4 v134, s[12:13]
	s_add_i32 m0, s14, 0x2000
	s_nop 0
	global_load_lds_dwordx4 v138, s[12:13]
	s_mov_b32 m0, s21
	v_lshl_add_u64 v[144:145], s[22:23], 0, v[132:133]
	global_load_lds_dwordx4 v[144:145], off
	s_mov_b32 m0, s24
	s_nop 0
	global_load_lds_dwordx4 v[222:223], off
	s_waitcnt vmcnt(8) lgkmcnt(0)
	s_barrier
	v_mfma_f32_16x16x32_bf16 v[56:59], v[158:161], v[190:193], v[56:59]
	v_mfma_f32_16x16x32_bf16 v[56:59], v[162:165], v[194:197], v[56:59]
	v_mfma_f32_16x16x32_bf16 v[52:55], v[166:169], v[190:193], v[52:55]
	v_mfma_f32_16x16x32_bf16 v[52:55], v[170:173], v[194:197], v[52:55]
	v_mfma_f32_16x16x32_bf16 v[36:39], v[166:169], v[198:201], v[36:39]
	v_mfma_f32_16x16x32_bf16 v[36:39], v[170:173], v[202:205], v[36:39]
	v_mfma_f32_16x16x32_bf16 v[40:43], v[158:161], v[198:201], v[40:43]
	v_mfma_f32_16x16x32_bf16 v[40:43], v[162:165], v[202:205], v[40:43]
	v_mfma_f32_16x16x32_bf16 v[24:27], v[158:161], v[206:209], v[24:27]
	v_mfma_f32_16x16x32_bf16 v[24:27], v[162:165], v[210:213], v[24:27]
	v_mfma_f32_16x16x32_bf16 v[20:23], v[166:169], v[206:209], v[20:23]
	v_mfma_f32_16x16x32_bf16 v[20:23], v[170:173], v[210:213], v[20:23]
	v_mfma_f32_16x16x32_bf16 v[4:7], v[166:169], v[214:217], v[4:7]
	v_mfma_f32_16x16x32_bf16 v[4:7], v[170:173], v[218:221], v[4:7]
	v_mfma_f32_16x16x32_bf16 v[8:11], v[158:161], v[214:217], v[8:11]
	v_mfma_f32_16x16x32_bf16 v[8:11], v[162:165], v[218:221], v[8:11]
	v_mfma_f32_16x16x32_bf16 v[16:19], v[174:177], v[214:217], v[16:19]
	v_mfma_f32_16x16x32_bf16 v[16:19], v[178:181], v[218:221], v[16:19]
	v_mfma_f32_16x16x32_bf16 v[12:15], v[182:185], v[214:217], v[12:15]
	v_mfma_f32_16x16x32_bf16 v[12:15], v[186:189], v[218:221], v[12:15]
	v_mfma_f32_16x16x32_bf16 v[28:31], v[182:185], v[206:209], v[28:31]
	v_mfma_f32_16x16x32_bf16 v[28:31], v[186:189], v[210:213], v[28:31]
	v_mfma_f32_16x16x32_bf16 v[32:35], v[174:177], v[206:209], v[32:35]
	v_mfma_f32_16x16x32_bf16 v[32:35], v[178:181], v[210:213], v[32:35]
	v_mfma_f32_16x16x32_bf16 v[48:51], v[174:177], v[198:201], v[48:51]
	v_mfma_f32_16x16x32_bf16 v[48:51], v[178:181], v[202:205], v[48:51]
	v_mfma_f32_16x16x32_bf16 v[44:47], v[182:185], v[198:201], v[44:47]
	v_mfma_f32_16x16x32_bf16 v[44:47], v[186:189], v[202:205], v[44:47]
	v_mfma_f32_16x16x32_bf16 v[60:63], v[182:185], v[190:193], v[60:63]
	v_mfma_f32_16x16x32_bf16 v[60:63], v[186:189], v[194:197], v[60:63]
	v_mfma_f32_16x16x32_bf16 v[64:67], v[174:177], v[190:193], v[64:67]
	v_mfma_f32_16x16x32_bf16 v[64:67], v[178:181], v[194:197], v[64:67]
	s_barrier
	s_add_i32 s14, 0, 0x18000
	v_add_u32_e32 v1, s14, v152
	s_add_i32 s74, 0, 0x1c000
	ds_read_b128 v[158:161], v1
	ds_read_b128 v[162:165], v1 offset:1024
	ds_read_b128 v[166:169], v1 offset:2048
	ds_read_b128 v[170:173], v1 offset:3072
	v_add_u32_e32 v1, s74, v152
	ds_read_b128 v[174:177], v1
	ds_read_b128 v[178:181], v1 offset:1024
	ds_read_b128 v[182:185], v1 offset:2048
	ds_read_b128 v[186:189], v1 offset:3072
	s_add_u32 s12, s22, 0x100000
	s_addc_u32 s13, s23, 0
	s_mov_b32 m0, s25
	ds_read_b128 v[190:193], v157 offset:32768
	ds_read_b128 v[194:197], v157 offset:33792
	ds_read_b128 v[198:201], v157 offset:34816
	ds_read_b128 v[202:205], v157 offset:35840
	ds_read_b128 v[206:209], v157 offset:36864
	ds_read_b128 v[210:213], v157 offset:37888
	ds_read_b128 v[214:217], v157 offset:38912
	ds_read_b128 v[218:221], v157 offset:39936
	global_load_lds_dwordx4 v132, s[12:13]
	s_mov_b32 m0, s33
	s_nop 0
	global_load_lds_dwordx4 v136, s[12:13]
	s_waitcnt vmcnt(8) lgkmcnt(0)
	s_barrier
	v_mfma_f32_16x16x32_bf16 v[120:123], v[158:161], v[190:193], v[120:123]
	v_mfma_f32_16x16x32_bf16 v[120:123], v[162:165], v[194:197], v[120:123]
	v_mfma_f32_16x16x32_bf16 v[116:119], v[166:169], v[190:193], v[116:119]
	v_mfma_f32_16x16x32_bf16 v[116:119], v[170:173], v[194:197], v[116:119]
	v_mfma_f32_16x16x32_bf16 v[100:103], v[166:169], v[198:201], v[100:103]
	v_mfma_f32_16x16x32_bf16 v[100:103], v[170:173], v[202:205], v[100:103]
	v_mfma_f32_16x16x32_bf16 v[104:107], v[158:161], v[198:201], v[104:107]
	v_mfma_f32_16x16x32_bf16 v[104:107], v[162:165], v[202:205], v[104:107]
	v_mfma_f32_16x16x32_bf16 v[88:91], v[158:161], v[206:209], v[88:91]
	v_mfma_f32_16x16x32_bf16 v[88:91], v[162:165], v[210:213], v[88:91]
	v_mfma_f32_16x16x32_bf16 v[84:87], v[166:169], v[206:209], v[84:87]
	v_mfma_f32_16x16x32_bf16 v[84:87], v[170:173], v[210:213], v[84:87]
	v_mfma_f32_16x16x32_bf16 v[68:71], v[166:169], v[214:217], v[68:71]
	v_mfma_f32_16x16x32_bf16 v[68:71], v[170:173], v[218:221], v[68:71]
	v_mfma_f32_16x16x32_bf16 v[72:75], v[158:161], v[214:217], v[72:75]
	v_mfma_f32_16x16x32_bf16 v[72:75], v[162:165], v[218:221], v[72:75]
	v_mfma_f32_16x16x32_bf16 v[80:83], v[174:177], v[214:217], v[80:83]
	v_mfma_f32_16x16x32_bf16 v[80:83], v[178:181], v[218:221], v[80:83]
	v_mfma_f32_16x16x32_bf16 v[76:79], v[182:185], v[214:217], v[76:79]
	v_mfma_f32_16x16x32_bf16 v[76:79], v[186:189], v[218:221], v[76:79]
	v_mfma_f32_16x16x32_bf16 v[92:95], v[182:185], v[206:209], v[92:95]
	v_mfma_f32_16x16x32_bf16 v[92:95], v[186:189], v[210:213], v[92:95]
	v_mfma_f32_16x16x32_bf16 v[96:99], v[174:177], v[206:209], v[96:99]
	v_mfma_f32_16x16x32_bf16 v[96:99], v[178:181], v[210:213], v[96:99]
	v_mfma_f32_16x16x32_bf16 v[112:115], v[174:177], v[198:201], v[112:115]
	v_mfma_f32_16x16x32_bf16 v[112:115], v[178:181], v[202:205], v[112:115]
	v_mfma_f32_16x16x32_bf16 v[108:111], v[182:185], v[198:201], v[108:111]
	v_mfma_f32_16x16x32_bf16 v[108:111], v[186:189], v[202:205], v[108:111]
	v_mfma_f32_16x16x32_bf16 v[124:127], v[182:185], v[190:193], v[124:127]
	v_mfma_f32_16x16x32_bf16 v[124:127], v[186:189], v[194:197], v[124:127]
	v_mfma_f32_16x16x32_bf16 v[128:131], v[174:177], v[190:193], v[128:131]
	v_mfma_f32_16x16x32_bf16 v[128:131], v[178:181], v[194:197], v[128:131]
	s_barrier
	s_add_u32 s12, s54, 0x8000
	s_addc_u32 s13, s55, 0
	s_add_i32 s14, s14, s20
	s_mov_b32 m0, s14
	ds_read_b128 v[190:193], v157 offset:49152
	ds_read_b128 v[194:197], v157 offset:50176
	ds_read_b128 v[198:201], v157 offset:51200
	ds_read_b128 v[202:205], v157 offset:52224
	ds_read_b128 v[206:209], v157 offset:53248
	ds_read_b128 v[210:213], v157 offset:54272
	ds_read_b128 v[214:217], v157 offset:55296
	ds_read_b128 v[218:221], v157 offset:56320
	global_load_lds_dwordx4 v134, s[12:13]
	s_add_i32 m0, s14, 0x2000
	v_lshl_add_u64 v[224:225], s[12:13], 0, v[138:139]
	s_add_u32 s12, s54, 0xc000
	s_addc_u32 s13, s55, 0
	s_add_i32 s14, s74, s20
	global_load_lds_dwordx4 v[224:225], off
	s_mov_b32 m0, s14
	v_lshl_add_u64 v[144:145], v[144:145], 0, s[30:31]
	global_load_lds_dwordx4 v134, s[12:13]
	s_add_i32 m0, s14, 0x2000
	s_nop 0
	global_load_lds_dwordx4 v138, s[12:13]
	s_mov_b32 m0, s51
	s_nop 0
	global_load_lds_dwordx4 v[144:145], off
	s_mov_b32 m0, s53
	v_lshl_add_u64 v[144:145], v[222:223], 0, s[30:31]
	global_load_lds_dwordx4 v[144:145], off
	s_waitcnt vmcnt(8) lgkmcnt(0)
	s_barrier
	v_mfma_f32_16x16x32_bf16 v[56:59], v[158:161], v[190:193], v[56:59]
	v_mfma_f32_16x16x32_bf16 v[56:59], v[162:165], v[194:197], v[56:59]
	v_mfma_f32_16x16x32_bf16 v[52:55], v[166:169], v[190:193], v[52:55]
	v_mfma_f32_16x16x32_bf16 v[52:55], v[170:173], v[194:197], v[52:55]
	v_mfma_f32_16x16x32_bf16 v[36:39], v[166:169], v[198:201], v[36:39]
	v_mfma_f32_16x16x32_bf16 v[36:39], v[170:173], v[202:205], v[36:39]
	v_mfma_f32_16x16x32_bf16 v[40:43], v[158:161], v[198:201], v[40:43]
	v_mfma_f32_16x16x32_bf16 v[40:43], v[162:165], v[202:205], v[40:43]
	v_mfma_f32_16x16x32_bf16 v[24:27], v[158:161], v[206:209], v[24:27]
	v_mfma_f32_16x16x32_bf16 v[24:27], v[162:165], v[210:213], v[24:27]
	v_mfma_f32_16x16x32_bf16 v[20:23], v[166:169], v[206:209], v[20:23]
	v_mfma_f32_16x16x32_bf16 v[20:23], v[170:173], v[210:213], v[20:23]
	v_mfma_f32_16x16x32_bf16 v[4:7], v[166:169], v[214:217], v[4:7]
	v_mfma_f32_16x16x32_bf16 v[4:7], v[170:173], v[218:221], v[4:7]
	v_mfma_f32_16x16x32_bf16 v[8:11], v[158:161], v[214:217], v[8:11]
	v_mfma_f32_16x16x32_bf16 v[8:11], v[162:165], v[218:221], v[8:11]
	v_mfma_f32_16x16x32_bf16 v[16:19], v[174:177], v[214:217], v[16:19]
	v_mfma_f32_16x16x32_bf16 v[16:19], v[178:181], v[218:221], v[16:19]
	v_mfma_f32_16x16x32_bf16 v[12:15], v[182:185], v[214:217], v[12:15]
	v_mfma_f32_16x16x32_bf16 v[12:15], v[186:189], v[218:221], v[12:15]
	v_mfma_f32_16x16x32_bf16 v[28:31], v[182:185], v[206:209], v[28:31]
	v_mfma_f32_16x16x32_bf16 v[28:31], v[186:189], v[210:213], v[28:31]
	v_mfma_f32_16x16x32_bf16 v[32:35], v[174:177], v[206:209], v[32:35]
	v_mfma_f32_16x16x32_bf16 v[32:35], v[178:181], v[210:213], v[32:35]
	v_mfma_f32_16x16x32_bf16 v[48:51], v[174:177], v[198:201], v[48:51]
	v_mfma_f32_16x16x32_bf16 v[48:51], v[178:181], v[202:205], v[48:51]
	v_mfma_f32_16x16x32_bf16 v[44:47], v[182:185], v[198:201], v[44:47]
	v_mfma_f32_16x16x32_bf16 v[44:47], v[186:189], v[202:205], v[44:47]
	v_mfma_f32_16x16x32_bf16 v[60:63], v[182:185], v[190:193], v[60:63]
	v_mfma_f32_16x16x32_bf16 v[60:63], v[186:189], v[194:197], v[60:63]
	v_mfma_f32_16x16x32_bf16 v[64:67], v[174:177], v[190:193], v[64:67]
	v_mfma_f32_16x16x32_bf16 v[64:67], v[178:181], v[194:197], v[64:67]
	s_barrier
	s_add_i32 s67, s67, 2
	s_add_u32 s68, s68, 0x10000
	s_addc_u32 s69, s69, 0
	s_add_u32 s70, s70, 0x100
	s_addc_u32 s71, s71, 0
	s_add_u32 s6, s6, 0xffffff00
	s_addc_u32 s7, s7, -1
	v_lshl_add_u64 v[2:3], v[2:3], 0, s[38:39]
	s_cmp_gt_u32 s67, 61
	v_lshl_add_u64 v[148:149], v[148:149], 0, s[38:39]
	s_cbranch_scc0 .LBB0_668
	s_and_b64 vcc, exec, s[36:37]
	s_cbranch_vccnz .LBB0_676
	s_and_b64 s[0:1], s[10:11], s[4:5]
	s_andn2_b64 vcc, exec, s[0:1]
	s_cbranch_vccz .LBB0_677

.LBB0_672:
	s_add_u32 s0, s46, 0x100080
	s_addc_u32 s1, s47, 0
	s_mov_b32 m0, s73
	v_lshl_add_u64 v[2:3], s[0:1], 0, v[132:133]
	global_load_lds_dwordx4 v[2:3], off
	s_mov_b32 m0, s72
	s_nop 0
	global_load_lds_dwordx4 v136, s[0:1]

.LBB0_745:
	s_add_u32 s36, s78, 0x43400000
	s_addc_u32 s37, s79, 0
	s_add_u32 s38, s78, 0x900000
	s_addc_u32 s39, s79, 0
	s_bfe_u32 s25, s88, 0x20006
	s_add_u32 s6, s50, 0x8000
	s_addc_u32 s7, s51, 0
	s_add_i32 m0, s19, 0x18000
	s_waitcnt vmcnt(0)
	s_waitcnt vmcnt(2)
	s_barrier
	global_load_lds_dwordx4 v134, s[6:7]
	v_lshl_add_u64 v[16:17], s[6:7], 0, v[138:139]
	s_add_i32 m0, s19, 0x1a000
	s_mov_b64 s[40:41], 0x80
	s_add_i32 s33, s19, 0x8000
	s_add_i32 s54, s19, 0xa000
	global_load_lds_dwordx4 v[16:17], off
	v_lshl_add_u64 v[2:3], v[2:3], 0, s[40:41]
	s_mov_b32 m0, s33
	s_add_u32 s6, s50, 0xc000
	global_load_lds_dwordx4 v[2:3], off
	v_lshl_add_u64 v[2:3], v[4:5], 0, s[40:41]
	s_mov_b32 m0, s54
	s_addc_u32 s7, s51, 0
	global_load_lds_dwordx4 v[2:3], off
	s_add_i32 m0, s19, 0x1c000
	s_nop 0
	global_load_lds_dwordx4 v134, s[6:7]
	v_lshl_add_u64 v[2:3], s[6:7], 0, v[138:139]
	s_add_i32 m0, s19, 0x1e000
	v_and_b32_e32 v5, 48, v1
	global_load_lds_dwordx4 v[2:3], off
	v_and_b32_e32 v2, 15, v1
	v_or_b32_e32 v150, s3, v2
	v_lshlrev_b32_e32 v4, 6, v150
	s_movk_i32 s1, 0x3c0
	v_and_b32_e32 v10, 0xfffffc00, v10
	v_and_or_b32 v4, v4, s1, v5
	v_add_u32_e32 v15, s15, v10
	v_lshl_or_b32 v2, v2, 6, v5
	v_lshl_add_u32 v5, s25, 12, v10
	v_lshlrev_b32_e32 v10, 2, v1
	v_ashrrev_i32_e32 v3, 1, v1
	v_and_b32_e32 v10, 32, v10
	v_and_b32_e32 v3, -8, v3
	v_bitop3_b32 v151, v2, v5, v10 bitop3:0xde
	v_cmp_gt_u32_e64 s[6:7], 16, v1
	v_lshrrev_b32_e32 v1, 1, v6
	v_mul_lo_u32 v2, v8, s0
	s_mov_b32 s1, 0x2b000
	v_lshl_add_u32 v152, s25, 5, v3
	v_mad_u64_u32 v[2:3], s[8:9], v1, s1, v[2:3]
	v_or_b32_e32 v1, v2, v7
	v_add_lshl_u32 v2, v1, v9, 1
	v_mov_b32_e32 v3, v0
	s_mov_b64 s[8:9], 0x2b0080
	v_lshl_add_u64 v[140:141], v[2:3], 0, s[8:9]
	v_lshrrev_b32_e32 v1, 1, v11
	v_mul_lo_u32 v2, v12, s0
	v_lshlrev_b32_e32 v16, 2, v150
	v_mad_u64_u32 v[2:3], s[0:1], v1, s1, v[2:3]
	v_and_b32_e32 v16, 32, v16
	s_waitcnt vmcnt(6)
	s_cmpk_lt_u32 s88, 0x100
	v_or_b32_e32 v1, v2, v13
	v_bitop3_b32 v4, v4, v15, v16 bitop3:0xde
	s_cselect_b64 s[42:43], -1, 0
	v_add_lshl_u32 v2, v1, v14, 1
	v_mov_b32_e32 v3, v0
	s_add_i32 s57, 0, 0x10000
	s_add_i32 s58, 0, 0x14000
	v_mbcnt_lo_u32_b32 v1, -1, 0
	s_ashr_i32 s55, s77, 31
	s_ashr_i32 s56, s90, 31
	v_lshl_add_u64 v[142:143], v[2:3], 0, s[8:9]
	v_mov_b64_e32 v[146:147], 0x1ff
	v_add_u32_e32 v153, s57, v151
	v_add_u32_e32 v154, s58, v151
	v_add_u32_e32 v155, 0, v4
	s_mov_b64 s[44:45], 0x100
	s_mov_b64 s[46:47], 0x180
	v_mbcnt_hi_u32_b32 v156, -1, v1
	s_mov_b32 s22, 0
	s_barrier
	s_branch .LBB0_748

.LBB0_757:
	ds_read_b128 v[2:5], v153
	ds_read_b128 v[6:9], v153 offset:1024
	ds_read_b128 v[10:13], v153 offset:2048
	ds_read_b128 v[14:17], v153 offset:3072
	ds_read_b128 v[18:21], v154
	ds_read_b128 v[22:25], v154 offset:1024
	ds_read_b128 v[26:29], v154 offset:2048
	ds_read_b128 v[30:33], v154 offset:3072
	s_add_u32 s0, s50, 0x10000
	s_addc_u32 s1, s51, 0
	ds_read_b128 v[34:37], v155
	ds_read_b128 v[38:41], v155 offset:1024
	ds_read_b128 v[42:45], v155 offset:2048
	ds_read_b128 v[46:49], v155 offset:3072
	ds_read_b128 v[50:53], v155 offset:4096
	ds_read_b128 v[54:57], v155 offset:5120
	ds_read_b128 v[58:61], v155 offset:6144
	ds_read_b128 v[62:65], v155 offset:7168
	s_waitcnt vmcnt(24) lgkmcnt(0)
	s_barrier
	v_mfma_f32_16x16x32_bf16 v[66:69], v[2:5], v[34:37], 0
	v_mfma_f32_16x16x32_bf16 v[70:73], v[10:13], v[34:37], 0
	v_mfma_f32_16x16x32_bf16 v[74:77], v[2:5], v[42:45], 0
	v_mfma_f32_16x16x32_bf16 v[78:81], v[10:13], v[42:45], 0
	v_mfma_f32_16x16x32_bf16 v[82:85], v[2:5], v[50:53], 0
	v_mfma_f32_16x16x32_bf16 v[86:89], v[10:13], v[50:53], 0
	v_mfma_f32_16x16x32_bf16 v[90:93], v[2:5], v[58:61], 0
	v_mfma_f32_16x16x32_bf16 v[94:97], v[10:13], v[58:61], 0
	v_mfma_f32_16x16x32_bf16 v[66:69], v[6:9], v[38:41], v[66:69]
	v_mfma_f32_16x16x32_bf16 v[70:73], v[14:17], v[38:41], v[70:73]
	v_mfma_f32_16x16x32_bf16 v[74:77], v[6:9], v[46:49], v[74:77]
	v_mfma_f32_16x16x32_bf16 v[78:81], v[14:17], v[46:49], v[78:81]
	v_mfma_f32_16x16x32_bf16 v[82:85], v[6:9], v[54:57], v[82:85]
	v_mfma_f32_16x16x32_bf16 v[86:89], v[14:17], v[54:57], v[86:89]
	v_mfma_f32_16x16x32_bf16 v[90:93], v[6:9], v[62:65], v[90:93]
	v_mfma_f32_16x16x32_bf16 v[104:107], v[14:17], v[62:65], v[94:97]
	v_mfma_f32_16x16x32_bf16 v[94:97], v[18:21], v[34:37], 0
	v_mfma_f32_16x16x32_bf16 v[34:37], v[26:29], v[34:37], 0
	v_mfma_f32_16x16x32_bf16 v[108:111], v[22:25], v[38:41], v[94:97]
	v_mfma_f32_16x16x32_bf16 v[34:37], v[30:33], v[38:41], v[34:37]
	v_mfma_f32_16x16x32_bf16 v[38:41], v[18:21], v[42:45], 0
	v_mfma_f32_16x16x32_bf16 v[42:45], v[26:29], v[42:45], 0
	v_mfma_f32_16x16x32_bf16 v[38:41], v[22:25], v[46:49], v[38:41]
	v_mfma_f32_16x16x32_bf16 v[42:45], v[30:33], v[46:49], v[42:45]
	v_mfma_f32_16x16x32_bf16 v[46:49], v[18:21], v[50:53], 0
	v_mfma_f32_16x16x32_bf16 v[50:53], v[26:29], v[50:53], 0
	v_mfma_f32_16x16x32_bf16 v[46:49], v[22:25], v[54:57], v[46:49]
	v_mfma_f32_16x16x32_bf16 v[50:53], v[30:33], v[54:57], v[50:53]
	v_mfma_f32_16x16x32_bf16 v[54:57], v[18:21], v[58:61], 0
	v_mfma_f32_16x16x32_bf16 v[58:61], v[26:29], v[58:61], 0
	v_mfma_f32_16x16x32_bf16 v[54:57], v[22:25], v[62:65], v[54:57]
	v_mfma_f32_16x16x32_bf16 v[58:61], v[30:33], v[62:65], v[58:61]
	s_barrier
	s_add_i32 s12, s57, s2
	s_mov_b32 m0, s12
	ds_read_b128 v[62:65], v155 offset:16384
	ds_read_b128 v[94:97], v155 offset:17408
	ds_read_b128 v[98:101], v155 offset:18432
	ds_read_b128 v[112:115], v155 offset:19456
	ds_read_b128 v[116:119], v155 offset:20480
	ds_read_b128 v[120:123], v155 offset:21504
	ds_read_b128 v[124:127], v155 offset:22528
	ds_read_b128 v[128:131], v155 offset:23552
	global_load_lds_dwordx4 v134, s[0:1]
	s_add_i32 m0, s12, 0x2000
	v_lshl_add_u64 v[102:103], s[0:1], 0, v[138:139]
	s_add_u32 s0, s50, 0x14000
	s_addc_u32 s1, s51, 0
	s_add_i32 s12, s58, s2
	global_load_lds_dwordx4 v[102:103], off
	s_mov_b32 m0, s12
	v_lshl_add_u64 v[148:149], s[52:53], 0, v[132:133]
	global_load_lds_dwordx4 v134, s[0:1]
	s_add_i32 m0, s12, 0x2000
	v_lshl_add_u64 v[144:145], s[52:53], 0, v[136:137]
	global_load_lds_dwordx4 v138, s[0:1]
	s_mov_b32 m0, s19
	v_lshl_add_u64 v[102:103], v[148:149], 0, s[44:45]
	global_load_lds_dwordx4 v[102:103], off
	s_mov_b32 m0, s20
	v_lshl_add_u64 v[102:103], v[144:145], 0, s[44:45]
	global_load_lds_dwordx4 v[102:103], off
	s_waitcnt vmcnt(24) lgkmcnt(0)
	s_barrier
	v_mfma_f32_16x16x32_bf16 v[158:161], v[2:5], v[62:65], 0
	v_mfma_f32_16x16x32_bf16 v[166:169], v[2:5], v[98:101], 0
	v_mfma_f32_16x16x32_bf16 v[174:177], v[2:5], v[116:119], 0
	v_mfma_f32_16x16x32_bf16 v[2:5], v[2:5], v[124:127], 0
	v_mfma_f32_16x16x32_bf16 v[158:161], v[6:9], v[94:97], v[158:161]
	v_mfma_f32_16x16x32_bf16 v[166:169], v[6:9], v[112:115], v[166:169]
	v_mfma_f32_16x16x32_bf16 v[174:177], v[6:9], v[120:123], v[174:177]
	v_mfma_f32_16x16x32_bf16 v[2:5], v[6:9], v[128:131], v[2:5]
	v_mfma_f32_16x16x32_bf16 v[6:9], v[10:13], v[124:127], 0
	v_mfma_f32_16x16x32_bf16 v[162:165], v[10:13], v[62:65], 0
	v_mfma_f32_16x16x32_bf16 v[170:173], v[10:13], v[98:101], 0
	v_mfma_f32_16x16x32_bf16 v[178:181], v[10:13], v[116:119], 0
	v_mfma_f32_16x16x32_bf16 v[6:9], v[14:17], v[128:131], v[6:9]
	v_mfma_f32_16x16x32_bf16 v[162:165], v[14:17], v[94:97], v[162:165]
	v_mfma_f32_16x16x32_bf16 v[170:173], v[14:17], v[112:115], v[170:173]
	v_mfma_f32_16x16x32_bf16 v[178:181], v[14:17], v[120:123], v[178:181]
	v_mfma_f32_16x16x32_bf16 v[14:17], v[26:29], v[62:65], 0
	v_mfma_f32_16x16x32_bf16 v[182:185], v[30:33], v[94:97], v[14:17]
	v_mfma_f32_16x16x32_bf16 v[14:17], v[18:21], v[98:101], 0
	v_mfma_f32_16x16x32_bf16 v[186:189], v[22:25], v[112:115], v[14:17]
	v_mfma_f32_16x16x32_bf16 v[14:17], v[26:29], v[98:101], 0
	v_mfma_f32_16x16x32_bf16 v[190:193], v[30:33], v[112:115], v[14:17]
	v_mfma_f32_16x16x32_bf16 v[14:17], v[18:21], v[116:119], 0
	v_mfma_f32_16x16x32_bf16 v[194:197], v[22:25], v[120:123], v[14:17]
	v_mfma_f32_16x16x32_bf16 v[14:17], v[26:29], v[116:119], 0
	v_mfma_f32_16x16x32_bf16 v[10:13], v[18:21], v[62:65], 0
	v_mfma_f32_16x16x32_bf16 v[198:201], v[30:33], v[120:123], v[14:17]
	v_mfma_f32_16x16x32_bf16 v[14:17], v[18:21], v[124:127], 0
	v_mfma_f32_16x16x32_bf16 v[10:13], v[22:25], v[94:97], v[10:13]
	v_mfma_f32_16x16x32_bf16 v[202:205], v[22:25], v[128:131], v[14:17]
	v_mfma_f32_16x16x32_bf16 v[14:17], v[26:29], v[124:127], 0
	v_mfma_f32_16x16x32_bf16 v[206:209], v[30:33], v[128:131], v[14:17]
	s_barrier
	s_add_i32 s12, 0, 0x18000
	v_add_u32_e32 v1, s12, v151
	s_add_i32 s13, 0, 0x1c000
	s_nop 1
	ds_read_b128 v[14:17], v1
	ds_read_b128 v[24:27], v1 offset:1024
	ds_read_b128 v[28:31], v1 offset:2048
	ds_read_b128 v[210:213], v1 offset:3072
	v_add_u32_e32 v1, s13, v151
	ds_read_b128 v[214:217], v1
	ds_read_b128 v[218:221], v1 offset:1024
	ds_read_b128 v[222:225], v1 offset:2048
	ds_read_b128 v[226:229], v1 offset:3072
	s_add_u32 s0, s52, 0x2b0100
	s_addc_u32 s1, s53, 0
	s_mov_b32 m0, s21
	ds_read_b128 v[18:21], v155 offset:32768
	ds_read_b128 v[120:123], v155 offset:33792
	ds_read_b128 v[230:233], v155 offset:34816
	ds_read_b128 v[234:237], v155 offset:35840
	ds_read_b128 v[238:241], v155 offset:36864
	ds_read_b128 v[242:245], v155 offset:37888
	ds_read_b128 v[246:249], v155 offset:38912
	ds_read_b128 v[250:253], v155 offset:39936
	global_load_lds_dwordx4 v132, s[0:1]
	s_mov_b32 m0, s24
	s_nop 0
	global_load_lds_dwordx4 v136, s[0:1]
	s_waitcnt vmcnt(24) lgkmcnt(0)
	s_barrier
	v_mfma_f32_16x16x32_bf16 v[62:65], v[14:17], v[18:21], v[66:69]
	v_mfma_f32_16x16x32_bf16 v[128:131], v[24:27], v[120:123], v[62:65]
	v_mfma_f32_16x16x32_bf16 v[62:65], v[28:31], v[18:21], v[70:73]
	v_mfma_f32_16x16x32_bf16 v[116:119], v[210:213], v[120:123], v[62:65]
	v_mfma_f32_16x16x32_bf16 v[62:65], v[14:17], v[230:233], v[74:77]
	v_mfma_f32_16x16x32_bf16 v[112:115], v[24:27], v[234:237], v[62:65]
	v_mfma_f32_16x16x32_bf16 v[62:65], v[28:31], v[230:233], v[78:81]
	v_mfma_f32_16x16x32_bf16 v[100:103], v[210:213], v[234:237], v[62:65]
	v_mfma_f32_16x16x32_bf16 v[62:65], v[14:17], v[238:241], v[82:85]
	v_mfma_f32_16x16x32_bf16 v[96:99], v[24:27], v[242:245], v[62:65]
	v_mfma_f32_16x16x32_bf16 v[62:65], v[28:31], v[238:241], v[86:89]
	v_mfma_f32_16x16x32_bf16 v[84:87], v[210:213], v[242:245], v[62:65]
	v_mfma_f32_16x16x32_bf16 v[62:65], v[14:17], v[246:249], v[90:93]
	v_mfma_f32_16x16x32_bf16 v[80:83], v[24:27], v[250:253], v[62:65]
	v_mfma_f32_16x16x32_bf16 v[62:65], v[28:31], v[246:249], v[104:107]
	v_mfma_f32_16x16x32_bf16 v[64:67], v[210:213], v[250:253], v[62:65]
	v_mfma_f32_16x16x32_bf16 v[68:71], v[214:217], v[18:21], v[108:111]
	v_mfma_f32_16x16x32_bf16 v[18:21], v[222:225], v[18:21], v[34:37]
	v_mfma_f32_16x16x32_bf16 v[124:127], v[218:221], v[120:123], v[68:71]
	v_mfma_f32_16x16x32_bf16 v[120:123], v[226:229], v[120:123], v[18:21]
	v_mfma_f32_16x16x32_bf16 v[18:21], v[214:217], v[230:233], v[38:41]
	v_mfma_f32_16x16x32_bf16 v[108:111], v[218:221], v[234:237], v[18:21]
	v_mfma_f32_16x16x32_bf16 v[18:21], v[222:225], v[230:233], v[42:45]
	v_mfma_f32_16x16x32_bf16 v[104:107], v[226:229], v[234:237], v[18:21]
	v_mfma_f32_16x16x32_bf16 v[18:21], v[214:217], v[238:241], v[46:49]
	v_mfma_f32_16x16x32_bf16 v[92:95], v[218:221], v[242:245], v[18:21]
	v_mfma_f32_16x16x32_bf16 v[18:21], v[222:225], v[238:241], v[50:53]
	v_mfma_f32_16x16x32_bf16 v[88:91], v[226:229], v[242:245], v[18:21]
	v_mfma_f32_16x16x32_bf16 v[18:21], v[214:217], v[246:249], v[54:57]
	v_mfma_f32_16x16x32_bf16 v[72:75], v[218:221], v[250:253], v[18:21]
	v_mfma_f32_16x16x32_bf16 v[18:21], v[222:225], v[246:249], v[58:61]
	v_mfma_f32_16x16x32_bf16 v[68:71], v[226:229], v[250:253], v[18:21]
	s_barrier
	s_add_u32 s0, s50, 0x18000
	s_addc_u32 s1, s51, 0
	s_add_i32 s12, s12, s2
	s_nop 1
	s_mov_b32 m0, s12
	ds_read_b128 v[40:43], v155 offset:49152
	ds_read_b128 v[44:47], v155 offset:50176
	ds_read_b128 v[230:233], v155 offset:51200
	ds_read_b128 v[234:237], v155 offset:52224
	ds_read_b128 v[238:241], v155 offset:53248
	ds_read_b128 v[242:245], v155 offset:54272
	ds_read_b128 v[246:249], v155 offset:55296
	ds_read_b128 v[250:253], v155 offset:56320
	global_load_lds_dwordx4 v134, s[0:1]
	s_add_i32 m0, s12, 0x2000
	v_lshl_add_u64 v[18:19], s[0:1], 0, v[138:139]
	s_add_u32 s0, s50, 0x1c000
	s_addc_u32 s1, s51, 0
	s_add_i32 s12, s13, s2
	global_load_lds_dwordx4 v[18:19], off
	s_mov_b32 m0, s12
	s_nop 0
	global_load_lds_dwordx4 v134, s[0:1]
	s_add_i32 m0, s12, 0x2000
	s_nop 0
	global_load_lds_dwordx4 v138, s[0:1]
	s_mov_b32 m0, s33
	v_lshl_add_u64 v[18:19], v[148:149], 0, s[46:47]
	global_load_lds_dwordx4 v[18:19], off
	s_mov_b32 m0, s54
	v_lshl_add_u64 v[18:19], v[144:145], 0, s[46:47]
	global_load_lds_dwordx4 v[18:19], off
	s_waitcnt vmcnt(8) lgkmcnt(0)
	s_barrier
	v_mfma_f32_16x16x32_bf16 v[18:21], v[14:17], v[40:43], v[158:161]
	v_mfma_f32_16x16x32_bf16 v[76:79], v[24:27], v[44:47], v[18:21]
	v_mfma_f32_16x16x32_bf16 v[18:21], v[28:31], v[40:43], v[162:165]
	v_mfma_f32_16x16x32_bf16 v[52:55], v[210:213], v[44:47], v[18:21]
	v_mfma_f32_16x16x32_bf16 v[18:21], v[14:17], v[230:233], v[166:169]
	v_mfma_f32_16x16x32_bf16 v[48:51], v[24:27], v[234:237], v[18:21]
	v_mfma_f32_16x16x32_bf16 v[18:21], v[28:31], v[230:233], v[170:173]
	v_mfma_f32_16x16x32_bf16 v[36:39], v[210:213], v[234:237], v[18:21]
	v_mfma_f32_16x16x32_bf16 v[18:21], v[14:17], v[238:241], v[174:177]
	v_mfma_f32_16x16x32_bf16 v[32:35], v[24:27], v[242:245], v[18:21]
	v_mfma_f32_16x16x32_bf16 v[18:21], v[28:31], v[238:241], v[178:181]
	v_mfma_f32_16x16x32_bf16 v[2:5], v[14:17], v[246:249], v[2:5]
	v_mfma_f32_16x16x32_bf16 v[20:23], v[210:213], v[242:245], v[18:21]
	v_mfma_f32_16x16x32_bf16 v[16:19], v[24:27], v[250:253], v[2:5]
	v_mfma_f32_16x16x32_bf16 v[2:5], v[28:31], v[246:249], v[6:9]
	v_mfma_f32_16x16x32_bf16 v[4:7], v[210:213], v[250:253], v[2:5]
	v_mfma_f32_16x16x32_bf16 v[8:11], v[214:217], v[40:43], v[10:13]
	v_mfma_f32_16x16x32_bf16 v[60:63], v[218:221], v[44:47], v[8:11]
	v_mfma_f32_16x16x32_bf16 v[8:11], v[222:225], v[40:43], v[182:185]
	v_mfma_f32_16x16x32_bf16 v[56:59], v[226:229], v[44:47], v[8:11]
	v_mfma_f32_16x16x32_bf16 v[8:11], v[214:217], v[230:233], v[186:189]
	v_mfma_f32_16x16x32_bf16 v[44:47], v[218:221], v[234:237], v[8:11]
	v_mfma_f32_16x16x32_bf16 v[8:11], v[222:225], v[230:233], v[190:193]
	v_mfma_f32_16x16x32_bf16 v[40:43], v[226:229], v[234:237], v[8:11]
	v_mfma_f32_16x16x32_bf16 v[8:11], v[214:217], v[238:241], v[194:197]
	v_mfma_f32_16x16x32_bf16 v[28:31], v[218:221], v[242:245], v[8:11]
	v_mfma_f32_16x16x32_bf16 v[8:11], v[222:225], v[238:241], v[198:201]
	v_mfma_f32_16x16x32_bf16 v[24:27], v[226:229], v[242:245], v[8:11]
	v_mfma_f32_16x16x32_bf16 v[8:11], v[214:217], v[246:249], v[202:205]
	v_mfma_f32_16x16x32_bf16 v[12:15], v[218:221], v[250:253], v[8:11]
	v_mfma_f32_16x16x32_bf16 v[8:11], v[222:225], v[246:249], v[206:209]
	v_mfma_f32_16x16x32_bf16 v[8:11], v[226:229], v[250:253], v[8:11]
	s_barrier
	s_mov_b32 s22, 2
	s_branch .LBB0_761

.LBB0_762:
	ds_read_b128 v[158:161], v153
	ds_read_b128 v[162:165], v153 offset:1024
	ds_read_b128 v[166:169], v153 offset:2048
	ds_read_b128 v[170:173], v153 offset:3072
	ds_read_b128 v[174:177], v154
	ds_read_b128 v[178:181], v154 offset:1024
	ds_read_b128 v[182:185], v154 offset:2048
	ds_read_b128 v[186:189], v154 offset:3072
	s_add_u32 s12, s65, s30
	s_addc_u32 s13, s66, 0
	s_cmp_eq_u32 s30, s50
	s_cselect_b32 s23, s11, s13
	s_cselect_b32 s22, s10, s12
	s_cselect_b32 s53, s49, s64
	s_cselect_b32 s52, s48, s1
	s_add_i32 s68, s19, 0xc000
	v_lshl_add_u64 v[144:145], v[2:3], 0, s[30:31]
	s_mov_b32 m0, s68
	s_add_i32 s67, s19, 0xe000
	ds_read_b128 v[190:193], v155
	ds_read_b128 v[194:197], v155 offset:1024
	ds_read_b128 v[198:201], v155 offset:2048
	ds_read_b128 v[202:205], v155 offset:3072
	ds_read_b128 v[206:209], v155 offset:4096
	ds_read_b128 v[210:213], v155 offset:5120
	ds_read_b128 v[214:217], v155 offset:6144
	ds_read_b128 v[218:221], v155 offset:7168
	global_load_lds_dwordx4 v[144:145], off
	s_mov_b32 m0, s67
	v_lshl_add_u64 v[144:145], v[148:149], 0, s[30:31]
	global_load_lds_dwordx4 v[144:145], off
	s_waitcnt vmcnt(8) lgkmcnt(0)
	s_barrier
	v_mfma_f32_16x16x32_bf16 v[128:131], v[158:161], v[190:193], v[128:131]
	v_mfma_f32_16x16x32_bf16 v[128:131], v[162:165], v[194:197], v[128:131]
	v_mfma_f32_16x16x32_bf16 v[116:119], v[166:169], v[190:193], v[116:119]
	v_mfma_f32_16x16x32_bf16 v[116:119], v[170:173], v[194:197], v[116:119]
	v_mfma_f32_16x16x32_bf16 v[100:103], v[166:169], v[198:201], v[100:103]
	v_mfma_f32_16x16x32_bf16 v[100:103], v[170:173], v[202:205], v[100:103]
	v_mfma_f32_16x16x32_bf16 v[112:115], v[158:161], v[198:201], v[112:115]
	v_mfma_f32_16x16x32_bf16 v[112:115], v[162:165], v[202:205], v[112:115]
	v_mfma_f32_16x16x32_bf16 v[96:99], v[158:161], v[206:209], v[96:99]
	v_mfma_f32_16x16x32_bf16 v[96:99], v[162:165], v[210:213], v[96:99]
	v_mfma_f32_16x16x32_bf16 v[84:87], v[166:169], v[206:209], v[84:87]
	v_mfma_f32_16x16x32_bf16 v[84:87], v[170:173], v[210:213], v[84:87]
	v_mfma_f32_16x16x32_bf16 v[64:67], v[166:169], v[214:217], v[64:67]
	v_mfma_f32_16x16x32_bf16 v[64:67], v[170:173], v[218:221], v[64:67]
	v_mfma_f32_16x16x32_bf16 v[80:83], v[158:161], v[214:217], v[80:83]
	v_mfma_f32_16x16x32_bf16 v[80:83], v[162:165], v[218:221], v[80:83]
	v_mfma_f32_16x16x32_bf16 v[72:75], v[174:177], v[214:217], v[72:75]
	v_mfma_f32_16x16x32_bf16 v[72:75], v[178:181], v[218:221], v[72:75]
	v_mfma_f32_16x16x32_bf16 v[68:71], v[182:185], v[214:217], v[68:71]
	v_mfma_f32_16x16x32_bf16 v[68:71], v[186:189], v[218:221], v[68:71]
	v_mfma_f32_16x16x32_bf16 v[88:91], v[182:185], v[206:209], v[88:91]
	v_mfma_f32_16x16x32_bf16 v[88:91], v[186:189], v[210:213], v[88:91]
	v_mfma_f32_16x16x32_bf16 v[92:95], v[174:177], v[206:209], v[92:95]
	v_mfma_f32_16x16x32_bf16 v[92:95], v[178:181], v[210:213], v[92:95]
	v_mfma_f32_16x16x32_bf16 v[108:111], v[174:177], v[198:201], v[108:111]
	v_mfma_f32_16x16x32_bf16 v[108:111], v[178:181], v[202:205], v[108:111]
	v_mfma_f32_16x16x32_bf16 v[104:107], v[182:185], v[198:201], v[104:107]
	v_mfma_f32_16x16x32_bf16 v[104:107], v[186:189], v[202:205], v[104:107]
	v_mfma_f32_16x16x32_bf16 v[120:123], v[182:185], v[190:193], v[120:123]
	v_mfma_f32_16x16x32_bf16 v[120:123], v[186:189], v[194:197], v[120:123]
	v_mfma_f32_16x16x32_bf16 v[124:127], v[174:177], v[190:193], v[124:127]
	v_mfma_f32_16x16x32_bf16 v[124:127], v[178:181], v[194:197], v[124:127]
	s_barrier
	s_add_i32 s12, s57, s2
	s_mov_b32 m0, s12
	ds_read_b128 v[190:193], v155 offset:16384
	ds_read_b128 v[194:197], v155 offset:17408
	ds_read_b128 v[198:201], v155 offset:18432
	ds_read_b128 v[202:205], v155 offset:19456
	ds_read_b128 v[206:209], v155 offset:20480
	ds_read_b128 v[210:213], v155 offset:21504
	ds_read_b128 v[214:217], v155 offset:22528
	ds_read_b128 v[218:221], v155 offset:23552
	global_load_lds_dwordx4 v134, s[52:53]
	s_add_i32 m0, s12, 0x2000
	s_add_u32 s12, s52, 0x4000
	s_addc_u32 s13, s53, 0
	s_add_i32 s14, s58, s2
	global_load_lds_dwordx4 v138, s[52:53]
	s_mov_b32 m0, s14
	v_lshl_add_u64 v[222:223], s[22:23], 0, v[136:137]
	global_load_lds_dwordx4 v134, s[12:13]
	s_add_i32 m0, s14, 0x2000
	s_nop 0
	global_load_lds_dwordx4 v138, s[12:13]
	s_mov_b32 m0, s19
	v_lshl_add_u64 v[144:145], s[22:23], 0, v[132:133]
	global_load_lds_dwordx4 v[144:145], off
	s_mov_b32 m0, s20
	s_nop 0
	global_load_lds_dwordx4 v[222:223], off
	s_waitcnt vmcnt(8) lgkmcnt(0)
	s_barrier
	v_mfma_f32_16x16x32_bf16 v[76:79], v[158:161], v[190:193], v[76:79]
	v_mfma_f32_16x16x32_bf16 v[76:79], v[162:165], v[194:197], v[76:79]
	v_mfma_f32_16x16x32_bf16 v[52:55], v[166:169], v[190:193], v[52:55]
	v_mfma_f32_16x16x32_bf16 v[52:55], v[170:173], v[194:197], v[52:55]
	v_mfma_f32_16x16x32_bf16 v[36:39], v[166:169], v[198:201], v[36:39]
	v_mfma_f32_16x16x32_bf16 v[36:39], v[170:173], v[202:205], v[36:39]
	v_mfma_f32_16x16x32_bf16 v[48:51], v[158:161], v[198:201], v[48:51]
	v_mfma_f32_16x16x32_bf16 v[48:51], v[162:165], v[202:205], v[48:51]
	v_mfma_f32_16x16x32_bf16 v[32:35], v[158:161], v[206:209], v[32:35]
	v_mfma_f32_16x16x32_bf16 v[32:35], v[162:165], v[210:213], v[32:35]
	v_mfma_f32_16x16x32_bf16 v[20:23], v[166:169], v[206:209], v[20:23]
	v_mfma_f32_16x16x32_bf16 v[20:23], v[170:173], v[210:213], v[20:23]
	v_mfma_f32_16x16x32_bf16 v[4:7], v[166:169], v[214:217], v[4:7]
	v_mfma_f32_16x16x32_bf16 v[4:7], v[170:173], v[218:221], v[4:7]
	v_mfma_f32_16x16x32_bf16 v[16:19], v[158:161], v[214:217], v[16:19]
	v_mfma_f32_16x16x32_bf16 v[16:19], v[162:165], v[218:221], v[16:19]
	v_mfma_f32_16x16x32_bf16 v[12:15], v[174:177], v[214:217], v[12:15]
	v_mfma_f32_16x16x32_bf16 v[12:15], v[178:181], v[218:221], v[12:15]
	v_mfma_f32_16x16x32_bf16 v[8:11], v[182:185], v[214:217], v[8:11]
	v_mfma_f32_16x16x32_bf16 v[8:11], v[186:189], v[218:221], v[8:11]
	v_mfma_f32_16x16x32_bf16 v[24:27], v[182:185], v[206:209], v[24:27]
	v_mfma_f32_16x16x32_bf16 v[24:27], v[186:189], v[210:213], v[24:27]
	v_mfma_f32_16x16x32_bf16 v[28:31], v[174:177], v[206:209], v[28:31]
	v_mfma_f32_16x16x32_bf16 v[28:31], v[178:181], v[210:213], v[28:31]
	v_mfma_f32_16x16x32_bf16 v[44:47], v[174:177], v[198:201], v[44:47]
	v_mfma_f32_16x16x32_bf16 v[44:47], v[178:181], v[202:205], v[44:47]
	v_mfma_f32_16x16x32_bf16 v[40:43], v[182:185], v[198:201], v[40:43]
	v_mfma_f32_16x16x32_bf16 v[40:43], v[186:189], v[202:205], v[40:43]
	v_mfma_f32_16x16x32_bf16 v[56:59], v[182:185], v[190:193], v[56:59]
	v_mfma_f32_16x16x32_bf16 v[56:59], v[186:189], v[194:197], v[56:59]
	v_mfma_f32_16x16x32_bf16 v[60:63], v[174:177], v[190:193], v[60:63]
	v_mfma_f32_16x16x32_bf16 v[60:63], v[178:181], v[194:197], v[60:63]
	s_barrier
	s_add_i32 s14, 0, 0x18000
	v_add_u32_e32 v1, s14, v151
	s_add_i32 s69, 0, 0x1c000
	ds_read_b128 v[158:161], v1
	ds_read_b128 v[162:165], v1 offset:1024
	ds_read_b128 v[166:169], v1 offset:2048
	ds_read_b128 v[170:173], v1 offset:3072
	v_add_u32_e32 v1, s69, v151
	ds_read_b128 v[174:177], v1
	ds_read_b128 v[178:181], v1 offset:1024
	ds_read_b128 v[182:185], v1 offset:2048
	ds_read_b128 v[186:189], v1 offset:3072
	s_add_u32 s12, s22, 0x2b0000
	s_addc_u32 s13, s23, 0
	s_mov_b32 m0, s21
	ds_read_b128 v[190:193], v155 offset:32768
	ds_read_b128 v[194:197], v155 offset:33792
	ds_read_b128 v[198:201], v155 offset:34816
	ds_read_b128 v[202:205], v155 offset:35840
	ds_read_b128 v[206:209], v155 offset:36864
	ds_read_b128 v[210:213], v155 offset:37888
	ds_read_b128 v[214:217], v155 offset:38912
	ds_read_b128 v[218:221], v155 offset:39936
	global_load_lds_dwordx4 v132, s[12:13]
	s_mov_b32 m0, s24
	s_nop 0
	global_load_lds_dwordx4 v136, s[12:13]
	s_waitcnt vmcnt(8) lgkmcnt(0)
	s_barrier
	v_mfma_f32_16x16x32_bf16 v[128:131], v[158:161], v[190:193], v[128:131]
	v_mfma_f32_16x16x32_bf16 v[128:131], v[162:165], v[194:197], v[128:131]
	v_mfma_f32_16x16x32_bf16 v[116:119], v[166:169], v[190:193], v[116:119]
	v_mfma_f32_16x16x32_bf16 v[116:119], v[170:173], v[194:197], v[116:119]
	v_mfma_f32_16x16x32_bf16 v[100:103], v[166:169], v[198:201], v[100:103]
	v_mfma_f32_16x16x32_bf16 v[100:103], v[170:173], v[202:205], v[100:103]
	v_mfma_f32_16x16x32_bf16 v[112:115], v[158:161], v[198:201], v[112:115]
	v_mfma_f32_16x16x32_bf16 v[112:115], v[162:165], v[202:205], v[112:115]
	v_mfma_f32_16x16x32_bf16 v[96:99], v[158:161], v[206:209], v[96:99]
	v_mfma_f32_16x16x32_bf16 v[96:99], v[162:165], v[210:213], v[96:99]
	v_mfma_f32_16x16x32_bf16 v[84:87], v[166:169], v[206:209], v[84:87]
	v_mfma_f32_16x16x32_bf16 v[84:87], v[170:173], v[210:213], v[84:87]
	v_mfma_f32_16x16x32_bf16 v[64:67], v[166:169], v[214:217], v[64:67]
	v_mfma_f32_16x16x32_bf16 v[64:67], v[170:173], v[218:221], v[64:67]
	v_mfma_f32_16x16x32_bf16 v[80:83], v[158:161], v[214:217], v[80:83]
	v_mfma_f32_16x16x32_bf16 v[80:83], v[162:165], v[218:221], v[80:83]
	v_mfma_f32_16x16x32_bf16 v[72:75], v[174:177], v[214:217], v[72:75]
	v_mfma_f32_16x16x32_bf16 v[72:75], v[178:181], v[218:221], v[72:75]
	v_mfma_f32_16x16x32_bf16 v[68:71], v[182:185], v[214:217], v[68:71]
	v_mfma_f32_16x16x32_bf16 v[68:71], v[186:189], v[218:221], v[68:71]
	v_mfma_f32_16x16x32_bf16 v[88:91], v[182:185], v[206:209], v[88:91]
	v_mfma_f32_16x16x32_bf16 v[88:91], v[186:189], v[210:213], v[88:91]
	v_mfma_f32_16x16x32_bf16 v[92:95], v[174:177], v[206:209], v[92:95]
	v_mfma_f32_16x16x32_bf16 v[92:95], v[178:181], v[210:213], v[92:95]
	v_mfma_f32_16x16x32_bf16 v[108:111], v[174:177], v[198:201], v[108:111]
	v_mfma_f32_16x16x32_bf16 v[108:111], v[178:181], v[202:205], v[108:111]
	v_mfma_f32_16x16x32_bf16 v[104:107], v[182:185], v[198:201], v[104:107]
	v_mfma_f32_16x16x32_bf16 v[104:107], v[186:189], v[202:205], v[104:107]
	v_mfma_f32_16x16x32_bf16 v[120:123], v[182:185], v[190:193], v[120:123]
	v_mfma_f32_16x16x32_bf16 v[120:123], v[186:189], v[194:197], v[120:123]
	v_mfma_f32_16x16x32_bf16 v[124:127], v[174:177], v[190:193], v[124:127]
	v_mfma_f32_16x16x32_bf16 v[124:127], v[178:181], v[194:197], v[124:127]
	s_barrier
	s_add_u32 s12, s52, 0x8000
	s_addc_u32 s13, s53, 0
	s_add_i32 s14, s14, s2
	s_mov_b32 m0, s14
	ds_read_b128 v[190:193], v155 offset:49152
	ds_read_b128 v[194:197], v155 offset:50176
	ds_read_b128 v[198:201], v155 offset:51200
	ds_read_b128 v[202:205], v155 offset:52224
	ds_read_b128 v[206:209], v155 offset:53248
	ds_read_b128 v[210:213], v155 offset:54272
	ds_read_b128 v[214:217], v155 offset:55296
	ds_read_b128 v[218:221], v155 offset:56320
	global_load_lds_dwordx4 v134, s[12:13]
	s_add_i32 m0, s14, 0x2000
	v_lshl_add_u64 v[224:225], s[12:13], 0, v[138:139]
	s_add_u32 s12, s52, 0xc000
	s_addc_u32 s13, s53, 0
	s_add_i32 s14, s69, s2
	global_load_lds_dwordx4 v[224:225], off
	s_mov_b32 m0, s14
	v_lshl_add_u64 v[144:145], v[144:145], 0, s[40:41]
	global_load_lds_dwordx4 v134, s[12:13]
	s_add_i32 m0, s14, 0x2000
	s_nop 0
	global_load_lds_dwordx4 v138, s[12:13]
	s_mov_b32 m0, s33
	s_nop 0
	global_load_lds_dwordx4 v[144:145], off
	s_mov_b32 m0, s54
	v_lshl_add_u64 v[144:145], v[222:223], 0, s[40:41]
	global_load_lds_dwordx4 v[144:145], off
	s_waitcnt vmcnt(8) lgkmcnt(0)
	s_barrier
	v_mfma_f32_16x16x32_bf16 v[76:79], v[158:161], v[190:193], v[76:79]
	v_mfma_f32_16x16x32_bf16 v[76:79], v[162:165], v[194:197], v[76:79]
	v_mfma_f32_16x16x32_bf16 v[52:55], v[166:169], v[190:193], v[52:55]
	v_mfma_f32_16x16x32_bf16 v[52:55], v[170:173], v[194:197], v[52:55]
	v_mfma_f32_16x16x32_bf16 v[36:39], v[166:169], v[198:201], v[36:39]
	v_mfma_f32_16x16x32_bf16 v[36:39], v[170:173], v[202:205], v[36:39]
	v_mfma_f32_16x16x32_bf16 v[48:51], v[158:161], v[198:201], v[48:51]
	v_mfma_f32_16x16x32_bf16 v[48:51], v[162:165], v[202:205], v[48:51]
	v_mfma_f32_16x16x32_bf16 v[32:35], v[158:161], v[206:209], v[32:35]
	v_mfma_f32_16x16x32_bf16 v[32:35], v[162:165], v[210:213], v[32:35]
	v_mfma_f32_16x16x32_bf16 v[20:23], v[166:169], v[206:209], v[20:23]
	v_mfma_f32_16x16x32_bf16 v[20:23], v[170:173], v[210:213], v[20:23]
	v_mfma_f32_16x16x32_bf16 v[4:7], v[166:169], v[214:217], v[4:7]
	v_mfma_f32_16x16x32_bf16 v[4:7], v[170:173], v[218:221], v[4:7]
	v_mfma_f32_16x16x32_bf16 v[16:19], v[158:161], v[214:217], v[16:19]
	v_mfma_f32_16x16x32_bf16 v[16:19], v[162:165], v[218:221], v[16:19]
	v_mfma_f32_16x16x32_bf16 v[12:15], v[174:177], v[214:217], v[12:15]
	v_mfma_f32_16x16x32_bf16 v[12:15], v[178:181], v[218:221], v[12:15]
	v_mfma_f32_16x16x32_bf16 v[8:11], v[182:185], v[214:217], v[8:11]
	v_mfma_f32_16x16x32_bf16 v[8:11], v[186:189], v[218:221], v[8:11]
	v_mfma_f32_16x16x32_bf16 v[24:27], v[182:185], v[206:209], v[24:27]
	v_mfma_f32_16x16x32_bf16 v[24:27], v[186:189], v[210:213], v[24:27]
	v_mfma_f32_16x16x32_bf16 v[28:31], v[174:177], v[206:209], v[28:31]
	v_mfma_f32_16x16x32_bf16 v[28:31], v[178:181], v[210:213], v[28:31]
	v_mfma_f32_16x16x32_bf16 v[44:47], v[174:177], v[198:201], v[44:47]
	v_mfma_f32_16x16x32_bf16 v[44:47], v[178:181], v[202:205], v[44:47]
	v_mfma_f32_16x16x32_bf16 v[40:43], v[182:185], v[198:201], v[40:43]
	v_mfma_f32_16x16x32_bf16 v[40:43], v[186:189], v[202:205], v[40:43]
	v_mfma_f32_16x16x32_bf16 v[56:59], v[182:185], v[190:193], v[56:59]
	v_mfma_f32_16x16x32_bf16 v[56:59], v[186:189], v[194:197], v[56:59]
	v_mfma_f32_16x16x32_bf16 v[60:63], v[174:177], v[190:193], v[60:63]
	v_mfma_f32_16x16x32_bf16 v[60:63], v[178:181], v[194:197], v[60:63]
	s_barrier
	s_add_i32 s0, s0, 2
	s_add_u32 s1, s1, 0x10000
	s_addc_u32 s64, s64, 0
	s_add_u32 s65, s65, 0x100
	s_addc_u32 s66, s66, 0
	s_add_u32 s50, s50, 0xffffff00
	s_addc_u32 s51, s51, -1
	v_lshl_add_u64 v[2:3], v[2:3], 0, s[44:45]
	s_cmpk_gt_u32 s0, 0xa9
	v_lshl_add_u64 v[148:149], v[148:149], 0, s[44:45]
	s_cbranch_scc0 .LBB0_762
	s_and_b64 vcc, exec, s[42:43]
	s_cbranch_vccz .LBB0_765
	s_barrier
.LBB0_765:
	s_and_b64 vcc, exec, s[8:9]
	s_cbranch_vccnz .LBB0_767
	s_add_u32 s0, s10, 0x2b0080
	s_addc_u32 s1, s11, 0
	s_mov_b32 m0, s68
	v_lshl_add_u64 v[2:3], s[0:1], 0, v[132:133]
	global_load_lds_dwordx4 v[2:3], off
	s_mov_b32 m0, s67
	s_nop 0
	global_load_lds_dwordx4 v136, s[0:1]

.LBB0_792:
	v_readlane_b32 s0, v254, 5
	s_lshl_b32 s0, s0, 5
	s_and_b32 s6, s0, 0x60
	s_lshr_b32 s7, s6, 3
	v_readlane_b32 s1, v254, 6
	s_add_u32 s0, s56, 0x8000
	s_addc_u32 s1, s57, 0
	s_add_i32 m0, s33, 0x18000
	s_waitcnt vmcnt(2)
	s_barrier
	global_load_lds_dwordx4 v134, s[0:1]
	v_lshl_add_u64 v[12:13], s[0:1], 0, v[138:139]
	s_add_i32 m0, s33, 0x1a000
	s_mov_b64 s[34:35], 0x80
	s_add_i32 s16, s33, 0x8000
	s_add_i32 s59, s33, 0xa000
	global_load_lds_dwordx4 v[12:13], off
	v_lshl_add_u64 v[2:3], v[2:3], 0, s[34:35]
	s_mov_b32 m0, s16
	s_add_u32 s0, s56, 0xc000
	global_load_lds_dwordx4 v[2:3], off
	v_lshl_add_u64 v[2:3], v[4:5], 0, s[34:35]
	s_mov_b32 m0, s59
	s_addc_u32 s1, s57, 0
	global_load_lds_dwordx4 v[2:3], off
	s_add_i32 m0, s33, 0x1c000
	s_nop 0
	global_load_lds_dwordx4 v134, s[0:1]
	v_lshl_add_u64 v[2:3], s[0:1], 0, v[138:139]
	s_add_i32 m0, s33, 0x1e000
	v_ashrrev_i32_e32 v4, 6, v1
	global_load_lds_dwordx4 v[2:3], off
	v_and_b32_e32 v2, 15, v1
	v_or_b32_e32 v151, s3, v2
	v_ashrrev_i32_e32 v3, 1, v1
	v_lshlrev_b32_e32 v5, 6, v151
	v_and_b32_e32 v12, 48, v1
	s_movk_i32 s0, 0x3c0
	v_lshlrev_b32_e32 v1, 2, v1
	v_and_or_b32 v5, v5, s0, v12
	v_lshl_add_u32 v13, v4, 10, s15
	v_lshl_or_b32 v12, v2, 6, v12
	v_add_lshl_u32 v4, v4, s7, 10
	v_and_b32_e32 v1, 32, v1
	v_bitop3_b32 v152, v12, v4, v1 bitop3:0xde
	s_movk_i32 s0, 0xcf
	v_mov_b32_e32 v1, s3
	v_bitop3_b32 v154, v2, s0, v1 bitop3:0xc8
	v_lshlrev_b32_e32 v1, 16, v6
	v_and_b32_e32 v1, 0xfffe0000, v1
	v_lshl_add_u32 v1, v7, 13, v1
	v_and_b32_e32 v2, 1, v6
	v_lshl_or_b32 v1, v2, 6, v1
	v_and_b32_e32 v3, -8, v3
	v_lshl_add_u32 v2, v8, 1, v1
	v_lshlrev_b32_e32 v1, 16, v9
	v_add_u32_e32 v153, s6, v3
	v_mov_b32_e32 v3, v0
	s_mov_b64 s[0:1], 0x100080
	v_and_b32_e32 v1, 0xfffe0000, v1
	v_lshlrev_b32_e32 v14, 2, v151
	v_lshl_add_u64 v[140:141], v[2:3], 0, s[0:1]
	v_lshl_add_u32 v1, v10, 13, v1
	v_and_b32_e32 v2, 1, v9
	v_and_b32_e32 v14, 32, v14
	s_waitcnt vmcnt(6)
	s_cmpk_lt_u32 s88, 0x100
	v_lshl_or_b32 v1, v2, 6, v1
	v_bitop3_b32 v5, v5, v13, v14 bitop3:0xde
	s_cselect_b64 s[38:39], -1, 0
	v_lshl_add_u32 v2, v11, 1, v1
	s_add_i32 s60, 0, 0x10000
	s_add_i32 s61, 0, 0x14000
	s_mov_b32 s37, 0
	s_ashr_i32 s3, s77, 31
	v_lshl_add_u64 v[142:143], v[2:3], 0, s[0:1]
	v_mov_b64_e32 v[146:147], 0xabf
	s_movk_i32 s15, 0x159
	v_add_u32_e32 v155, s60, v152
	v_add_u32_e32 v156, s61, v152
	v_add_u32_e32 v157, 0, v5
	s_mov_b64 s[40:41], 0x100
	s_mov_b64 s[42:43], 0x180
	s_movk_i32 s62, 0x5600
	s_movk_i32 s63, 0xdf
	s_movk_i32 s64, 0xef
	s_movk_i32 s65, 0xff
	s_mov_b32 s67, 0
	s_barrier
	s_waitcnt vmcnt(0)
	s_branch .LBB0_795

.LBB0_797:
	s_cmp_lg_u32 s67, 0
	s_mov_b32 s22, 0
	s_cbranch_scc0 .LBB0_799
	ds_read_b128 v[2:5], v155
	ds_read_b128 v[6:9], v155 offset:1024
	ds_read_b128 v[10:13], v155 offset:2048
	ds_read_b128 v[14:17], v155 offset:3072
	ds_read_b128 v[18:21], v156
	ds_read_b128 v[22:25], v156 offset:1024
	ds_read_b128 v[26:29], v156 offset:2048
	ds_read_b128 v[30:33], v156 offset:3072
	s_add_u32 s0, s56, 0x10000
	s_addc_u32 s1, s57, 0
	ds_read_b128 v[34:37], v157
	ds_read_b128 v[38:41], v157 offset:1024
	ds_read_b128 v[42:45], v157 offset:2048
	ds_read_b128 v[46:49], v157 offset:3072
	ds_read_b128 v[50:53], v157 offset:4096
	ds_read_b128 v[54:57], v157 offset:5120
	ds_read_b128 v[58:61], v157 offset:6144
	ds_read_b128 v[62:65], v157 offset:7168
	s_waitcnt vmcnt(16) lgkmcnt(0)
	s_barrier
	v_mfma_f32_16x16x32_bf16 v[86:89], v[10:13], v[50:53], 0
	v_mfma_f32_16x16x32_bf16 v[92:95], v[14:17], v[54:57], v[86:89]
	v_mfma_f32_16x16x32_bf16 v[86:89], v[2:5], v[58:61], 0
	v_mfma_f32_16x16x32_bf16 v[66:69], v[2:5], v[34:37], 0
	v_mfma_f32_16x16x32_bf16 v[70:73], v[10:13], v[34:37], 0
	v_mfma_f32_16x16x32_bf16 v[74:77], v[2:5], v[42:45], 0
	v_mfma_f32_16x16x32_bf16 v[78:81], v[10:13], v[42:45], 0
	v_mfma_f32_16x16x32_bf16 v[82:85], v[2:5], v[50:53], 0
	v_mfma_f32_16x16x32_bf16 v[96:99], v[6:9], v[62:65], v[86:89]
	v_mfma_f32_16x16x32_bf16 v[86:89], v[10:13], v[58:61], 0
	v_mfma_f32_16x16x32_bf16 v[66:69], v[6:9], v[38:41], v[66:69]
	v_mfma_f32_16x16x32_bf16 v[70:73], v[14:17], v[38:41], v[70:73]
	v_mfma_f32_16x16x32_bf16 v[74:77], v[6:9], v[46:49], v[74:77]
	v_mfma_f32_16x16x32_bf16 v[78:81], v[14:17], v[46:49], v[78:81]
	v_mfma_f32_16x16x32_bf16 v[82:85], v[6:9], v[54:57], v[82:85]
	v_mfma_f32_16x16x32_bf16 v[108:111], v[14:17], v[62:65], v[86:89]
	v_mfma_f32_16x16x32_bf16 v[86:89], v[18:21], v[34:37], 0
	v_mfma_f32_16x16x32_bf16 v[34:37], v[26:29], v[34:37], 0
	v_mfma_f32_16x16x32_bf16 v[112:115], v[22:25], v[38:41], v[86:89]
	v_mfma_f32_16x16x32_bf16 v[34:37], v[30:33], v[38:41], v[34:37]
	v_mfma_f32_16x16x32_bf16 v[38:41], v[18:21], v[42:45], 0
	v_mfma_f32_16x16x32_bf16 v[42:45], v[26:29], v[42:45], 0
	v_mfma_f32_16x16x32_bf16 v[38:41], v[22:25], v[46:49], v[38:41]
	v_mfma_f32_16x16x32_bf16 v[42:45], v[30:33], v[46:49], v[42:45]
	v_mfma_f32_16x16x32_bf16 v[46:49], v[18:21], v[50:53], 0
	v_mfma_f32_16x16x32_bf16 v[50:53], v[26:29], v[50:53], 0
	v_mfma_f32_16x16x32_bf16 v[46:49], v[22:25], v[54:57], v[46:49]
	v_mfma_f32_16x16x32_bf16 v[50:53], v[30:33], v[54:57], v[50:53]
	v_mfma_f32_16x16x32_bf16 v[54:57], v[18:21], v[58:61], 0
	v_mfma_f32_16x16x32_bf16 v[58:61], v[26:29], v[58:61], 0
	v_mfma_f32_16x16x32_bf16 v[54:57], v[22:25], v[62:65], v[54:57]
	v_mfma_f32_16x16x32_bf16 v[58:61], v[30:33], v[62:65], v[58:61]
	s_barrier
	s_add_i32 s12, s60, s2
	s_mov_b32 m0, s12
	ds_read_b128 v[62:65], v157 offset:16384
	ds_read_b128 v[86:89], v157 offset:17408
	ds_read_b128 v[100:103], v157 offset:18432
	ds_read_b128 v[104:107], v157 offset:19456
	ds_read_b128 v[116:119], v157 offset:20480
	ds_read_b128 v[120:123], v157 offset:21504
	ds_read_b128 v[124:127], v157 offset:22528
	ds_read_b128 v[128:131], v157 offset:23552
	global_load_lds_dwordx4 v134, s[0:1]
	s_add_i32 m0, s12, 0x2000
	v_lshl_add_u64 v[90:91], s[0:1], 0, v[138:139]
	s_add_u32 s0, s56, 0x14000
	s_addc_u32 s1, s57, 0
	s_add_i32 s12, s61, s2
	global_load_lds_dwordx4 v[90:91], off
	s_mov_b32 m0, s12
	v_lshl_add_u64 v[148:149], s[8:9], 0, v[132:133]
	global_load_lds_dwordx4 v134, s[0:1]
	s_add_i32 m0, s12, 0x2000
	v_lshl_add_u64 v[144:145], s[8:9], 0, v[136:137]
	global_load_lds_dwordx4 v138, s[0:1]
	s_mov_b32 m0, s33
	v_lshl_add_u64 v[90:91], v[148:149], 0, s[40:41]
	global_load_lds_dwordx4 v[90:91], off
	s_mov_b32 m0, s53
	v_lshl_add_u64 v[90:91], v[144:145], 0, s[40:41]
	global_load_lds_dwordx4 v[90:91], off
	s_waitcnt vmcnt(16) lgkmcnt(0)
	s_barrier
	v_mfma_f32_16x16x32_bf16 v[158:161], v[2:5], v[62:65], 0
	v_mfma_f32_16x16x32_bf16 v[166:169], v[2:5], v[100:103], 0
	v_mfma_f32_16x16x32_bf16 v[174:177], v[2:5], v[116:119], 0
	v_mfma_f32_16x16x32_bf16 v[2:5], v[2:5], v[124:127], 0
	v_mfma_f32_16x16x32_bf16 v[158:161], v[6:9], v[86:89], v[158:161]
	v_mfma_f32_16x16x32_bf16 v[162:165], v[10:13], v[62:65], 0
	v_mfma_f32_16x16x32_bf16 v[166:169], v[6:9], v[104:107], v[166:169]
	v_mfma_f32_16x16x32_bf16 v[170:173], v[10:13], v[100:103], 0
	v_mfma_f32_16x16x32_bf16 v[174:177], v[6:9], v[120:123], v[174:177]
	v_mfma_f32_16x16x32_bf16 v[178:181], v[10:13], v[116:119], 0
	v_mfma_f32_16x16x32_bf16 v[2:5], v[6:9], v[128:131], v[2:5]
	v_mfma_f32_16x16x32_bf16 v[6:9], v[10:13], v[124:127], 0
	v_mfma_f32_16x16x32_bf16 v[162:165], v[14:17], v[86:89], v[162:165]
	v_mfma_f32_16x16x32_bf16 v[170:173], v[14:17], v[104:107], v[170:173]
	v_mfma_f32_16x16x32_bf16 v[178:181], v[14:17], v[120:123], v[178:181]
	v_mfma_f32_16x16x32_bf16 v[12:15], v[14:17], v[128:131], v[6:9]
	v_mfma_f32_16x16x32_bf16 v[6:9], v[18:21], v[62:65], 0
	v_mfma_f32_16x16x32_bf16 v[182:185], v[22:25], v[86:89], v[6:9]
	v_mfma_f32_16x16x32_bf16 v[6:9], v[26:29], v[62:65], 0
	v_mfma_f32_16x16x32_bf16 v[186:189], v[30:33], v[86:89], v[6:9]
	v_mfma_f32_16x16x32_bf16 v[6:9], v[18:21], v[100:103], 0
	v_mfma_f32_16x16x32_bf16 v[190:193], v[22:25], v[104:107], v[6:9]
	v_mfma_f32_16x16x32_bf16 v[6:9], v[26:29], v[100:103], 0
	v_mfma_f32_16x16x32_bf16 v[194:197], v[30:33], v[104:107], v[6:9]
	v_mfma_f32_16x16x32_bf16 v[6:9], v[18:21], v[116:119], 0
	v_mfma_f32_16x16x32_bf16 v[198:201], v[22:25], v[120:123], v[6:9]
	v_mfma_f32_16x16x32_bf16 v[6:9], v[26:29], v[116:119], 0
	v_mfma_f32_16x16x32_bf16 v[202:205], v[30:33], v[120:123], v[6:9]
	v_mfma_f32_16x16x32_bf16 v[6:9], v[18:21], v[124:127], 0
	v_mfma_f32_16x16x32_bf16 v[16:19], v[22:25], v[128:131], v[6:9]
	v_mfma_f32_16x16x32_bf16 v[6:9], v[26:29], v[124:127], 0
	v_mfma_f32_16x16x32_bf16 v[206:209], v[30:33], v[128:131], v[6:9]
	s_barrier
	s_add_i32 s12, 0, 0x18000
	v_add_u32_e32 v1, s12, v152
	s_add_i32 s13, 0, 0x1c000
	s_nop 1
	ds_read_b128 v[6:9], v1
	ds_read_b128 v[28:31], v1 offset:1024
	ds_read_b128 v[62:65], v1 offset:2048
	ds_read_b128 v[210:213], v1 offset:3072
	v_add_u32_e32 v1, s13, v152
	ds_read_b128 v[214:217], v1
	ds_read_b128 v[218:221], v1 offset:1024
	ds_read_b128 v[222:225], v1 offset:2048
	ds_read_b128 v[226:229], v1 offset:3072
	s_add_u32 s0, s8, 0x100100
	s_addc_u32 s1, s9, 0
	s_mov_b32 m0, s55
	ds_read_b128 v[20:23], v157 offset:32768
	ds_read_b128 v[24:27], v157 offset:33792
	ds_read_b128 v[230:233], v157 offset:34816
	ds_read_b128 v[234:237], v157 offset:35840
	ds_read_b128 v[238:241], v157 offset:36864
	ds_read_b128 v[242:245], v157 offset:37888
	ds_read_b128 v[246:249], v157 offset:38912
	ds_read_b128 v[250:253], v157 offset:39936
	global_load_lds_dwordx4 v132, s[0:1]
	s_mov_b32 m0, s58
	s_nop 0
	global_load_lds_dwordx4 v136, s[0:1]
	s_waitcnt vmcnt(16) lgkmcnt(0)
	s_barrier
	v_mfma_f32_16x16x32_bf16 v[66:69], v[6:9], v[20:23], v[66:69]
	v_mfma_f32_16x16x32_bf16 v[120:123], v[28:31], v[24:27], v[66:69]
	v_mfma_f32_16x16x32_bf16 v[66:69], v[62:65], v[20:23], v[70:73]
	v_mfma_f32_16x16x32_bf16 v[116:119], v[210:213], v[24:27], v[66:69]
	v_mfma_f32_16x16x32_bf16 v[66:69], v[6:9], v[230:233], v[74:77]
	v_mfma_f32_16x16x32_bf16 v[104:107], v[28:31], v[234:237], v[66:69]
	v_mfma_f32_16x16x32_bf16 v[66:69], v[62:65], v[230:233], v[78:81]
	v_mfma_f32_16x16x32_bf16 v[100:103], v[210:213], v[234:237], v[66:69]
	v_mfma_f32_16x16x32_bf16 v[66:69], v[6:9], v[238:241], v[82:85]
	v_mfma_f32_16x16x32_bf16 v[88:91], v[28:31], v[242:245], v[66:69]
	v_mfma_f32_16x16x32_bf16 v[66:69], v[62:65], v[238:241], v[92:95]
	v_mfma_f32_16x16x32_bf16 v[84:87], v[210:213], v[242:245], v[66:69]
	v_mfma_f32_16x16x32_bf16 v[66:69], v[6:9], v[246:249], v[96:99]
	v_mfma_f32_16x16x32_bf16 v[72:75], v[28:31], v[250:253], v[66:69]
	v_mfma_f32_16x16x32_bf16 v[66:69], v[62:65], v[246:249], v[108:111]
	v_mfma_f32_16x16x32_bf16 v[68:71], v[210:213], v[250:253], v[66:69]
	v_mfma_f32_16x16x32_bf16 v[76:79], v[214:217], v[20:23], v[112:115]
	v_mfma_f32_16x16x32_bf16 v[20:23], v[222:225], v[20:23], v[34:37]
	v_mfma_f32_16x16x32_bf16 v[124:127], v[226:229], v[24:27], v[20:23]
	v_mfma_f32_16x16x32_bf16 v[20:23], v[214:217], v[230:233], v[38:41]
	v_mfma_f32_16x16x32_bf16 v[112:115], v[218:221], v[234:237], v[20:23]
	v_mfma_f32_16x16x32_bf16 v[20:23], v[222:225], v[230:233], v[42:45]
	v_mfma_f32_16x16x32_bf16 v[108:111], v[226:229], v[234:237], v[20:23]
	v_mfma_f32_16x16x32_bf16 v[20:23], v[214:217], v[238:241], v[46:49]
	v_mfma_f32_16x16x32_bf16 v[96:99], v[218:221], v[242:245], v[20:23]
	v_mfma_f32_16x16x32_bf16 v[20:23], v[222:225], v[238:241], v[50:53]
	v_mfma_f32_16x16x32_bf16 v[92:95], v[226:229], v[242:245], v[20:23]
	v_mfma_f32_16x16x32_bf16 v[20:23], v[214:217], v[246:249], v[54:57]
	v_mfma_f32_16x16x32_bf16 v[80:83], v[218:221], v[250:253], v[20:23]
	v_mfma_f32_16x16x32_bf16 v[20:23], v[222:225], v[246:249], v[58:61]
	v_mfma_f32_16x16x32_bf16 v[128:131], v[218:221], v[24:27], v[76:79]
	v_mfma_f32_16x16x32_bf16 v[76:79], v[226:229], v[250:253], v[20:23]
	s_barrier
	s_add_u32 s0, s56, 0x18000
	s_addc_u32 s1, s57, 0
	s_add_i32 s12, s12, s2
	s_mov_b32 m0, s12
	ds_read_b128 v[32:35], v157 offset:49152
	ds_read_b128 v[44:47], v157 offset:50176
	ds_read_b128 v[230:233], v157 offset:51200
	ds_read_b128 v[234:237], v157 offset:52224
	ds_read_b128 v[238:241], v157 offset:53248
	ds_read_b128 v[242:245], v157 offset:54272
	ds_read_b128 v[246:249], v157 offset:55296
	ds_read_b128 v[250:253], v157 offset:56320
	global_load_lds_dwordx4 v134, s[0:1]
	s_add_i32 m0, s12, 0x2000
	v_lshl_add_u64 v[10:11], s[0:1], 0, v[138:139]
	s_add_u32 s0, s56, 0x1c000
	s_addc_u32 s1, s57, 0
	s_add_i32 s12, s13, s2
	global_load_lds_dwordx4 v[10:11], off
	s_mov_b32 m0, s12
	s_nop 0
	global_load_lds_dwordx4 v134, s[0:1]
	s_add_i32 m0, s12, 0x2000
	s_nop 0
	global_load_lds_dwordx4 v138, s[0:1]
	s_mov_b32 m0, s16
	v_lshl_add_u64 v[10:11], v[148:149], 0, s[42:43]
	global_load_lds_dwordx4 v[10:11], off
	s_mov_b32 m0, s59
	v_lshl_add_u64 v[10:11], v[144:145], 0, s[42:43]
	global_load_lds_dwordx4 v[10:11], off
	s_waitcnt vmcnt(8) lgkmcnt(0)
	s_barrier
	v_mfma_f32_16x16x32_bf16 v[20:23], v[6:9], v[32:35], v[158:161]
	v_mfma_f32_16x16x32_bf16 v[56:59], v[28:31], v[44:47], v[20:23]
	v_mfma_f32_16x16x32_bf16 v[20:23], v[62:65], v[32:35], v[162:165]
	v_mfma_f32_16x16x32_bf16 v[52:55], v[210:213], v[44:47], v[20:23]
	v_mfma_f32_16x16x32_bf16 v[20:23], v[6:9], v[230:233], v[166:169]
	v_mfma_f32_16x16x32_bf16 v[40:43], v[28:31], v[234:237], v[20:23]
	v_mfma_f32_16x16x32_bf16 v[20:23], v[62:65], v[230:233], v[170:173]
	v_mfma_f32_16x16x32_bf16 v[36:39], v[210:213], v[234:237], v[20:23]
	v_mfma_f32_16x16x32_bf16 v[20:23], v[6:9], v[238:241], v[174:177]
	v_mfma_f32_16x16x32_bf16 v[2:5], v[6:9], v[246:249], v[2:5]
	v_mfma_f32_16x16x32_bf16 v[24:27], v[28:31], v[242:245], v[20:23]
	v_mfma_f32_16x16x32_bf16 v[20:23], v[62:65], v[238:241], v[178:181]
	v_mfma_f32_16x16x32_bf16 v[8:11], v[28:31], v[250:253], v[2:5]
	v_mfma_f32_16x16x32_bf16 v[2:5], v[62:65], v[246:249], v[12:15]
	v_mfma_f32_16x16x32_bf16 v[20:23], v[210:213], v[242:245], v[20:23]
	v_mfma_f32_16x16x32_bf16 v[4:7], v[210:213], v[250:253], v[2:5]
	v_mfma_f32_16x16x32_bf16 v[12:15], v[214:217], v[32:35], v[182:185]
	v_mfma_f32_16x16x32_bf16 v[64:67], v[218:221], v[44:47], v[12:15]
	v_mfma_f32_16x16x32_bf16 v[12:15], v[222:225], v[32:35], v[186:189]
	v_mfma_f32_16x16x32_bf16 v[60:63], v[226:229], v[44:47], v[12:15]
	v_mfma_f32_16x16x32_bf16 v[12:15], v[214:217], v[230:233], v[190:193]
	v_mfma_f32_16x16x32_bf16 v[48:51], v[218:221], v[234:237], v[12:15]
	v_mfma_f32_16x16x32_bf16 v[12:15], v[222:225], v[230:233], v[194:197]
	v_mfma_f32_16x16x32_bf16 v[44:47], v[226:229], v[234:237], v[12:15]
	v_mfma_f32_16x16x32_bf16 v[12:15], v[214:217], v[238:241], v[198:201]
	v_mfma_f32_16x16x32_bf16 v[32:35], v[218:221], v[242:245], v[12:15]
	v_mfma_f32_16x16x32_bf16 v[12:15], v[222:225], v[238:241], v[202:205]
	v_mfma_f32_16x16x32_bf16 v[28:31], v[226:229], v[242:245], v[12:15]
	v_mfma_f32_16x16x32_bf16 v[12:15], v[214:217], v[246:249], v[16:19]
	v_mfma_f32_16x16x32_bf16 v[16:19], v[218:221], v[250:253], v[12:15]
	v_mfma_f32_16x16x32_bf16 v[12:15], v[222:225], v[246:249], v[206:209]
	v_mfma_f32_16x16x32_bf16 v[12:15], v[226:229], v[250:253], v[12:15]
	s_barrier
	s_mov_b32 s22, 2
	s_branch .LBB0_800

.LBB0_801:
	ds_read_b128 v[158:161], v155
	ds_read_b128 v[162:165], v155 offset:1024
	ds_read_b128 v[166:169], v155 offset:2048
	ds_read_b128 v[170:173], v155 offset:3072
	ds_read_b128 v[174:177], v156
	ds_read_b128 v[178:181], v156 offset:1024
	ds_read_b128 v[182:185], v156 offset:2048
	ds_read_b128 v[186:189], v156 offset:3072
	s_add_u32 s12, s72, s36
	s_addc_u32 s13, s73, 0
	s_cmp_eq_u32 s36, s8
	s_cselect_b32 s23, s0, s13
	s_cselect_b32 s22, s1, s12
	s_cselect_b32 s57, s45, s71
	s_cselect_b32 s56, s68, s70
	s_add_i32 s75, s33, 0xc000
	v_lshl_add_u64 v[144:145], v[2:3], 0, s[36:37]
	s_mov_b32 m0, s75
	s_add_i32 s74, s33, 0xe000
	ds_read_b128 v[190:193], v157
	ds_read_b128 v[194:197], v157 offset:1024
	ds_read_b128 v[198:201], v157 offset:2048
	ds_read_b128 v[202:205], v157 offset:3072
	ds_read_b128 v[206:209], v157 offset:4096
	ds_read_b128 v[210:213], v157 offset:5120
	ds_read_b128 v[214:217], v157 offset:6144
	ds_read_b128 v[218:221], v157 offset:7168
	global_load_lds_dwordx4 v[144:145], off
	s_mov_b32 m0, s74
	v_lshl_add_u64 v[144:145], v[148:149], 0, s[36:37]
	global_load_lds_dwordx4 v[144:145], off
	s_waitcnt vmcnt(8) lgkmcnt(0)
	s_barrier
	v_mfma_f32_16x16x32_bf16 v[120:123], v[158:161], v[190:193], v[120:123]
	v_mfma_f32_16x16x32_bf16 v[120:123], v[162:165], v[194:197], v[120:123]
	v_mfma_f32_16x16x32_bf16 v[116:119], v[166:169], v[190:193], v[116:119]
	v_mfma_f32_16x16x32_bf16 v[116:119], v[170:173], v[194:197], v[116:119]
	v_mfma_f32_16x16x32_bf16 v[100:103], v[166:169], v[198:201], v[100:103]
	v_mfma_f32_16x16x32_bf16 v[100:103], v[170:173], v[202:205], v[100:103]
	v_mfma_f32_16x16x32_bf16 v[104:107], v[158:161], v[198:201], v[104:107]
	v_mfma_f32_16x16x32_bf16 v[104:107], v[162:165], v[202:205], v[104:107]
	v_mfma_f32_16x16x32_bf16 v[88:91], v[158:161], v[206:209], v[88:91]
	v_mfma_f32_16x16x32_bf16 v[88:91], v[162:165], v[210:213], v[88:91]
	v_mfma_f32_16x16x32_bf16 v[84:87], v[166:169], v[206:209], v[84:87]
	v_mfma_f32_16x16x32_bf16 v[84:87], v[170:173], v[210:213], v[84:87]
	v_mfma_f32_16x16x32_bf16 v[68:71], v[166:169], v[214:217], v[68:71]
	v_mfma_f32_16x16x32_bf16 v[68:71], v[170:173], v[218:221], v[68:71]
	v_mfma_f32_16x16x32_bf16 v[72:75], v[158:161], v[214:217], v[72:75]
	v_mfma_f32_16x16x32_bf16 v[72:75], v[162:165], v[218:221], v[72:75]
	v_mfma_f32_16x16x32_bf16 v[80:83], v[174:177], v[214:217], v[80:83]
	v_mfma_f32_16x16x32_bf16 v[80:83], v[178:181], v[218:221], v[80:83]
	v_mfma_f32_16x16x32_bf16 v[76:79], v[182:185], v[214:217], v[76:79]
	v_mfma_f32_16x16x32_bf16 v[76:79], v[186:189], v[218:221], v[76:79]
	v_mfma_f32_16x16x32_bf16 v[92:95], v[182:185], v[206:209], v[92:95]
	v_mfma_f32_16x16x32_bf16 v[92:95], v[186:189], v[210:213], v[92:95]
	v_mfma_f32_16x16x32_bf16 v[96:99], v[174:177], v[206:209], v[96:99]
	v_mfma_f32_16x16x32_bf16 v[96:99], v[178:181], v[210:213], v[96:99]
	v_mfma_f32_16x16x32_bf16 v[112:115], v[174:177], v[198:201], v[112:115]
	v_mfma_f32_16x16x32_bf16 v[112:115], v[178:181], v[202:205], v[112:115]
	v_mfma_f32_16x16x32_bf16 v[108:111], v[182:185], v[198:201], v[108:111]
	v_mfma_f32_16x16x32_bf16 v[108:111], v[186:189], v[202:205], v[108:111]
	v_mfma_f32_16x16x32_bf16 v[124:127], v[182:185], v[190:193], v[124:127]
	v_mfma_f32_16x16x32_bf16 v[124:127], v[186:189], v[194:197], v[124:127]
	v_mfma_f32_16x16x32_bf16 v[128:131], v[174:177], v[190:193], v[128:131]
	v_mfma_f32_16x16x32_bf16 v[128:131], v[178:181], v[194:197], v[128:131]
	s_barrier
	s_add_i32 s12, s60, s2
	s_mov_b32 m0, s12
	ds_read_b128 v[190:193], v157 offset:16384
	ds_read_b128 v[194:197], v157 offset:17408
	ds_read_b128 v[198:201], v157 offset:18432
	ds_read_b128 v[202:205], v157 offset:19456
	ds_read_b128 v[206:209], v157 offset:20480
	ds_read_b128 v[210:213], v157 offset:21504
	ds_read_b128 v[214:217], v157 offset:22528
	ds_read_b128 v[218:221], v157 offset:23552
	global_load_lds_dwordx4 v134, s[56:57]
	s_add_i32 m0, s12, 0x2000
	s_add_u32 s12, s56, 0x4000
	s_addc_u32 s13, s57, 0
	s_add_i32 s14, s61, s2
	global_load_lds_dwordx4 v138, s[56:57]
	s_mov_b32 m0, s14
	v_lshl_add_u64 v[222:223], s[22:23], 0, v[136:137]
	global_load_lds_dwordx4 v134, s[12:13]
	s_add_i32 m0, s14, 0x2000
	s_nop 0
	global_load_lds_dwordx4 v138, s[12:13]
	s_mov_b32 m0, s33
	v_lshl_add_u64 v[144:145], s[22:23], 0, v[132:133]
	global_load_lds_dwordx4 v[144:145], off
	s_mov_b32 m0, s53
	s_nop 0
	global_load_lds_dwordx4 v[222:223], off
	s_waitcnt vmcnt(8) lgkmcnt(0)
	s_barrier
	v_mfma_f32_16x16x32_bf16 v[56:59], v[158:161], v[190:193], v[56:59]
	v_mfma_f32_16x16x32_bf16 v[56:59], v[162:165], v[194:197], v[56:59]
	v_mfma_f32_16x16x32_bf16 v[52:55], v[166:169], v[190:193], v[52:55]
	v_mfma_f32_16x16x32_bf16 v[52:55], v[170:173], v[194:197], v[52:55]
	v_mfma_f32_16x16x32_bf16 v[36:39], v[166:169], v[198:201], v[36:39]
	v_mfma_f32_16x16x32_bf16 v[36:39], v[170:173], v[202:205], v[36:39]
	v_mfma_f32_16x16x32_bf16 v[40:43], v[158:161], v[198:201], v[40:43]
	v_mfma_f32_16x16x32_bf16 v[40:43], v[162:165], v[202:205], v[40:43]
	v_mfma_f32_16x16x32_bf16 v[24:27], v[158:161], v[206:209], v[24:27]
	v_mfma_f32_16x16x32_bf16 v[24:27], v[162:165], v[210:213], v[24:27]
	v_mfma_f32_16x16x32_bf16 v[20:23], v[166:169], v[206:209], v[20:23]
	v_mfma_f32_16x16x32_bf16 v[20:23], v[170:173], v[210:213], v[20:23]
	v_mfma_f32_16x16x32_bf16 v[4:7], v[166:169], v[214:217], v[4:7]
	v_mfma_f32_16x16x32_bf16 v[4:7], v[170:173], v[218:221], v[4:7]
	v_mfma_f32_16x16x32_bf16 v[8:11], v[158:161], v[214:217], v[8:11]
	v_mfma_f32_16x16x32_bf16 v[8:11], v[162:165], v[218:221], v[8:11]
	v_mfma_f32_16x16x32_bf16 v[16:19], v[174:177], v[214:217], v[16:19]
	v_mfma_f32_16x16x32_bf16 v[16:19], v[178:181], v[218:221], v[16:19]
	v_mfma_f32_16x16x32_bf16 v[12:15], v[182:185], v[214:217], v[12:15]
	v_mfma_f32_16x16x32_bf16 v[12:15], v[186:189], v[218:221], v[12:15]
	v_mfma_f32_16x16x32_bf16 v[28:31], v[182:185], v[206:209], v[28:31]
	v_mfma_f32_16x16x32_bf16 v[28:31], v[186:189], v[210:213], v[28:31]
	v_mfma_f32_16x16x32_bf16 v[32:35], v[174:177], v[206:209], v[32:35]
	v_mfma_f32_16x16x32_bf16 v[32:35], v[178:181], v[210:213], v[32:35]
	v_mfma_f32_16x16x32_bf16 v[48:51], v[174:177], v[198:201], v[48:51]
	v_mfma_f32_16x16x32_bf16 v[48:51], v[178:181], v[202:205], v[48:51]
	v_mfma_f32_16x16x32_bf16 v[44:47], v[182:185], v[198:201], v[44:47]
	v_mfma_f32_16x16x32_bf16 v[44:47], v[186:189], v[202:205], v[44:47]
	v_mfma_f32_16x16x32_bf16 v[60:63], v[182:185], v[190:193], v[60:63]
	v_mfma_f32_16x16x32_bf16 v[60:63], v[186:189], v[194:197], v[60:63]
	v_mfma_f32_16x16x32_bf16 v[64:67], v[174:177], v[190:193], v[64:67]
	v_mfma_f32_16x16x32_bf16 v[64:67], v[178:181], v[194:197], v[64:67]
	s_barrier
	s_add_i32 s14, 0, 0x18000
	v_add_u32_e32 v1, s14, v152
	s_add_i32 s76, 0, 0x1c000
	ds_read_b128 v[158:161], v1
	ds_read_b128 v[162:165], v1 offset:1024
	ds_read_b128 v[166:169], v1 offset:2048
	ds_read_b128 v[170:173], v1 offset:3072
	v_add_u32_e32 v1, s76, v152
	ds_read_b128 v[174:177], v1
	ds_read_b128 v[178:181], v1 offset:1024
	ds_read_b128 v[182:185], v1 offset:2048
	ds_read_b128 v[186:189], v1 offset:3072
	s_add_u32 s12, s22, 0x100000
	s_addc_u32 s13, s23, 0
	s_mov_b32 m0, s55
	ds_read_b128 v[190:193], v157 offset:32768
	ds_read_b128 v[194:197], v157 offset:33792
	ds_read_b128 v[198:201], v157 offset:34816
	ds_read_b128 v[202:205], v157 offset:35840
	ds_read_b128 v[206:209], v157 offset:36864
	ds_read_b128 v[210:213], v157 offset:37888
	ds_read_b128 v[214:217], v157 offset:38912
	ds_read_b128 v[218:221], v157 offset:39936
	global_load_lds_dwordx4 v132, s[12:13]
	s_mov_b32 m0, s58
	s_nop 0
	global_load_lds_dwordx4 v136, s[12:13]
	s_waitcnt vmcnt(8) lgkmcnt(0)
	s_barrier
	v_mfma_f32_16x16x32_bf16 v[120:123], v[158:161], v[190:193], v[120:123]
	v_mfma_f32_16x16x32_bf16 v[120:123], v[162:165], v[194:197], v[120:123]
	v_mfma_f32_16x16x32_bf16 v[116:119], v[166:169], v[190:193], v[116:119]
	v_mfma_f32_16x16x32_bf16 v[116:119], v[170:173], v[194:197], v[116:119]
	v_mfma_f32_16x16x32_bf16 v[100:103], v[166:169], v[198:201], v[100:103]
	v_mfma_f32_16x16x32_bf16 v[100:103], v[170:173], v[202:205], v[100:103]
	v_mfma_f32_16x16x32_bf16 v[104:107], v[158:161], v[198:201], v[104:107]
	v_mfma_f32_16x16x32_bf16 v[104:107], v[162:165], v[202:205], v[104:107]
	v_mfma_f32_16x16x32_bf16 v[88:91], v[158:161], v[206:209], v[88:91]
	v_mfma_f32_16x16x32_bf16 v[88:91], v[162:165], v[210:213], v[88:91]
	v_mfma_f32_16x16x32_bf16 v[84:87], v[166:169], v[206:209], v[84:87]
	v_mfma_f32_16x16x32_bf16 v[84:87], v[170:173], v[210:213], v[84:87]
	v_mfma_f32_16x16x32_bf16 v[68:71], v[166:169], v[214:217], v[68:71]
	v_mfma_f32_16x16x32_bf16 v[68:71], v[170:173], v[218:221], v[68:71]
	v_mfma_f32_16x16x32_bf16 v[72:75], v[158:161], v[214:217], v[72:75]
	v_mfma_f32_16x16x32_bf16 v[72:75], v[162:165], v[218:221], v[72:75]
	v_mfma_f32_16x16x32_bf16 v[80:83], v[174:177], v[214:217], v[80:83]
	v_mfma_f32_16x16x32_bf16 v[80:83], v[178:181], v[218:221], v[80:83]
	v_mfma_f32_16x16x32_bf16 v[76:79], v[182:185], v[214:217], v[76:79]
	v_mfma_f32_16x16x32_bf16 v[76:79], v[186:189], v[218:221], v[76:79]
	v_mfma_f32_16x16x32_bf16 v[92:95], v[182:185], v[206:209], v[92:95]
	v_mfma_f32_16x16x32_bf16 v[92:95], v[186:189], v[210:213], v[92:95]
	v_mfma_f32_16x16x32_bf16 v[96:99], v[174:177], v[206:209], v[96:99]
	v_mfma_f32_16x16x32_bf16 v[96:99], v[178:181], v[210:213], v[96:99]
	v_mfma_f32_16x16x32_bf16 v[112:115], v[174:177], v[198:201], v[112:115]
	v_mfma_f32_16x16x32_bf16 v[112:115], v[178:181], v[202:205], v[112:115]
	v_mfma_f32_16x16x32_bf16 v[108:111], v[182:185], v[198:201], v[108:111]
	v_mfma_f32_16x16x32_bf16 v[108:111], v[186:189], v[202:205], v[108:111]
	v_mfma_f32_16x16x32_bf16 v[124:127], v[182:185], v[190:193], v[124:127]
	v_mfma_f32_16x16x32_bf16 v[124:127], v[186:189], v[194:197], v[124:127]
	v_mfma_f32_16x16x32_bf16 v[128:131], v[174:177], v[190:193], v[128:131]
	v_mfma_f32_16x16x32_bf16 v[128:131], v[178:181], v[194:197], v[128:131]
	s_barrier
	s_add_u32 s12, s56, 0x8000
	s_addc_u32 s13, s57, 0
	s_add_i32 s14, s14, s2
	s_mov_b32 m0, s14
	ds_read_b128 v[190:193], v157 offset:49152
	ds_read_b128 v[194:197], v157 offset:50176
	ds_read_b128 v[198:201], v157 offset:51200
	ds_read_b128 v[202:205], v157 offset:52224
	ds_read_b128 v[206:209], v157 offset:53248
	ds_read_b128 v[210:213], v157 offset:54272
	ds_read_b128 v[214:217], v157 offset:55296
	ds_read_b128 v[218:221], v157 offset:56320
	global_load_lds_dwordx4 v134, s[12:13]
	s_add_i32 m0, s14, 0x2000
	v_lshl_add_u64 v[224:225], s[12:13], 0, v[138:139]
	s_add_u32 s12, s56, 0xc000
	s_addc_u32 s13, s57, 0
	s_add_i32 s14, s76, s2
	global_load_lds_dwordx4 v[224:225], off
	s_mov_b32 m0, s14
	v_lshl_add_u64 v[144:145], v[144:145], 0, s[34:35]
	global_load_lds_dwordx4 v134, s[12:13]
	s_add_i32 m0, s14, 0x2000
	s_nop 0
	global_load_lds_dwordx4 v138, s[12:13]
	s_mov_b32 m0, s16
	s_nop 0
	global_load_lds_dwordx4 v[144:145], off
	s_mov_b32 m0, s59
	v_lshl_add_u64 v[144:145], v[222:223], 0, s[34:35]
	global_load_lds_dwordx4 v[144:145], off
	s_waitcnt vmcnt(8) lgkmcnt(0)
	s_barrier
	v_mfma_f32_16x16x32_bf16 v[56:59], v[158:161], v[190:193], v[56:59]
	v_mfma_f32_16x16x32_bf16 v[56:59], v[162:165], v[194:197], v[56:59]
	v_mfma_f32_16x16x32_bf16 v[52:55], v[166:169], v[190:193], v[52:55]
	v_mfma_f32_16x16x32_bf16 v[52:55], v[170:173], v[194:197], v[52:55]
	v_mfma_f32_16x16x32_bf16 v[36:39], v[166:169], v[198:201], v[36:39]
	v_mfma_f32_16x16x32_bf16 v[36:39], v[170:173], v[202:205], v[36:39]
	v_mfma_f32_16x16x32_bf16 v[40:43], v[158:161], v[198:201], v[40:43]
	v_mfma_f32_16x16x32_bf16 v[40:43], v[162:165], v[202:205], v[40:43]
	v_mfma_f32_16x16x32_bf16 v[24:27], v[158:161], v[206:209], v[24:27]
	v_mfma_f32_16x16x32_bf16 v[24:27], v[162:165], v[210:213], v[24:27]
	v_mfma_f32_16x16x32_bf16 v[20:23], v[166:169], v[206:209], v[20:23]
	v_mfma_f32_16x16x32_bf16 v[20:23], v[170:173], v[210:213], v[20:23]
	v_mfma_f32_16x16x32_bf16 v[4:7], v[166:169], v[214:217], v[4:7]
	v_mfma_f32_16x16x32_bf16 v[4:7], v[170:173], v[218:221], v[4:7]
	v_mfma_f32_16x16x32_bf16 v[8:11], v[158:161], v[214:217], v[8:11]
	v_mfma_f32_16x16x32_bf16 v[8:11], v[162:165], v[218:221], v[8:11]
	v_mfma_f32_16x16x32_bf16 v[16:19], v[174:177], v[214:217], v[16:19]
	v_mfma_f32_16x16x32_bf16 v[16:19], v[178:181], v[218:221], v[16:19]
	v_mfma_f32_16x16x32_bf16 v[12:15], v[182:185], v[214:217], v[12:15]
	v_mfma_f32_16x16x32_bf16 v[12:15], v[186:189], v[218:221], v[12:15]
	v_mfma_f32_16x16x32_bf16 v[28:31], v[182:185], v[206:209], v[28:31]
	v_mfma_f32_16x16x32_bf16 v[28:31], v[186:189], v[210:213], v[28:31]
	v_mfma_f32_16x16x32_bf16 v[32:35], v[174:177], v[206:209], v[32:35]
	v_mfma_f32_16x16x32_bf16 v[32:35], v[178:181], v[210:213], v[32:35]
	v_mfma_f32_16x16x32_bf16 v[48:51], v[174:177], v[198:201], v[48:51]
	v_mfma_f32_16x16x32_bf16 v[48:51], v[178:181], v[202:205], v[48:51]
	v_mfma_f32_16x16x32_bf16 v[44:47], v[182:185], v[198:201], v[44:47]
	v_mfma_f32_16x16x32_bf16 v[44:47], v[186:189], v[202:205], v[44:47]
	v_mfma_f32_16x16x32_bf16 v[60:63], v[182:185], v[190:193], v[60:63]
	v_mfma_f32_16x16x32_bf16 v[60:63], v[186:189], v[194:197], v[60:63]
	v_mfma_f32_16x16x32_bf16 v[64:67], v[174:177], v[190:193], v[64:67]
	v_mfma_f32_16x16x32_bf16 v[64:67], v[178:181], v[194:197], v[64:67]
	s_barrier
	s_add_i32 s69, s69, 2
	s_add_u32 s70, s70, 0x10000
	s_addc_u32 s71, s71, 0
	s_add_u32 s72, s72, 0x100
	s_addc_u32 s73, s73, 0
	s_add_u32 s8, s8, 0xffffff00
	s_addc_u32 s9, s9, -1
	v_lshl_add_u64 v[2:3], v[2:3], 0, s[40:41]
	s_cmp_gt_u32 s69, 61
	v_lshl_add_u64 v[148:149], v[148:149], 0, s[40:41]
	s_cbranch_scc0 .LBB0_801
	s_and_b64 vcc, exec, s[38:39]
	s_cbranch_vccnz .LBB0_809
	s_and_b64 s[0:1], s[10:11], s[6:7]
	s_andn2_b64 vcc, exec, s[0:1]
	s_cbranch_vccz .LBB0_810

.LBB0_805:
	s_add_u32 s0, s48, 0x100080
	s_addc_u32 s1, s49, 0
	s_mov_b32 m0, s75
	v_lshl_add_u64 v[2:3], s[0:1], 0, v[132:133]
	global_load_lds_dwordx4 v[2:3], off
	s_mov_b32 m0, s74
	s_nop 0
	global_load_lds_dwordx4 v136, s[0:1]

.LBB0_879:
	s_add_u32 s30, s78, 0x43400000
	s_addc_u32 s31, s79, 0
	s_add_u32 s34, s78, 0x900000
	s_addc_u32 s35, s79, 0
	s_bfe_u32 s24, s88, 0x20006
	s_add_u32 s4, s46, 0x8000
	s_addc_u32 s5, s47, 0
	s_add_i32 m0, s18, 0x18000
	s_waitcnt vmcnt(0)
	s_waitcnt vmcnt(2)
	s_barrier
	global_load_lds_dwordx4 v134, s[4:5]
	s_add_i32 m0, s18, 0x1a000
	s_mov_b64 s[36:37], 0x80
	s_add_i32 s25, s18, 0x8000
	s_add_i32 s33, s18, 0xa000
	global_load_lds_dwordx4 v138, s[4:5]
	v_lshl_add_u64 v[2:3], v[2:3], 0, s[36:37]
	s_mov_b32 m0, s25
	s_add_u32 s4, s46, 0xc000
	global_load_lds_dwordx4 v[2:3], off
	v_lshl_add_u64 v[2:3], v[4:5], 0, s[36:37]
	s_mov_b32 m0, s33
	s_addc_u32 s5, s47, 0
	global_load_lds_dwordx4 v[2:3], off
	s_add_i32 m0, s18, 0x1c000
	s_nop 0
	global_load_lds_dwordx4 v134, s[4:5]
	v_lshl_add_u64 v[2:3], s[4:5], 0, v[138:139]
	s_add_i32 m0, s18, 0x1e000
	v_and_b32_e32 v4, 48, v1
	global_load_lds_dwordx4 v[2:3], off
	v_and_b32_e32 v2, 15, v1
	v_lshl_or_b32 v150, s0, 6, v2
	v_and_b32_e32 v5, 0xfffffc00, v10
	v_lshl_or_b32 v2, v2, 6, v4
	v_lshlrev_b32_e32 v4, 2, v1
	v_ashrrev_i32_e32 v3, 1, v1
	v_lshl_add_u32 v10, s0, 13, v5
	v_and_b32_e32 v4, 32, v4
	v_lshl_add_u32 v5, s24, 12, v5
	v_and_b32_e32 v3, -8, v3
	v_bitop3_b32 v10, v2, v10, v4 bitop3:0xde
	v_bitop3_b32 v151, v2, v5, v4 bitop3:0xde
	v_cmp_gt_u32_e64 s[4:5], 16, v1
	v_lshrrev_b32_e32 v1, 1, v6
	v_mul_lo_u32 v2, v8, s1
	s_mov_b32 s0, 0x2b000
	v_lshl_add_u32 v152, s24, 5, v3
	v_mad_u64_u32 v[2:3], s[6:7], v1, s0, v[2:3]
	v_or_b32_e32 v1, v2, v7
	v_add_lshl_u32 v2, v1, v9, 1
	v_mov_b32_e32 v3, v0
	s_mov_b64 s[6:7], 0x2b0080
	v_lshl_add_u64 v[140:141], v[2:3], 0, s[6:7]
	v_lshrrev_b32_e32 v1, 1, v11
	v_mul_lo_u32 v2, v12, s1
	v_mad_u64_u32 v[2:3], s[0:1], v1, s0, v[2:3]
	s_waitcnt vmcnt(6)
	s_cmpk_lt_u32 s88, 0x100
	v_or_b32_e32 v1, v2, v13
	s_cselect_b64 s[38:39], -1, 0
	v_add_lshl_u32 v2, v1, v14, 1
	v_mov_b32_e32 v3, v0
	s_add_i32 s52, 0, 0x10000
	s_add_i32 s53, 0, 0x14000
	v_mbcnt_lo_u32_b32 v1, -1, 0
	s_ashr_i32 s50, s77, 31
	s_ashr_i32 s51, s90, 31
	v_lshl_add_u64 v[142:143], v[2:3], 0, s[6:7]
	v_mov_b64_e32 v[146:147], 0x1ff
	v_add_u32_e32 v153, s52, v151
	v_add_u32_e32 v154, s53, v151
	v_add_u32_e32 v155, 0, v10
	s_mov_b64 s[40:41], 0x100
	s_mov_b64 s[42:43], 0x180
	v_mbcnt_hi_u32_b32 v156, -1, v1
	s_mov_b32 s22, 0
	s_barrier
	s_branch .LBB0_882

.LBB0_891:
	ds_read_b128 v[2:5], v153
	ds_read_b128 v[6:9], v153 offset:1024
	ds_read_b128 v[10:13], v153 offset:2048
	ds_read_b128 v[14:17], v153 offset:3072
	ds_read_b128 v[18:21], v154
	ds_read_b128 v[22:25], v154 offset:1024
	ds_read_b128 v[26:29], v154 offset:2048
	ds_read_b128 v[30:33], v154 offset:3072
	s_add_u32 s0, s46, 0x10000
	s_addc_u32 s1, s47, 0
	ds_read_b128 v[34:37], v155
	ds_read_b128 v[38:41], v155 offset:1024
	ds_read_b128 v[42:45], v155 offset:2048
	ds_read_b128 v[46:49], v155 offset:3072
	ds_read_b128 v[50:53], v155 offset:4096
	ds_read_b128 v[54:57], v155 offset:5120
	ds_read_b128 v[58:61], v155 offset:6144
	ds_read_b128 v[62:65], v155 offset:7168
	s_waitcnt vmcnt(24) lgkmcnt(0)
	s_barrier
	v_mfma_f32_16x16x32_bf16 v[66:69], v[2:5], v[34:37], 0
	v_mfma_f32_16x16x32_bf16 v[70:73], v[10:13], v[34:37], 0
	v_mfma_f32_16x16x32_bf16 v[74:77], v[2:5], v[42:45], 0
	v_mfma_f32_16x16x32_bf16 v[78:81], v[10:13], v[42:45], 0
	v_mfma_f32_16x16x32_bf16 v[82:85], v[2:5], v[50:53], 0
	v_mfma_f32_16x16x32_bf16 v[86:89], v[10:13], v[50:53], 0
	v_mfma_f32_16x16x32_bf16 v[90:93], v[2:5], v[58:61], 0
	v_mfma_f32_16x16x32_bf16 v[94:97], v[10:13], v[58:61], 0
	v_mfma_f32_16x16x32_bf16 v[66:69], v[6:9], v[38:41], v[66:69]
	v_mfma_f32_16x16x32_bf16 v[70:73], v[14:17], v[38:41], v[70:73]
	v_mfma_f32_16x16x32_bf16 v[74:77], v[6:9], v[46:49], v[74:77]
	v_mfma_f32_16x16x32_bf16 v[78:81], v[14:17], v[46:49], v[78:81]
	v_mfma_f32_16x16x32_bf16 v[82:85], v[6:9], v[54:57], v[82:85]
	v_mfma_f32_16x16x32_bf16 v[86:89], v[14:17], v[54:57], v[86:89]
	v_mfma_f32_16x16x32_bf16 v[90:93], v[6:9], v[62:65], v[90:93]
	v_mfma_f32_16x16x32_bf16 v[104:107], v[14:17], v[62:65], v[94:97]
	v_mfma_f32_16x16x32_bf16 v[94:97], v[18:21], v[34:37], 0
	v_mfma_f32_16x16x32_bf16 v[34:37], v[26:29], v[34:37], 0
	v_mfma_f32_16x16x32_bf16 v[108:111], v[22:25], v[38:41], v[94:97]
	v_mfma_f32_16x16x32_bf16 v[34:37], v[30:33], v[38:41], v[34:37]
	v_mfma_f32_16x16x32_bf16 v[38:41], v[18:21], v[42:45], 0
	v_mfma_f32_16x16x32_bf16 v[42:45], v[26:29], v[42:45], 0
	v_mfma_f32_16x16x32_bf16 v[38:41], v[22:25], v[46:49], v[38:41]
	v_mfma_f32_16x16x32_bf16 v[42:45], v[30:33], v[46:49], v[42:45]
	v_mfma_f32_16x16x32_bf16 v[46:49], v[18:21], v[50:53], 0
	v_mfma_f32_16x16x32_bf16 v[50:53], v[26:29], v[50:53], 0
	v_mfma_f32_16x16x32_bf16 v[46:49], v[22:25], v[54:57], v[46:49]
	v_mfma_f32_16x16x32_bf16 v[50:53], v[30:33], v[54:57], v[50:53]
	v_mfma_f32_16x16x32_bf16 v[54:57], v[18:21], v[58:61], 0
	v_mfma_f32_16x16x32_bf16 v[58:61], v[26:29], v[58:61], 0
	v_mfma_f32_16x16x32_bf16 v[54:57], v[22:25], v[62:65], v[54:57]
	v_mfma_f32_16x16x32_bf16 v[58:61], v[30:33], v[62:65], v[58:61]
	s_barrier
	s_add_i32 s12, s52, s17
	s_mov_b32 m0, s12
	ds_read_b128 v[62:65], v155 offset:16384
	ds_read_b128 v[94:97], v155 offset:17408
	ds_read_b128 v[98:101], v155 offset:18432
	ds_read_b128 v[112:115], v155 offset:19456
	ds_read_b128 v[116:119], v155 offset:20480
	ds_read_b128 v[120:123], v155 offset:21504
	ds_read_b128 v[124:127], v155 offset:22528
	ds_read_b128 v[128:131], v155 offset:23552
	global_load_lds_dwordx4 v134, s[0:1]
	s_add_i32 m0, s12, 0x2000
	v_lshl_add_u64 v[102:103], s[0:1], 0, v[138:139]
	s_add_u32 s0, s46, 0x14000
	s_addc_u32 s1, s47, 0
	s_add_i32 s12, s53, s17
	global_load_lds_dwordx4 v[102:103], off
	s_mov_b32 m0, s12
	v_lshl_add_u64 v[148:149], s[48:49], 0, v[132:133]
	global_load_lds_dwordx4 v134, s[0:1]
	s_add_i32 m0, s12, 0x2000
	v_lshl_add_u64 v[144:145], s[48:49], 0, v[136:137]
	global_load_lds_dwordx4 v138, s[0:1]
	s_mov_b32 m0, s18
	v_lshl_add_u64 v[102:103], v[148:149], 0, s[40:41]
	global_load_lds_dwordx4 v[102:103], off
	s_mov_b32 m0, s19
	v_lshl_add_u64 v[102:103], v[144:145], 0, s[40:41]
	global_load_lds_dwordx4 v[102:103], off
	s_waitcnt vmcnt(24) lgkmcnt(0)
	s_barrier
	v_mfma_f32_16x16x32_bf16 v[158:161], v[2:5], v[62:65], 0
	v_mfma_f32_16x16x32_bf16 v[166:169], v[2:5], v[98:101], 0
	v_mfma_f32_16x16x32_bf16 v[174:177], v[2:5], v[116:119], 0
	v_mfma_f32_16x16x32_bf16 v[2:5], v[2:5], v[124:127], 0
	v_mfma_f32_16x16x32_bf16 v[158:161], v[6:9], v[94:97], v[158:161]
	v_mfma_f32_16x16x32_bf16 v[166:169], v[6:9], v[112:115], v[166:169]
	v_mfma_f32_16x16x32_bf16 v[174:177], v[6:9], v[120:123], v[174:177]
	v_mfma_f32_16x16x32_bf16 v[2:5], v[6:9], v[128:131], v[2:5]
	v_mfma_f32_16x16x32_bf16 v[6:9], v[10:13], v[124:127], 0
	v_mfma_f32_16x16x32_bf16 v[162:165], v[10:13], v[62:65], 0
	v_mfma_f32_16x16x32_bf16 v[170:173], v[10:13], v[98:101], 0
	v_mfma_f32_16x16x32_bf16 v[178:181], v[10:13], v[116:119], 0
	v_mfma_f32_16x16x32_bf16 v[6:9], v[14:17], v[128:131], v[6:9]
	v_mfma_f32_16x16x32_bf16 v[162:165], v[14:17], v[94:97], v[162:165]
	v_mfma_f32_16x16x32_bf16 v[170:173], v[14:17], v[112:115], v[170:173]
	v_mfma_f32_16x16x32_bf16 v[178:181], v[14:17], v[120:123], v[178:181]
	v_mfma_f32_16x16x32_bf16 v[14:17], v[26:29], v[62:65], 0
	v_mfma_f32_16x16x32_bf16 v[182:185], v[30:33], v[94:97], v[14:17]
	v_mfma_f32_16x16x32_bf16 v[14:17], v[18:21], v[98:101], 0
	v_mfma_f32_16x16x32_bf16 v[186:189], v[22:25], v[112:115], v[14:17]
	v_mfma_f32_16x16x32_bf16 v[14:17], v[26:29], v[98:101], 0
	v_mfma_f32_16x16x32_bf16 v[190:193], v[30:33], v[112:115], v[14:17]
	v_mfma_f32_16x16x32_bf16 v[14:17], v[18:21], v[116:119], 0
	v_mfma_f32_16x16x32_bf16 v[194:197], v[22:25], v[120:123], v[14:17]
	v_mfma_f32_16x16x32_bf16 v[14:17], v[26:29], v[116:119], 0
	v_mfma_f32_16x16x32_bf16 v[10:13], v[18:21], v[62:65], 0
	v_mfma_f32_16x16x32_bf16 v[198:201], v[30:33], v[120:123], v[14:17]
	v_mfma_f32_16x16x32_bf16 v[14:17], v[18:21], v[124:127], 0
	v_mfma_f32_16x16x32_bf16 v[10:13], v[22:25], v[94:97], v[10:13]
	v_mfma_f32_16x16x32_bf16 v[202:205], v[22:25], v[128:131], v[14:17]
	v_mfma_f32_16x16x32_bf16 v[14:17], v[26:29], v[124:127], 0
	v_mfma_f32_16x16x32_bf16 v[206:209], v[30:33], v[128:131], v[14:17]
	s_barrier
	s_add_i32 s12, 0, 0x18000
	v_add_u32_e32 v1, s12, v151
	s_add_i32 s13, 0, 0x1c000
	s_nop 1
	ds_read_b128 v[14:17], v1
	ds_read_b128 v[24:27], v1 offset:1024
	ds_read_b128 v[28:31], v1 offset:2048
	ds_read_b128 v[210:213], v1 offset:3072
	v_add_u32_e32 v1, s13, v151
	ds_read_b128 v[214:217], v1
	ds_read_b128 v[218:221], v1 offset:1024
	ds_read_b128 v[222:225], v1 offset:2048
	ds_read_b128 v[226:229], v1 offset:3072
	s_add_u32 s0, s48, 0x2b0100
	s_addc_u32 s1, s49, 0
	s_mov_b32 m0, s20
	ds_read_b128 v[18:21], v155 offset:32768
	ds_read_b128 v[120:123], v155 offset:33792
	ds_read_b128 v[230:233], v155 offset:34816
	ds_read_b128 v[234:237], v155 offset:35840
	ds_read_b128 v[238:241], v155 offset:36864
	ds_read_b128 v[242:245], v155 offset:37888
	ds_read_b128 v[246:249], v155 offset:38912
	ds_read_b128 v[250:253], v155 offset:39936
	global_load_lds_dwordx4 v132, s[0:1]
	s_mov_b32 m0, s21
	s_nop 0
	global_load_lds_dwordx4 v136, s[0:1]
	s_waitcnt vmcnt(24) lgkmcnt(0)
	s_barrier
	v_mfma_f32_16x16x32_bf16 v[62:65], v[14:17], v[18:21], v[66:69]
	v_mfma_f32_16x16x32_bf16 v[128:131], v[24:27], v[120:123], v[62:65]
	v_mfma_f32_16x16x32_bf16 v[62:65], v[28:31], v[18:21], v[70:73]
	v_mfma_f32_16x16x32_bf16 v[116:119], v[210:213], v[120:123], v[62:65]
	v_mfma_f32_16x16x32_bf16 v[62:65], v[14:17], v[230:233], v[74:77]
	v_mfma_f32_16x16x32_bf16 v[112:115], v[24:27], v[234:237], v[62:65]
	v_mfma_f32_16x16x32_bf16 v[62:65], v[28:31], v[230:233], v[78:81]
	v_mfma_f32_16x16x32_bf16 v[100:103], v[210:213], v[234:237], v[62:65]
	v_mfma_f32_16x16x32_bf16 v[62:65], v[14:17], v[238:241], v[82:85]
	v_mfma_f32_16x16x32_bf16 v[96:99], v[24:27], v[242:245], v[62:65]
	v_mfma_f32_16x16x32_bf16 v[62:65], v[28:31], v[238:241], v[86:89]
	v_mfma_f32_16x16x32_bf16 v[84:87], v[210:213], v[242:245], v[62:65]
	v_mfma_f32_16x16x32_bf16 v[62:65], v[14:17], v[246:249], v[90:93]
	v_mfma_f32_16x16x32_bf16 v[80:83], v[24:27], v[250:253], v[62:65]
	v_mfma_f32_16x16x32_bf16 v[62:65], v[28:31], v[246:249], v[104:107]
	v_mfma_f32_16x16x32_bf16 v[64:67], v[210:213], v[250:253], v[62:65]
	v_mfma_f32_16x16x32_bf16 v[68:71], v[214:217], v[18:21], v[108:111]
	v_mfma_f32_16x16x32_bf16 v[18:21], v[222:225], v[18:21], v[34:37]
	v_mfma_f32_16x16x32_bf16 v[124:127], v[218:221], v[120:123], v[68:71]
	v_mfma_f32_16x16x32_bf16 v[120:123], v[226:229], v[120:123], v[18:21]
	v_mfma_f32_16x16x32_bf16 v[18:21], v[214:217], v[230:233], v[38:41]
	v_mfma_f32_16x16x32_bf16 v[108:111], v[218:221], v[234:237], v[18:21]
	v_mfma_f32_16x16x32_bf16 v[18:21], v[222:225], v[230:233], v[42:45]
	v_mfma_f32_16x16x32_bf16 v[104:107], v[226:229], v[234:237], v[18:21]
	v_mfma_f32_16x16x32_bf16 v[18:21], v[214:217], v[238:241], v[46:49]
	v_mfma_f32_16x16x32_bf16 v[92:95], v[218:221], v[242:245], v[18:21]
	v_mfma_f32_16x16x32_bf16 v[18:21], v[222:225], v[238:241], v[50:53]
	v_mfma_f32_16x16x32_bf16 v[88:91], v[226:229], v[242:245], v[18:21]
	v_mfma_f32_16x16x32_bf16 v[18:21], v[214:217], v[246:249], v[54:57]
	v_mfma_f32_16x16x32_bf16 v[72:75], v[218:221], v[250:253], v[18:21]
	v_mfma_f32_16x16x32_bf16 v[18:21], v[222:225], v[246:249], v[58:61]
	v_mfma_f32_16x16x32_bf16 v[68:71], v[226:229], v[250:253], v[18:21]
	s_barrier
	s_add_u32 s0, s46, 0x18000
	s_addc_u32 s1, s47, 0
	s_add_i32 s12, s12, s17
	s_nop 1
	s_mov_b32 m0, s12
	ds_read_b128 v[40:43], v155 offset:49152
	ds_read_b128 v[44:47], v155 offset:50176
	ds_read_b128 v[230:233], v155 offset:51200
	ds_read_b128 v[234:237], v155 offset:52224
	ds_read_b128 v[238:241], v155 offset:53248
	ds_read_b128 v[242:245], v155 offset:54272
	ds_read_b128 v[246:249], v155 offset:55296
	ds_read_b128 v[250:253], v155 offset:56320
	global_load_lds_dwordx4 v134, s[0:1]
	s_add_i32 m0, s12, 0x2000
	v_lshl_add_u64 v[18:19], s[0:1], 0, v[138:139]
	s_add_u32 s0, s46, 0x1c000
	s_addc_u32 s1, s47, 0
	s_add_i32 s12, s13, s17
	global_load_lds_dwordx4 v[18:19], off
	s_mov_b32 m0, s12
	s_nop 0
	global_load_lds_dwordx4 v134, s[0:1]
	s_add_i32 m0, s12, 0x2000
	s_nop 0
	global_load_lds_dwordx4 v138, s[0:1]
	s_mov_b32 m0, s25
	v_lshl_add_u64 v[18:19], v[148:149], 0, s[42:43]
	global_load_lds_dwordx4 v[18:19], off
	s_mov_b32 m0, s33
	v_lshl_add_u64 v[18:19], v[144:145], 0, s[42:43]
	global_load_lds_dwordx4 v[18:19], off
	s_waitcnt vmcnt(8) lgkmcnt(0)
	s_barrier
	v_mfma_f32_16x16x32_bf16 v[18:21], v[14:17], v[40:43], v[158:161]
	v_mfma_f32_16x16x32_bf16 v[76:79], v[24:27], v[44:47], v[18:21]
	v_mfma_f32_16x16x32_bf16 v[18:21], v[28:31], v[40:43], v[162:165]
	v_mfma_f32_16x16x32_bf16 v[52:55], v[210:213], v[44:47], v[18:21]
	v_mfma_f32_16x16x32_bf16 v[18:21], v[14:17], v[230:233], v[166:169]
	v_mfma_f32_16x16x32_bf16 v[48:51], v[24:27], v[234:237], v[18:21]
	v_mfma_f32_16x16x32_bf16 v[18:21], v[28:31], v[230:233], v[170:173]
	v_mfma_f32_16x16x32_bf16 v[36:39], v[210:213], v[234:237], v[18:21]
	v_mfma_f32_16x16x32_bf16 v[18:21], v[14:17], v[238:241], v[174:177]
	v_mfma_f32_16x16x32_bf16 v[32:35], v[24:27], v[242:245], v[18:21]
	v_mfma_f32_16x16x32_bf16 v[18:21], v[28:31], v[238:241], v[178:181]
	v_mfma_f32_16x16x32_bf16 v[2:5], v[14:17], v[246:249], v[2:5]
	v_mfma_f32_16x16x32_bf16 v[20:23], v[210:213], v[242:245], v[18:21]
	v_mfma_f32_16x16x32_bf16 v[16:19], v[24:27], v[250:253], v[2:5]
	v_mfma_f32_16x16x32_bf16 v[2:5], v[28:31], v[246:249], v[6:9]
	v_mfma_f32_16x16x32_bf16 v[4:7], v[210:213], v[250:253], v[2:5]
	v_mfma_f32_16x16x32_bf16 v[8:11], v[214:217], v[40:43], v[10:13]
	v_mfma_f32_16x16x32_bf16 v[60:63], v[218:221], v[44:47], v[8:11]
	v_mfma_f32_16x16x32_bf16 v[8:11], v[222:225], v[40:43], v[182:185]
	v_mfma_f32_16x16x32_bf16 v[56:59], v[226:229], v[44:47], v[8:11]
	v_mfma_f32_16x16x32_bf16 v[8:11], v[214:217], v[230:233], v[186:189]
	v_mfma_f32_16x16x32_bf16 v[44:47], v[218:221], v[234:237], v[8:11]
	v_mfma_f32_16x16x32_bf16 v[8:11], v[222:225], v[230:233], v[190:193]
	v_mfma_f32_16x16x32_bf16 v[40:43], v[226:229], v[234:237], v[8:11]
	v_mfma_f32_16x16x32_bf16 v[8:11], v[214:217], v[238:241], v[194:197]
	v_mfma_f32_16x16x32_bf16 v[28:31], v[218:221], v[242:245], v[8:11]
	v_mfma_f32_16x16x32_bf16 v[8:11], v[222:225], v[238:241], v[198:201]
	v_mfma_f32_16x16x32_bf16 v[24:27], v[226:229], v[242:245], v[8:11]
	v_mfma_f32_16x16x32_bf16 v[8:11], v[214:217], v[246:249], v[202:205]
	v_mfma_f32_16x16x32_bf16 v[12:15], v[218:221], v[250:253], v[8:11]
	v_mfma_f32_16x16x32_bf16 v[8:11], v[222:225], v[246:249], v[206:209]
	v_mfma_f32_16x16x32_bf16 v[8:11], v[226:229], v[250:253], v[8:11]
	s_barrier
	s_mov_b32 s22, 2
	s_branch .LBB0_895

.LBB0_896:
	ds_read_b128 v[158:161], v153
	ds_read_b128 v[162:165], v153 offset:1024
	ds_read_b128 v[166:169], v153 offset:2048
	ds_read_b128 v[170:173], v153 offset:3072
	ds_read_b128 v[174:177], v154
	ds_read_b128 v[178:181], v154 offset:1024
	ds_read_b128 v[182:185], v154 offset:2048
	ds_read_b128 v[186:189], v154 offset:3072
	s_add_u32 s12, s60, s26
	s_addc_u32 s13, s61, 0
	s_cmp_eq_u32 s26, s46
	s_cselect_b32 s23, s9, s13
	s_cselect_b32 s22, s8, s12
	s_cselect_b32 s49, s45, s59
	s_cselect_b32 s48, s44, s1
	s_add_i32 s63, s18, 0xc000
	v_lshl_add_u64 v[144:145], v[2:3], 0, s[26:27]
	s_mov_b32 m0, s63
	s_add_i32 s62, s18, 0xe000
	ds_read_b128 v[190:193], v155
	ds_read_b128 v[194:197], v155 offset:1024
	ds_read_b128 v[198:201], v155 offset:2048
	ds_read_b128 v[202:205], v155 offset:3072
	ds_read_b128 v[206:209], v155 offset:4096
	ds_read_b128 v[210:213], v155 offset:5120
	ds_read_b128 v[214:217], v155 offset:6144
	ds_read_b128 v[218:221], v155 offset:7168
	global_load_lds_dwordx4 v[144:145], off
	s_mov_b32 m0, s62
	v_lshl_add_u64 v[144:145], v[148:149], 0, s[26:27]
	global_load_lds_dwordx4 v[144:145], off
	s_waitcnt vmcnt(8) lgkmcnt(0)
	s_barrier
	v_mfma_f32_16x16x32_bf16 v[128:131], v[158:161], v[190:193], v[128:131]
	v_mfma_f32_16x16x32_bf16 v[128:131], v[162:165], v[194:197], v[128:131]
	v_mfma_f32_16x16x32_bf16 v[116:119], v[166:169], v[190:193], v[116:119]
	v_mfma_f32_16x16x32_bf16 v[116:119], v[170:173], v[194:197], v[116:119]
	v_mfma_f32_16x16x32_bf16 v[100:103], v[166:169], v[198:201], v[100:103]
	v_mfma_f32_16x16x32_bf16 v[100:103], v[170:173], v[202:205], v[100:103]
	v_mfma_f32_16x16x32_bf16 v[112:115], v[158:161], v[198:201], v[112:115]
	v_mfma_f32_16x16x32_bf16 v[112:115], v[162:165], v[202:205], v[112:115]
	v_mfma_f32_16x16x32_bf16 v[96:99], v[158:161], v[206:209], v[96:99]
	v_mfma_f32_16x16x32_bf16 v[96:99], v[162:165], v[210:213], v[96:99]
	v_mfma_f32_16x16x32_bf16 v[84:87], v[166:169], v[206:209], v[84:87]
	v_mfma_f32_16x16x32_bf16 v[84:87], v[170:173], v[210:213], v[84:87]
	v_mfma_f32_16x16x32_bf16 v[64:67], v[166:169], v[214:217], v[64:67]
	v_mfma_f32_16x16x32_bf16 v[64:67], v[170:173], v[218:221], v[64:67]
	v_mfma_f32_16x16x32_bf16 v[80:83], v[158:161], v[214:217], v[80:83]
	v_mfma_f32_16x16x32_bf16 v[80:83], v[162:165], v[218:221], v[80:83]
	v_mfma_f32_16x16x32_bf16 v[72:75], v[174:177], v[214:217], v[72:75]
	v_mfma_f32_16x16x32_bf16 v[72:75], v[178:181], v[218:221], v[72:75]
	v_mfma_f32_16x16x32_bf16 v[68:71], v[182:185], v[214:217], v[68:71]
	v_mfma_f32_16x16x32_bf16 v[68:71], v[186:189], v[218:221], v[68:71]
	v_mfma_f32_16x16x32_bf16 v[88:91], v[182:185], v[206:209], v[88:91]
	v_mfma_f32_16x16x32_bf16 v[88:91], v[186:189], v[210:213], v[88:91]
	v_mfma_f32_16x16x32_bf16 v[92:95], v[174:177], v[206:209], v[92:95]
	v_mfma_f32_16x16x32_bf16 v[92:95], v[178:181], v[210:213], v[92:95]
	v_mfma_f32_16x16x32_bf16 v[108:111], v[174:177], v[198:201], v[108:111]
	v_mfma_f32_16x16x32_bf16 v[108:111], v[178:181], v[202:205], v[108:111]
	v_mfma_f32_16x16x32_bf16 v[104:107], v[182:185], v[198:201], v[104:107]
	v_mfma_f32_16x16x32_bf16 v[104:107], v[186:189], v[202:205], v[104:107]
	v_mfma_f32_16x16x32_bf16 v[120:123], v[182:185], v[190:193], v[120:123]
	v_mfma_f32_16x16x32_bf16 v[120:123], v[186:189], v[194:197], v[120:123]
	v_mfma_f32_16x16x32_bf16 v[124:127], v[174:177], v[190:193], v[124:127]
	v_mfma_f32_16x16x32_bf16 v[124:127], v[178:181], v[194:197], v[124:127]
	s_barrier
	s_add_i32 s12, s52, s17
	s_mov_b32 m0, s12
	ds_read_b128 v[190:193], v155 offset:16384
	ds_read_b128 v[194:197], v155 offset:17408
	ds_read_b128 v[198:201], v155 offset:18432
	ds_read_b128 v[202:205], v155 offset:19456
	ds_read_b128 v[206:209], v155 offset:20480
	ds_read_b128 v[210:213], v155 offset:21504
	ds_read_b128 v[214:217], v155 offset:22528
	ds_read_b128 v[218:221], v155 offset:23552
	global_load_lds_dwordx4 v134, s[48:49]
	s_add_i32 m0, s12, 0x2000
	s_add_u32 s12, s48, 0x4000
	s_addc_u32 s13, s49, 0
	s_add_i32 s14, s53, s17
	global_load_lds_dwordx4 v138, s[48:49]
	s_mov_b32 m0, s14
	v_lshl_add_u64 v[222:223], s[22:23], 0, v[136:137]
	global_load_lds_dwordx4 v134, s[12:13]
	s_add_i32 m0, s14, 0x2000
	s_nop 0
	global_load_lds_dwordx4 v138, s[12:13]
	s_mov_b32 m0, s18
	v_lshl_add_u64 v[144:145], s[22:23], 0, v[132:133]
	global_load_lds_dwordx4 v[144:145], off
	s_mov_b32 m0, s19
	s_nop 0
	global_load_lds_dwordx4 v[222:223], off
	s_waitcnt vmcnt(8) lgkmcnt(0)
	s_barrier
	v_mfma_f32_16x16x32_bf16 v[76:79], v[158:161], v[190:193], v[76:79]
	v_mfma_f32_16x16x32_bf16 v[76:79], v[162:165], v[194:197], v[76:79]
	v_mfma_f32_16x16x32_bf16 v[52:55], v[166:169], v[190:193], v[52:55]
	v_mfma_f32_16x16x32_bf16 v[52:55], v[170:173], v[194:197], v[52:55]
	v_mfma_f32_16x16x32_bf16 v[36:39], v[166:169], v[198:201], v[36:39]
	v_mfma_f32_16x16x32_bf16 v[36:39], v[170:173], v[202:205], v[36:39]
	v_mfma_f32_16x16x32_bf16 v[48:51], v[158:161], v[198:201], v[48:51]
	v_mfma_f32_16x16x32_bf16 v[48:51], v[162:165], v[202:205], v[48:51]
	v_mfma_f32_16x16x32_bf16 v[32:35], v[158:161], v[206:209], v[32:35]
	v_mfma_f32_16x16x32_bf16 v[32:35], v[162:165], v[210:213], v[32:35]
	v_mfma_f32_16x16x32_bf16 v[20:23], v[166:169], v[206:209], v[20:23]
	v_mfma_f32_16x16x32_bf16 v[20:23], v[170:173], v[210:213], v[20:23]
	v_mfma_f32_16x16x32_bf16 v[4:7], v[166:169], v[214:217], v[4:7]
	v_mfma_f32_16x16x32_bf16 v[4:7], v[170:173], v[218:221], v[4:7]
	v_mfma_f32_16x16x32_bf16 v[16:19], v[158:161], v[214:217], v[16:19]
	v_mfma_f32_16x16x32_bf16 v[16:19], v[162:165], v[218:221], v[16:19]
	v_mfma_f32_16x16x32_bf16 v[12:15], v[174:177], v[214:217], v[12:15]
	v_mfma_f32_16x16x32_bf16 v[12:15], v[178:181], v[218:221], v[12:15]
	v_mfma_f32_16x16x32_bf16 v[8:11], v[182:185], v[214:217], v[8:11]
	v_mfma_f32_16x16x32_bf16 v[8:11], v[186:189], v[218:221], v[8:11]
	v_mfma_f32_16x16x32_bf16 v[24:27], v[182:185], v[206:209], v[24:27]
	v_mfma_f32_16x16x32_bf16 v[24:27], v[186:189], v[210:213], v[24:27]
	v_mfma_f32_16x16x32_bf16 v[28:31], v[174:177], v[206:209], v[28:31]
	v_mfma_f32_16x16x32_bf16 v[28:31], v[178:181], v[210:213], v[28:31]
	v_mfma_f32_16x16x32_bf16 v[44:47], v[174:177], v[198:201], v[44:47]
	v_mfma_f32_16x16x32_bf16 v[44:47], v[178:181], v[202:205], v[44:47]
	v_mfma_f32_16x16x32_bf16 v[40:43], v[182:185], v[198:201], v[40:43]
	v_mfma_f32_16x16x32_bf16 v[40:43], v[186:189], v[202:205], v[40:43]
	v_mfma_f32_16x16x32_bf16 v[56:59], v[182:185], v[190:193], v[56:59]
	v_mfma_f32_16x16x32_bf16 v[56:59], v[186:189], v[194:197], v[56:59]
	v_mfma_f32_16x16x32_bf16 v[60:63], v[174:177], v[190:193], v[60:63]
	v_mfma_f32_16x16x32_bf16 v[60:63], v[178:181], v[194:197], v[60:63]
	s_barrier
	s_add_i32 s14, 0, 0x18000
	v_add_u32_e32 v1, s14, v151
	s_add_i32 s64, 0, 0x1c000
	ds_read_b128 v[158:161], v1
	ds_read_b128 v[162:165], v1 offset:1024
	ds_read_b128 v[166:169], v1 offset:2048
	ds_read_b128 v[170:173], v1 offset:3072
	v_add_u32_e32 v1, s64, v151
	ds_read_b128 v[174:177], v1
	ds_read_b128 v[178:181], v1 offset:1024
	ds_read_b128 v[182:185], v1 offset:2048
	ds_read_b128 v[186:189], v1 offset:3072
	s_add_u32 s12, s22, 0x2b0000
	s_addc_u32 s13, s23, 0
	s_mov_b32 m0, s20
	ds_read_b128 v[190:193], v155 offset:32768
	ds_read_b128 v[194:197], v155 offset:33792
	ds_read_b128 v[198:201], v155 offset:34816
	ds_read_b128 v[202:205], v155 offset:35840
	ds_read_b128 v[206:209], v155 offset:36864
	ds_read_b128 v[210:213], v155 offset:37888
	ds_read_b128 v[214:217], v155 offset:38912
	ds_read_b128 v[218:221], v155 offset:39936
	global_load_lds_dwordx4 v132, s[12:13]
	s_mov_b32 m0, s21
	s_nop 0
	global_load_lds_dwordx4 v136, s[12:13]
	s_waitcnt vmcnt(8) lgkmcnt(0)
	s_barrier
	v_mfma_f32_16x16x32_bf16 v[128:131], v[158:161], v[190:193], v[128:131]
	v_mfma_f32_16x16x32_bf16 v[128:131], v[162:165], v[194:197], v[128:131]
	v_mfma_f32_16x16x32_bf16 v[116:119], v[166:169], v[190:193], v[116:119]
	v_mfma_f32_16x16x32_bf16 v[116:119], v[170:173], v[194:197], v[116:119]
	v_mfma_f32_16x16x32_bf16 v[100:103], v[166:169], v[198:201], v[100:103]
	v_mfma_f32_16x16x32_bf16 v[100:103], v[170:173], v[202:205], v[100:103]
	v_mfma_f32_16x16x32_bf16 v[112:115], v[158:161], v[198:201], v[112:115]
	v_mfma_f32_16x16x32_bf16 v[112:115], v[162:165], v[202:205], v[112:115]
	v_mfma_f32_16x16x32_bf16 v[96:99], v[158:161], v[206:209], v[96:99]
	v_mfma_f32_16x16x32_bf16 v[96:99], v[162:165], v[210:213], v[96:99]
	v_mfma_f32_16x16x32_bf16 v[84:87], v[166:169], v[206:209], v[84:87]
	v_mfma_f32_16x16x32_bf16 v[84:87], v[170:173], v[210:213], v[84:87]
	v_mfma_f32_16x16x32_bf16 v[64:67], v[166:169], v[214:217], v[64:67]
	v_mfma_f32_16x16x32_bf16 v[64:67], v[170:173], v[218:221], v[64:67]
	v_mfma_f32_16x16x32_bf16 v[80:83], v[158:161], v[214:217], v[80:83]
	v_mfma_f32_16x16x32_bf16 v[80:83], v[162:165], v[218:221], v[80:83]
	v_mfma_f32_16x16x32_bf16 v[72:75], v[174:177], v[214:217], v[72:75]
	v_mfma_f32_16x16x32_bf16 v[72:75], v[178:181], v[218:221], v[72:75]
	v_mfma_f32_16x16x32_bf16 v[68:71], v[182:185], v[214:217], v[68:71]
	v_mfma_f32_16x16x32_bf16 v[68:71], v[186:189], v[218:221], v[68:71]
	v_mfma_f32_16x16x32_bf16 v[88:91], v[182:185], v[206:209], v[88:91]
	v_mfma_f32_16x16x32_bf16 v[88:91], v[186:189], v[210:213], v[88:91]
	v_mfma_f32_16x16x32_bf16 v[92:95], v[174:177], v[206:209], v[92:95]
	v_mfma_f32_16x16x32_bf16 v[92:95], v[178:181], v[210:213], v[92:95]
	v_mfma_f32_16x16x32_bf16 v[108:111], v[174:177], v[198:201], v[108:111]
	v_mfma_f32_16x16x32_bf16 v[108:111], v[178:181], v[202:205], v[108:111]
	v_mfma_f32_16x16x32_bf16 v[104:107], v[182:185], v[198:201], v[104:107]
	v_mfma_f32_16x16x32_bf16 v[104:107], v[186:189], v[202:205], v[104:107]
	v_mfma_f32_16x16x32_bf16 v[120:123], v[182:185], v[190:193], v[120:123]
	v_mfma_f32_16x16x32_bf16 v[120:123], v[186:189], v[194:197], v[120:123]
	v_mfma_f32_16x16x32_bf16 v[124:127], v[174:177], v[190:193], v[124:127]
	v_mfma_f32_16x16x32_bf16 v[124:127], v[178:181], v[194:197], v[124:127]
	s_barrier
	s_add_u32 s12, s48, 0x8000
	s_addc_u32 s13, s49, 0
	s_add_i32 s14, s14, s17
	s_mov_b32 m0, s14
	ds_read_b128 v[190:193], v155 offset:49152
	ds_read_b128 v[194:197], v155 offset:50176
	ds_read_b128 v[198:201], v155 offset:51200
	ds_read_b128 v[202:205], v155 offset:52224
	ds_read_b128 v[206:209], v155 offset:53248
	ds_read_b128 v[210:213], v155 offset:54272
	ds_read_b128 v[214:217], v155 offset:55296
	ds_read_b128 v[218:221], v155 offset:56320
	global_load_lds_dwordx4 v134, s[12:13]
	s_add_i32 m0, s14, 0x2000
	v_lshl_add_u64 v[224:225], s[12:13], 0, v[138:139]
	s_add_u32 s12, s48, 0xc000
	s_addc_u32 s13, s49, 0
	s_add_i32 s14, s64, s17
	global_load_lds_dwordx4 v[224:225], off
	s_mov_b32 m0, s14
	v_lshl_add_u64 v[144:145], v[144:145], 0, s[36:37]
	global_load_lds_dwordx4 v134, s[12:13]
	s_add_i32 m0, s14, 0x2000
	v_lshl_add_u64 v[224:225], s[12:13], 0, v[138:139]
	global_load_lds_dwordx4 v[224:225], off
	s_mov_b32 m0, s25
	s_nop 0
	global_load_lds_dwordx4 v[144:145], off
	s_mov_b32 m0, s33
	v_lshl_add_u64 v[144:145], v[222:223], 0, s[36:37]
	global_load_lds_dwordx4 v[144:145], off
	s_waitcnt vmcnt(8) lgkmcnt(0)
	s_barrier
	v_mfma_f32_16x16x32_bf16 v[76:79], v[158:161], v[190:193], v[76:79]
	v_mfma_f32_16x16x32_bf16 v[76:79], v[162:165], v[194:197], v[76:79]
	v_mfma_f32_16x16x32_bf16 v[52:55], v[166:169], v[190:193], v[52:55]
	v_mfma_f32_16x16x32_bf16 v[52:55], v[170:173], v[194:197], v[52:55]
	v_mfma_f32_16x16x32_bf16 v[36:39], v[166:169], v[198:201], v[36:39]
	v_mfma_f32_16x16x32_bf16 v[36:39], v[170:173], v[202:205], v[36:39]
	v_mfma_f32_16x16x32_bf16 v[48:51], v[158:161], v[198:201], v[48:51]
	v_mfma_f32_16x16x32_bf16 v[48:51], v[162:165], v[202:205], v[48:51]
	v_mfma_f32_16x16x32_bf16 v[32:35], v[158:161], v[206:209], v[32:35]
	v_mfma_f32_16x16x32_bf16 v[32:35], v[162:165], v[210:213], v[32:35]
	v_mfma_f32_16x16x32_bf16 v[20:23], v[166:169], v[206:209], v[20:23]
	v_mfma_f32_16x16x32_bf16 v[20:23], v[170:173], v[210:213], v[20:23]
	v_mfma_f32_16x16x32_bf16 v[4:7], v[166:169], v[214:217], v[4:7]
	v_mfma_f32_16x16x32_bf16 v[4:7], v[170:173], v[218:221], v[4:7]
	v_mfma_f32_16x16x32_bf16 v[16:19], v[158:161], v[214:217], v[16:19]
	v_mfma_f32_16x16x32_bf16 v[16:19], v[162:165], v[218:221], v[16:19]
	v_mfma_f32_16x16x32_bf16 v[12:15], v[174:177], v[214:217], v[12:15]
	v_mfma_f32_16x16x32_bf16 v[12:15], v[178:181], v[218:221], v[12:15]
	v_mfma_f32_16x16x32_bf16 v[8:11], v[182:185], v[214:217], v[8:11]
	v_mfma_f32_16x16x32_bf16 v[8:11], v[186:189], v[218:221], v[8:11]
	v_mfma_f32_16x16x32_bf16 v[24:27], v[182:185], v[206:209], v[24:27]
	v_mfma_f32_16x16x32_bf16 v[24:27], v[186:189], v[210:213], v[24:27]
	v_mfma_f32_16x16x32_bf16 v[28:31], v[174:177], v[206:209], v[28:31]
	v_mfma_f32_16x16x32_bf16 v[28:31], v[178:181], v[210:213], v[28:31]
	v_mfma_f32_16x16x32_bf16 v[44:47], v[174:177], v[198:201], v[44:47]
	v_mfma_f32_16x16x32_bf16 v[44:47], v[178:181], v[202:205], v[44:47]
	v_mfma_f32_16x16x32_bf16 v[40:43], v[182:185], v[198:201], v[40:43]
	v_mfma_f32_16x16x32_bf16 v[40:43], v[186:189], v[202:205], v[40:43]
	v_mfma_f32_16x16x32_bf16 v[56:59], v[182:185], v[190:193], v[56:59]
	v_mfma_f32_16x16x32_bf16 v[56:59], v[186:189], v[194:197], v[56:59]
	v_mfma_f32_16x16x32_bf16 v[60:63], v[174:177], v[190:193], v[60:63]
	v_mfma_f32_16x16x32_bf16 v[60:63], v[178:181], v[194:197], v[60:63]
	s_barrier
	s_add_i32 s0, s0, 2
	s_add_u32 s1, s1, 0x10000
	s_addc_u32 s59, s59, 0
	s_add_u32 s60, s60, 0x100
	s_addc_u32 s61, s61, 0
	s_add_u32 s46, s46, 0xffffff00
	s_addc_u32 s47, s47, -1
	v_lshl_add_u64 v[2:3], v[2:3], 0, s[40:41]
	s_cmpk_gt_u32 s0, 0xa9
	v_lshl_add_u64 v[148:149], v[148:149], 0, s[40:41]
	s_cbranch_scc0 .LBB0_896
	s_and_b64 vcc, exec, s[38:39]
	s_cbranch_vccz .LBB0_899
	s_barrier
.LBB0_899:
	s_and_b64 vcc, exec, s[6:7]
	s_cbranch_vccnz .LBB0_901
	s_add_u32 s0, s8, 0x2b0080
	s_addc_u32 s1, s9, 0
	s_mov_b32 m0, s63
	v_lshl_add_u64 v[2:3], s[0:1], 0, v[132:133]
	global_load_lds_dwordx4 v[2:3], off
	s_mov_b32 m0, s62
	s_nop 0
	global_load_lds_dwordx4 v136, s[0:1]

.LBB0_1717:
	s_add_u32 s28, s78, 0x43400000
	s_addc_u32 s29, s79, 0
	s_add_u32 s30, s78, 0x900000
	s_addc_u32 s31, s79, 0
	s_bfe_u32 s33, s88, 0x20006
	s_add_u32 s4, s44, 0x8000
	s_addc_u32 s5, s45, 0
	s_add_i32 m0, s18, 0x18000
	s_waitcnt vmcnt(0)
	s_waitcnt vmcnt(2)
	s_barrier
	global_load_lds_dwordx4 v134, s[4:5]
	s_add_i32 m0, s18, 0x1a000
	s_mov_b64 s[34:35], 0x80
	s_add_i32 s48, s18, 0x8000
	s_add_i32 s49, s18, 0xa000
	global_load_lds_dwordx4 v138, s[4:5]
	v_lshl_add_u64 v[2:3], v[2:3], 0, s[34:35]
	s_mov_b32 m0, s48
	s_add_u32 s4, s44, 0xc000
	global_load_lds_dwordx4 v[2:3], off
	v_lshl_add_u64 v[2:3], v[4:5], 0, s[34:35]
	s_mov_b32 m0, s49
	s_addc_u32 s5, s45, 0
	global_load_lds_dwordx4 v[2:3], off
	s_add_i32 m0, s18, 0x1c000
	s_nop 0
	global_load_lds_dwordx4 v134, s[4:5]
	v_lshl_add_u64 v[2:3], s[4:5], 0, v[138:139]
	s_add_i32 m0, s18, 0x1e000
	v_and_b32_e32 v4, 48, v1
	global_load_lds_dwordx4 v[2:3], off
	v_and_b32_e32 v2, 15, v1
	v_lshl_or_b32 v150, s0, 6, v2
	v_and_b32_e32 v5, 0xfffffc00, v10
	v_lshl_or_b32 v2, v2, 6, v4
	v_lshlrev_b32_e32 v4, 2, v1
	v_ashrrev_i32_e32 v3, 1, v1
	v_lshl_add_u32 v10, s0, 13, v5
	v_and_b32_e32 v4, 32, v4
	v_lshl_add_u32 v5, s33, 12, v5
	v_and_b32_e32 v3, -8, v3
	v_bitop3_b32 v10, v2, v10, v4 bitop3:0xde
	v_bitop3_b32 v151, v2, v5, v4 bitop3:0xde
	v_cmp_gt_u32_e64 s[4:5], 16, v1
	v_lshrrev_b32_e32 v1, 1, v6
	v_mul_lo_u32 v2, v8, s1
	s_mov_b32 s0, 0x2b000
	v_lshl_add_u32 v152, s33, 5, v3
	v_mad_u64_u32 v[2:3], s[6:7], v1, s0, v[2:3]
	v_or_b32_e32 v1, v2, v7
	v_add_lshl_u32 v2, v1, v9, 1
	v_mov_b32_e32 v3, v0
	s_mov_b64 s[6:7], 0x2b0080
	v_lshl_add_u64 v[140:141], v[2:3], 0, s[6:7]
	v_lshrrev_b32_e32 v1, 1, v11
	v_mul_lo_u32 v2, v12, s1
	v_mad_u64_u32 v[2:3], s[0:1], v1, s0, v[2:3]
	s_waitcnt vmcnt(6)
	s_cmpk_lt_u32 s88, 0x100
	v_or_b32_e32 v1, v2, v13
	s_cselect_b64 s[36:37], -1, 0
	v_add_lshl_u32 v2, v1, v14, 1
	v_mov_b32_e32 v3, v0
	s_add_i32 s52, 0, 0x10000
	s_add_i32 s53, 0, 0x14000
	v_mbcnt_lo_u32_b32 v1, -1, 0
	s_ashr_i32 s50, s77, 31
	s_ashr_i32 s51, s90, 31
	v_lshl_add_u64 v[142:143], v[2:3], 0, s[6:7]
	v_mov_b64_e32 v[146:147], 0x1ff
	v_add_u32_e32 v153, s52, v151
	v_add_u32_e32 v154, s53, v151
	v_add_u32_e32 v155, 0, v10
	s_mov_b64 s[38:39], 0x100
	s_mov_b64 s[40:41], 0x180
	v_mbcnt_hi_u32_b32 v156, -1, v1
	s_mov_b32 s22, 0
	s_barrier
	s_branch .LBB0_1720

.LBB0_1729:
	ds_read_b128 v[2:5], v153
	ds_read_b128 v[6:9], v153 offset:1024
	ds_read_b128 v[10:13], v153 offset:2048
	ds_read_b128 v[14:17], v153 offset:3072
	ds_read_b128 v[18:21], v154
	ds_read_b128 v[22:25], v154 offset:1024
	ds_read_b128 v[26:29], v154 offset:2048
	ds_read_b128 v[30:33], v154 offset:3072
	s_add_u32 s0, s44, 0x10000
	s_addc_u32 s1, s45, 0
	ds_read_b128 v[34:37], v155
	ds_read_b128 v[38:41], v155 offset:1024
	ds_read_b128 v[42:45], v155 offset:2048
	ds_read_b128 v[46:49], v155 offset:3072
	ds_read_b128 v[50:53], v155 offset:4096
	ds_read_b128 v[54:57], v155 offset:5120
	ds_read_b128 v[58:61], v155 offset:6144
	ds_read_b128 v[62:65], v155 offset:7168
	s_waitcnt vmcnt(24) lgkmcnt(0)
	s_barrier
	v_mfma_f32_16x16x32_bf16 v[66:69], v[2:5], v[34:37], 0
	v_mfma_f32_16x16x32_bf16 v[70:73], v[10:13], v[34:37], 0
	v_mfma_f32_16x16x32_bf16 v[74:77], v[2:5], v[42:45], 0
	v_mfma_f32_16x16x32_bf16 v[78:81], v[10:13], v[42:45], 0
	v_mfma_f32_16x16x32_bf16 v[82:85], v[2:5], v[50:53], 0
	v_mfma_f32_16x16x32_bf16 v[86:89], v[10:13], v[50:53], 0
	v_mfma_f32_16x16x32_bf16 v[90:93], v[2:5], v[58:61], 0
	v_mfma_f32_16x16x32_bf16 v[94:97], v[10:13], v[58:61], 0
	v_mfma_f32_16x16x32_bf16 v[66:69], v[6:9], v[38:41], v[66:69]
	v_mfma_f32_16x16x32_bf16 v[70:73], v[14:17], v[38:41], v[70:73]
	v_mfma_f32_16x16x32_bf16 v[74:77], v[6:9], v[46:49], v[74:77]
	v_mfma_f32_16x16x32_bf16 v[78:81], v[14:17], v[46:49], v[78:81]
	v_mfma_f32_16x16x32_bf16 v[82:85], v[6:9], v[54:57], v[82:85]
	v_mfma_f32_16x16x32_bf16 v[86:89], v[14:17], v[54:57], v[86:89]
	v_mfma_f32_16x16x32_bf16 v[90:93], v[6:9], v[62:65], v[90:93]
	v_mfma_f32_16x16x32_bf16 v[104:107], v[14:17], v[62:65], v[94:97]
	v_mfma_f32_16x16x32_bf16 v[94:97], v[18:21], v[34:37], 0
	v_mfma_f32_16x16x32_bf16 v[34:37], v[26:29], v[34:37], 0
	v_mfma_f32_16x16x32_bf16 v[108:111], v[22:25], v[38:41], v[94:97]
	v_mfma_f32_16x16x32_bf16 v[34:37], v[30:33], v[38:41], v[34:37]
	v_mfma_f32_16x16x32_bf16 v[38:41], v[18:21], v[42:45], 0
	v_mfma_f32_16x16x32_bf16 v[42:45], v[26:29], v[42:45], 0
	v_mfma_f32_16x16x32_bf16 v[38:41], v[22:25], v[46:49], v[38:41]
	v_mfma_f32_16x16x32_bf16 v[42:45], v[30:33], v[46:49], v[42:45]
	v_mfma_f32_16x16x32_bf16 v[46:49], v[18:21], v[50:53], 0
	v_mfma_f32_16x16x32_bf16 v[50:53], v[26:29], v[50:53], 0
	v_mfma_f32_16x16x32_bf16 v[46:49], v[22:25], v[54:57], v[46:49]
	v_mfma_f32_16x16x32_bf16 v[50:53], v[30:33], v[54:57], v[50:53]
	v_mfma_f32_16x16x32_bf16 v[54:57], v[18:21], v[58:61], 0
	v_mfma_f32_16x16x32_bf16 v[58:61], v[26:29], v[58:61], 0
	v_mfma_f32_16x16x32_bf16 v[54:57], v[22:25], v[62:65], v[54:57]
	v_mfma_f32_16x16x32_bf16 v[58:61], v[30:33], v[62:65], v[58:61]
	s_barrier
	s_add_i32 s12, s52, s17
	s_mov_b32 m0, s12
	ds_read_b128 v[62:65], v155 offset:16384
	ds_read_b128 v[94:97], v155 offset:17408
	ds_read_b128 v[98:101], v155 offset:18432
	ds_read_b128 v[112:115], v155 offset:19456
	ds_read_b128 v[116:119], v155 offset:20480
	ds_read_b128 v[120:123], v155 offset:21504
	ds_read_b128 v[124:127], v155 offset:22528
	ds_read_b128 v[128:131], v155 offset:23552
	global_load_lds_dwordx4 v134, s[0:1]
	s_add_i32 m0, s12, 0x2000
	v_lshl_add_u64 v[102:103], s[0:1], 0, v[138:139]
	s_add_u32 s0, s44, 0x14000
	s_addc_u32 s1, s45, 0
	s_add_i32 s12, s53, s17
	global_load_lds_dwordx4 v[102:103], off
	s_mov_b32 m0, s12
	v_lshl_add_u64 v[148:149], s[46:47], 0, v[132:133]
	global_load_lds_dwordx4 v134, s[0:1]
	s_add_i32 m0, s12, 0x2000
	v_lshl_add_u64 v[144:145], s[46:47], 0, v[136:137]
	global_load_lds_dwordx4 v138, s[0:1]
	s_mov_b32 m0, s18
	v_lshl_add_u64 v[102:103], v[148:149], 0, s[38:39]
	global_load_lds_dwordx4 v[102:103], off
	s_mov_b32 m0, s19
	v_lshl_add_u64 v[102:103], v[144:145], 0, s[38:39]
	global_load_lds_dwordx4 v[102:103], off
	s_waitcnt vmcnt(24) lgkmcnt(0)
	s_barrier
	v_mfma_f32_16x16x32_bf16 v[158:161], v[2:5], v[62:65], 0
	v_mfma_f32_16x16x32_bf16 v[166:169], v[2:5], v[98:101], 0
	v_mfma_f32_16x16x32_bf16 v[174:177], v[2:5], v[116:119], 0
	v_mfma_f32_16x16x32_bf16 v[2:5], v[2:5], v[124:127], 0
	v_mfma_f32_16x16x32_bf16 v[158:161], v[6:9], v[94:97], v[158:161]
	v_mfma_f32_16x16x32_bf16 v[166:169], v[6:9], v[112:115], v[166:169]
	v_mfma_f32_16x16x32_bf16 v[174:177], v[6:9], v[120:123], v[174:177]
	v_mfma_f32_16x16x32_bf16 v[2:5], v[6:9], v[128:131], v[2:5]
	v_mfma_f32_16x16x32_bf16 v[6:9], v[10:13], v[124:127], 0
	v_mfma_f32_16x16x32_bf16 v[162:165], v[10:13], v[62:65], 0
	v_mfma_f32_16x16x32_bf16 v[170:173], v[10:13], v[98:101], 0
	v_mfma_f32_16x16x32_bf16 v[178:181], v[10:13], v[116:119], 0
	v_mfma_f32_16x16x32_bf16 v[6:9], v[14:17], v[128:131], v[6:9]
	v_mfma_f32_16x16x32_bf16 v[162:165], v[14:17], v[94:97], v[162:165]
	v_mfma_f32_16x16x32_bf16 v[170:173], v[14:17], v[112:115], v[170:173]
	v_mfma_f32_16x16x32_bf16 v[178:181], v[14:17], v[120:123], v[178:181]
	v_mfma_f32_16x16x32_bf16 v[14:17], v[26:29], v[62:65], 0
	v_mfma_f32_16x16x32_bf16 v[182:185], v[30:33], v[94:97], v[14:17]
	v_mfma_f32_16x16x32_bf16 v[14:17], v[18:21], v[98:101], 0
	v_mfma_f32_16x16x32_bf16 v[186:189], v[22:25], v[112:115], v[14:17]
	v_mfma_f32_16x16x32_bf16 v[14:17], v[26:29], v[98:101], 0
	v_mfma_f32_16x16x32_bf16 v[190:193], v[30:33], v[112:115], v[14:17]
	v_mfma_f32_16x16x32_bf16 v[14:17], v[18:21], v[116:119], 0
	v_mfma_f32_16x16x32_bf16 v[194:197], v[22:25], v[120:123], v[14:17]
	v_mfma_f32_16x16x32_bf16 v[14:17], v[26:29], v[116:119], 0
	v_mfma_f32_16x16x32_bf16 v[10:13], v[18:21], v[62:65], 0
	v_mfma_f32_16x16x32_bf16 v[198:201], v[30:33], v[120:123], v[14:17]
	v_mfma_f32_16x16x32_bf16 v[14:17], v[18:21], v[124:127], 0
	v_mfma_f32_16x16x32_bf16 v[10:13], v[22:25], v[94:97], v[10:13]
	v_mfma_f32_16x16x32_bf16 v[202:205], v[22:25], v[128:131], v[14:17]
	v_mfma_f32_16x16x32_bf16 v[14:17], v[26:29], v[124:127], 0
	v_mfma_f32_16x16x32_bf16 v[206:209], v[30:33], v[128:131], v[14:17]
	s_barrier
	s_add_i32 s12, 0, 0x18000
	v_add_u32_e32 v1, s12, v151
	s_add_i32 s13, 0, 0x1c000
	s_nop 1
	ds_read_b128 v[14:17], v1
	ds_read_b128 v[24:27], v1 offset:1024
	ds_read_b128 v[28:31], v1 offset:2048
	ds_read_b128 v[210:213], v1 offset:3072
	v_add_u32_e32 v1, s13, v151
	ds_read_b128 v[214:217], v1
	ds_read_b128 v[218:221], v1 offset:1024
	ds_read_b128 v[222:225], v1 offset:2048
	ds_read_b128 v[226:229], v1 offset:3072
	s_add_u32 s0, s46, 0x2b0100
	s_addc_u32 s1, s47, 0
	s_mov_b32 m0, s20
	ds_read_b128 v[18:21], v155 offset:32768
	ds_read_b128 v[120:123], v155 offset:33792
	ds_read_b128 v[230:233], v155 offset:34816
	ds_read_b128 v[234:237], v155 offset:35840
	ds_read_b128 v[238:241], v155 offset:36864
	ds_read_b128 v[242:245], v155 offset:37888
	ds_read_b128 v[246:249], v155 offset:38912
	ds_read_b128 v[250:253], v155 offset:39936
	global_load_lds_dwordx4 v132, s[0:1]
	s_mov_b32 m0, s21
	s_nop 0
	global_load_lds_dwordx4 v136, s[0:1]
	s_waitcnt vmcnt(24) lgkmcnt(0)
	s_barrier
	v_mfma_f32_16x16x32_bf16 v[62:65], v[14:17], v[18:21], v[66:69]
	v_mfma_f32_16x16x32_bf16 v[128:131], v[24:27], v[120:123], v[62:65]
	v_mfma_f32_16x16x32_bf16 v[62:65], v[28:31], v[18:21], v[70:73]
	v_mfma_f32_16x16x32_bf16 v[116:119], v[210:213], v[120:123], v[62:65]
	v_mfma_f32_16x16x32_bf16 v[62:65], v[14:17], v[230:233], v[74:77]
	v_mfma_f32_16x16x32_bf16 v[112:115], v[24:27], v[234:237], v[62:65]
	v_mfma_f32_16x16x32_bf16 v[62:65], v[28:31], v[230:233], v[78:81]
	v_mfma_f32_16x16x32_bf16 v[100:103], v[210:213], v[234:237], v[62:65]
	v_mfma_f32_16x16x32_bf16 v[62:65], v[14:17], v[238:241], v[82:85]
	v_mfma_f32_16x16x32_bf16 v[96:99], v[24:27], v[242:245], v[62:65]
	v_mfma_f32_16x16x32_bf16 v[62:65], v[28:31], v[238:241], v[86:89]
	v_mfma_f32_16x16x32_bf16 v[84:87], v[210:213], v[242:245], v[62:65]
	v_mfma_f32_16x16x32_bf16 v[62:65], v[14:17], v[246:249], v[90:93]
	v_mfma_f32_16x16x32_bf16 v[80:83], v[24:27], v[250:253], v[62:65]
	v_mfma_f32_16x16x32_bf16 v[62:65], v[28:31], v[246:249], v[104:107]
	v_mfma_f32_16x16x32_bf16 v[64:67], v[210:213], v[250:253], v[62:65]
	v_mfma_f32_16x16x32_bf16 v[68:71], v[214:217], v[18:21], v[108:111]
	v_mfma_f32_16x16x32_bf16 v[18:21], v[222:225], v[18:21], v[34:37]
	v_mfma_f32_16x16x32_bf16 v[124:127], v[218:221], v[120:123], v[68:71]
	v_mfma_f32_16x16x32_bf16 v[120:123], v[226:229], v[120:123], v[18:21]
	v_mfma_f32_16x16x32_bf16 v[18:21], v[214:217], v[230:233], v[38:41]
	v_mfma_f32_16x16x32_bf16 v[108:111], v[218:221], v[234:237], v[18:21]
	v_mfma_f32_16x16x32_bf16 v[18:21], v[222:225], v[230:233], v[42:45]
	v_mfma_f32_16x16x32_bf16 v[104:107], v[226:229], v[234:237], v[18:21]
	v_mfma_f32_16x16x32_bf16 v[18:21], v[214:217], v[238:241], v[46:49]
	v_mfma_f32_16x16x32_bf16 v[92:95], v[218:221], v[242:245], v[18:21]
	v_mfma_f32_16x16x32_bf16 v[18:21], v[222:225], v[238:241], v[50:53]
	v_mfma_f32_16x16x32_bf16 v[88:91], v[226:229], v[242:245], v[18:21]
	v_mfma_f32_16x16x32_bf16 v[18:21], v[214:217], v[246:249], v[54:57]
	v_mfma_f32_16x16x32_bf16 v[72:75], v[218:221], v[250:253], v[18:21]
	v_mfma_f32_16x16x32_bf16 v[18:21], v[222:225], v[246:249], v[58:61]
	v_mfma_f32_16x16x32_bf16 v[68:71], v[226:229], v[250:253], v[18:21]
	s_barrier
	s_add_u32 s0, s44, 0x18000
	s_addc_u32 s1, s45, 0
	s_add_i32 s12, s12, s17
	s_nop 1
	s_mov_b32 m0, s12
	ds_read_b128 v[40:43], v155 offset:49152
	ds_read_b128 v[44:47], v155 offset:50176
	ds_read_b128 v[230:233], v155 offset:51200
	ds_read_b128 v[234:237], v155 offset:52224
	ds_read_b128 v[238:241], v155 offset:53248
	ds_read_b128 v[242:245], v155 offset:54272
	ds_read_b128 v[246:249], v155 offset:55296
	ds_read_b128 v[250:253], v155 offset:56320
	global_load_lds_dwordx4 v134, s[0:1]
	s_add_i32 m0, s12, 0x2000
	v_lshl_add_u64 v[18:19], s[0:1], 0, v[138:139]
	s_add_u32 s0, s44, 0x1c000
	s_addc_u32 s1, s45, 0
	s_add_i32 s12, s13, s17
	global_load_lds_dwordx4 v[18:19], off
	s_mov_b32 m0, s12
	s_nop 0
	global_load_lds_dwordx4 v134, s[0:1]
	s_add_i32 m0, s12, 0x2000
	s_nop 0
	global_load_lds_dwordx4 v138, s[0:1]
	s_mov_b32 m0, s48
	v_lshl_add_u64 v[18:19], v[148:149], 0, s[40:41]
	global_load_lds_dwordx4 v[18:19], off
	s_mov_b32 m0, s49
	v_lshl_add_u64 v[18:19], v[144:145], 0, s[40:41]
	global_load_lds_dwordx4 v[18:19], off
	s_waitcnt vmcnt(8) lgkmcnt(0)
	s_barrier
	v_mfma_f32_16x16x32_bf16 v[18:21], v[14:17], v[40:43], v[158:161]
	v_mfma_f32_16x16x32_bf16 v[76:79], v[24:27], v[44:47], v[18:21]
	v_mfma_f32_16x16x32_bf16 v[18:21], v[28:31], v[40:43], v[162:165]
	v_mfma_f32_16x16x32_bf16 v[52:55], v[210:213], v[44:47], v[18:21]
	v_mfma_f32_16x16x32_bf16 v[18:21], v[14:17], v[230:233], v[166:169]
	v_mfma_f32_16x16x32_bf16 v[48:51], v[24:27], v[234:237], v[18:21]
	v_mfma_f32_16x16x32_bf16 v[18:21], v[28:31], v[230:233], v[170:173]
	v_mfma_f32_16x16x32_bf16 v[36:39], v[210:213], v[234:237], v[18:21]
	v_mfma_f32_16x16x32_bf16 v[18:21], v[14:17], v[238:241], v[174:177]
	v_mfma_f32_16x16x32_bf16 v[32:35], v[24:27], v[242:245], v[18:21]
	v_mfma_f32_16x16x32_bf16 v[18:21], v[28:31], v[238:241], v[178:181]
	v_mfma_f32_16x16x32_bf16 v[2:5], v[14:17], v[246:249], v[2:5]
	v_mfma_f32_16x16x32_bf16 v[20:23], v[210:213], v[242:245], v[18:21]
	v_mfma_f32_16x16x32_bf16 v[16:19], v[24:27], v[250:253], v[2:5]
	v_mfma_f32_16x16x32_bf16 v[2:5], v[28:31], v[246:249], v[6:9]
	v_mfma_f32_16x16x32_bf16 v[4:7], v[210:213], v[250:253], v[2:5]
	v_mfma_f32_16x16x32_bf16 v[8:11], v[214:217], v[40:43], v[10:13]
	v_mfma_f32_16x16x32_bf16 v[60:63], v[218:221], v[44:47], v[8:11]
	v_mfma_f32_16x16x32_bf16 v[8:11], v[222:225], v[40:43], v[182:185]
	v_mfma_f32_16x16x32_bf16 v[56:59], v[226:229], v[44:47], v[8:11]
	v_mfma_f32_16x16x32_bf16 v[8:11], v[214:217], v[230:233], v[186:189]
	v_mfma_f32_16x16x32_bf16 v[44:47], v[218:221], v[234:237], v[8:11]
	v_mfma_f32_16x16x32_bf16 v[8:11], v[222:225], v[230:233], v[190:193]
	v_mfma_f32_16x16x32_bf16 v[40:43], v[226:229], v[234:237], v[8:11]
	v_mfma_f32_16x16x32_bf16 v[8:11], v[214:217], v[238:241], v[194:197]
	v_mfma_f32_16x16x32_bf16 v[28:31], v[218:221], v[242:245], v[8:11]
	v_mfma_f32_16x16x32_bf16 v[8:11], v[222:225], v[238:241], v[198:201]
	v_mfma_f32_16x16x32_bf16 v[24:27], v[226:229], v[242:245], v[8:11]
	v_mfma_f32_16x16x32_bf16 v[8:11], v[214:217], v[246:249], v[202:205]
	v_mfma_f32_16x16x32_bf16 v[12:15], v[218:221], v[250:253], v[8:11]
	v_mfma_f32_16x16x32_bf16 v[8:11], v[222:225], v[246:249], v[206:209]
	v_mfma_f32_16x16x32_bf16 v[8:11], v[226:229], v[250:253], v[8:11]
	s_barrier
	s_mov_b32 s22, 2
	s_branch .LBB0_1733

.LBB0_1734:
	ds_read_b128 v[158:161], v153
	ds_read_b128 v[162:165], v153 offset:1024
	ds_read_b128 v[166:169], v153 offset:2048
	ds_read_b128 v[170:173], v153 offset:3072
	ds_read_b128 v[174:177], v154
	ds_read_b128 v[178:181], v154 offset:1024
	ds_read_b128 v[182:185], v154 offset:2048
	ds_read_b128 v[186:189], v154 offset:3072
	s_add_u32 s12, s60, s24
	s_addc_u32 s13, s61, 0
	s_cmp_eq_u32 s24, s44
	s_cselect_b32 s23, s9, s13
	s_cselect_b32 s22, s8, s12
	s_cselect_b32 s47, s43, s59
	s_cselect_b32 s46, s42, s1
	s_add_i32 s63, s18, 0xc000
	v_lshl_add_u64 v[144:145], v[2:3], 0, s[24:25]
	s_mov_b32 m0, s63
	s_add_i32 s62, s18, 0xe000
	ds_read_b128 v[190:193], v155
	ds_read_b128 v[194:197], v155 offset:1024
	ds_read_b128 v[198:201], v155 offset:2048
	ds_read_b128 v[202:205], v155 offset:3072
	ds_read_b128 v[206:209], v155 offset:4096
	ds_read_b128 v[210:213], v155 offset:5120
	ds_read_b128 v[214:217], v155 offset:6144
	ds_read_b128 v[218:221], v155 offset:7168
	global_load_lds_dwordx4 v[144:145], off
	s_mov_b32 m0, s62
	v_lshl_add_u64 v[144:145], v[148:149], 0, s[24:25]
	global_load_lds_dwordx4 v[144:145], off
	s_waitcnt vmcnt(8) lgkmcnt(0)
	s_barrier
	v_mfma_f32_16x16x32_bf16 v[128:131], v[158:161], v[190:193], v[128:131]
	v_mfma_f32_16x16x32_bf16 v[128:131], v[162:165], v[194:197], v[128:131]
	v_mfma_f32_16x16x32_bf16 v[116:119], v[166:169], v[190:193], v[116:119]
	v_mfma_f32_16x16x32_bf16 v[116:119], v[170:173], v[194:197], v[116:119]
	v_mfma_f32_16x16x32_bf16 v[100:103], v[166:169], v[198:201], v[100:103]
	v_mfma_f32_16x16x32_bf16 v[100:103], v[170:173], v[202:205], v[100:103]
	v_mfma_f32_16x16x32_bf16 v[112:115], v[158:161], v[198:201], v[112:115]
	v_mfma_f32_16x16x32_bf16 v[112:115], v[162:165], v[202:205], v[112:115]
	v_mfma_f32_16x16x32_bf16 v[96:99], v[158:161], v[206:209], v[96:99]
	v_mfma_f32_16x16x32_bf16 v[96:99], v[162:165], v[210:213], v[96:99]
	v_mfma_f32_16x16x32_bf16 v[84:87], v[166:169], v[206:209], v[84:87]
	v_mfma_f32_16x16x32_bf16 v[84:87], v[170:173], v[210:213], v[84:87]
	v_mfma_f32_16x16x32_bf16 v[64:67], v[166:169], v[214:217], v[64:67]
	v_mfma_f32_16x16x32_bf16 v[64:67], v[170:173], v[218:221], v[64:67]
	v_mfma_f32_16x16x32_bf16 v[80:83], v[158:161], v[214:217], v[80:83]
	v_mfma_f32_16x16x32_bf16 v[80:83], v[162:165], v[218:221], v[80:83]
	v_mfma_f32_16x16x32_bf16 v[72:75], v[174:177], v[214:217], v[72:75]
	v_mfma_f32_16x16x32_bf16 v[72:75], v[178:181], v[218:221], v[72:75]
	v_mfma_f32_16x16x32_bf16 v[68:71], v[182:185], v[214:217], v[68:71]
	v_mfma_f32_16x16x32_bf16 v[68:71], v[186:189], v[218:221], v[68:71]
	v_mfma_f32_16x16x32_bf16 v[88:91], v[182:185], v[206:209], v[88:91]
	v_mfma_f32_16x16x32_bf16 v[88:91], v[186:189], v[210:213], v[88:91]
	v_mfma_f32_16x16x32_bf16 v[92:95], v[174:177], v[206:209], v[92:95]
	v_mfma_f32_16x16x32_bf16 v[92:95], v[178:181], v[210:213], v[92:95]
	v_mfma_f32_16x16x32_bf16 v[108:111], v[174:177], v[198:201], v[108:111]
	v_mfma_f32_16x16x32_bf16 v[108:111], v[178:181], v[202:205], v[108:111]
	v_mfma_f32_16x16x32_bf16 v[104:107], v[182:185], v[198:201], v[104:107]
	v_mfma_f32_16x16x32_bf16 v[104:107], v[186:189], v[202:205], v[104:107]
	v_mfma_f32_16x16x32_bf16 v[120:123], v[182:185], v[190:193], v[120:123]
	v_mfma_f32_16x16x32_bf16 v[120:123], v[186:189], v[194:197], v[120:123]
	v_mfma_f32_16x16x32_bf16 v[124:127], v[174:177], v[190:193], v[124:127]
	v_mfma_f32_16x16x32_bf16 v[124:127], v[178:181], v[194:197], v[124:127]
	s_barrier
	s_add_i32 s12, s52, s17
	s_mov_b32 m0, s12
	ds_read_b128 v[190:193], v155 offset:16384
	ds_read_b128 v[194:197], v155 offset:17408
	ds_read_b128 v[198:201], v155 offset:18432
	ds_read_b128 v[202:205], v155 offset:19456
	ds_read_b128 v[206:209], v155 offset:20480
	ds_read_b128 v[210:213], v155 offset:21504
	ds_read_b128 v[214:217], v155 offset:22528
	ds_read_b128 v[218:221], v155 offset:23552
	global_load_lds_dwordx4 v134, s[46:47]
	s_add_i32 m0, s12, 0x2000
	s_add_u32 s12, s46, 0x4000
	s_addc_u32 s13, s47, 0
	s_add_i32 s14, s53, s17
	global_load_lds_dwordx4 v138, s[46:47]
	s_mov_b32 m0, s14
	v_lshl_add_u64 v[222:223], s[22:23], 0, v[136:137]
	global_load_lds_dwordx4 v134, s[12:13]
	s_add_i32 m0, s14, 0x2000
	s_nop 0
	global_load_lds_dwordx4 v138, s[12:13]
	s_mov_b32 m0, s18
	v_lshl_add_u64 v[144:145], s[22:23], 0, v[132:133]
	global_load_lds_dwordx4 v[144:145], off
	s_mov_b32 m0, s19
	s_nop 0
	global_load_lds_dwordx4 v[222:223], off
	s_waitcnt vmcnt(8) lgkmcnt(0)
	s_barrier
	v_mfma_f32_16x16x32_bf16 v[76:79], v[158:161], v[190:193], v[76:79]
	v_mfma_f32_16x16x32_bf16 v[76:79], v[162:165], v[194:197], v[76:79]
	v_mfma_f32_16x16x32_bf16 v[52:55], v[166:169], v[190:193], v[52:55]
	v_mfma_f32_16x16x32_bf16 v[52:55], v[170:173], v[194:197], v[52:55]
	v_mfma_f32_16x16x32_bf16 v[36:39], v[166:169], v[198:201], v[36:39]
	v_mfma_f32_16x16x32_bf16 v[36:39], v[170:173], v[202:205], v[36:39]
	v_mfma_f32_16x16x32_bf16 v[48:51], v[158:161], v[198:201], v[48:51]
	v_mfma_f32_16x16x32_bf16 v[48:51], v[162:165], v[202:205], v[48:51]
	v_mfma_f32_16x16x32_bf16 v[32:35], v[158:161], v[206:209], v[32:35]
	v_mfma_f32_16x16x32_bf16 v[32:35], v[162:165], v[210:213], v[32:35]
	v_mfma_f32_16x16x32_bf16 v[20:23], v[166:169], v[206:209], v[20:23]
	v_mfma_f32_16x16x32_bf16 v[20:23], v[170:173], v[210:213], v[20:23]
	v_mfma_f32_16x16x32_bf16 v[4:7], v[166:169], v[214:217], v[4:7]
	v_mfma_f32_16x16x32_bf16 v[4:7], v[170:173], v[218:221], v[4:7]
	v_mfma_f32_16x16x32_bf16 v[16:19], v[158:161], v[214:217], v[16:19]
	v_mfma_f32_16x16x32_bf16 v[16:19], v[162:165], v[218:221], v[16:19]
	v_mfma_f32_16x16x32_bf16 v[12:15], v[174:177], v[214:217], v[12:15]
	v_mfma_f32_16x16x32_bf16 v[12:15], v[178:181], v[218:221], v[12:15]
	v_mfma_f32_16x16x32_bf16 v[8:11], v[182:185], v[214:217], v[8:11]
	v_mfma_f32_16x16x32_bf16 v[8:11], v[186:189], v[218:221], v[8:11]
	v_mfma_f32_16x16x32_bf16 v[24:27], v[182:185], v[206:209], v[24:27]
	v_mfma_f32_16x16x32_bf16 v[24:27], v[186:189], v[210:213], v[24:27]
	v_mfma_f32_16x16x32_bf16 v[28:31], v[174:177], v[206:209], v[28:31]
	v_mfma_f32_16x16x32_bf16 v[28:31], v[178:181], v[210:213], v[28:31]
	v_mfma_f32_16x16x32_bf16 v[44:47], v[174:177], v[198:201], v[44:47]
	v_mfma_f32_16x16x32_bf16 v[44:47], v[178:181], v[202:205], v[44:47]
	v_mfma_f32_16x16x32_bf16 v[40:43], v[182:185], v[198:201], v[40:43]
	v_mfma_f32_16x16x32_bf16 v[40:43], v[186:189], v[202:205], v[40:43]
	v_mfma_f32_16x16x32_bf16 v[56:59], v[182:185], v[190:193], v[56:59]
	v_mfma_f32_16x16x32_bf16 v[56:59], v[186:189], v[194:197], v[56:59]
	v_mfma_f32_16x16x32_bf16 v[60:63], v[174:177], v[190:193], v[60:63]
	v_mfma_f32_16x16x32_bf16 v[60:63], v[178:181], v[194:197], v[60:63]
	s_barrier
	s_add_i32 s14, 0, 0x18000
	v_add_u32_e32 v1, s14, v151
	s_add_i32 s64, 0, 0x1c000
	ds_read_b128 v[158:161], v1
	ds_read_b128 v[162:165], v1 offset:1024
	ds_read_b128 v[166:169], v1 offset:2048
	ds_read_b128 v[170:173], v1 offset:3072
	v_add_u32_e32 v1, s64, v151
	ds_read_b128 v[174:177], v1
	ds_read_b128 v[178:181], v1 offset:1024
	ds_read_b128 v[182:185], v1 offset:2048
	ds_read_b128 v[186:189], v1 offset:3072
	s_add_u32 s12, s22, 0x2b0000
	s_addc_u32 s13, s23, 0
	s_mov_b32 m0, s20
	ds_read_b128 v[190:193], v155 offset:32768
	ds_read_b128 v[194:197], v155 offset:33792
	ds_read_b128 v[198:201], v155 offset:34816
	ds_read_b128 v[202:205], v155 offset:35840
	ds_read_b128 v[206:209], v155 offset:36864
	ds_read_b128 v[210:213], v155 offset:37888
	ds_read_b128 v[214:217], v155 offset:38912
	ds_read_b128 v[218:221], v155 offset:39936
	global_load_lds_dwordx4 v132, s[12:13]
	s_mov_b32 m0, s21
	s_nop 0
	global_load_lds_dwordx4 v136, s[12:13]
	s_waitcnt vmcnt(8) lgkmcnt(0)
	s_barrier
	v_mfma_f32_16x16x32_bf16 v[128:131], v[158:161], v[190:193], v[128:131]
	v_mfma_f32_16x16x32_bf16 v[128:131], v[162:165], v[194:197], v[128:131]
	v_mfma_f32_16x16x32_bf16 v[116:119], v[166:169], v[190:193], v[116:119]
	v_mfma_f32_16x16x32_bf16 v[116:119], v[170:173], v[194:197], v[116:119]
	v_mfma_f32_16x16x32_bf16 v[100:103], v[166:169], v[198:201], v[100:103]
	v_mfma_f32_16x16x32_bf16 v[100:103], v[170:173], v[202:205], v[100:103]
	v_mfma_f32_16x16x32_bf16 v[112:115], v[158:161], v[198:201], v[112:115]
	v_mfma_f32_16x16x32_bf16 v[112:115], v[162:165], v[202:205], v[112:115]
	v_mfma_f32_16x16x32_bf16 v[96:99], v[158:161], v[206:209], v[96:99]
	v_mfma_f32_16x16x32_bf16 v[96:99], v[162:165], v[210:213], v[96:99]
	v_mfma_f32_16x16x32_bf16 v[84:87], v[166:169], v[206:209], v[84:87]
	v_mfma_f32_16x16x32_bf16 v[84:87], v[170:173], v[210:213], v[84:87]
	v_mfma_f32_16x16x32_bf16 v[64:67], v[166:169], v[214:217], v[64:67]
	v_mfma_f32_16x16x32_bf16 v[64:67], v[170:173], v[218:221], v[64:67]
	v_mfma_f32_16x16x32_bf16 v[80:83], v[158:161], v[214:217], v[80:83]
	v_mfma_f32_16x16x32_bf16 v[80:83], v[162:165], v[218:221], v[80:83]
	v_mfma_f32_16x16x32_bf16 v[72:75], v[174:177], v[214:217], v[72:75]
	v_mfma_f32_16x16x32_bf16 v[72:75], v[178:181], v[218:221], v[72:75]
	v_mfma_f32_16x16x32_bf16 v[68:71], v[182:185], v[214:217], v[68:71]
	v_mfma_f32_16x16x32_bf16 v[68:71], v[186:189], v[218:221], v[68:71]
	v_mfma_f32_16x16x32_bf16 v[88:91], v[182:185], v[206:209], v[88:91]
	v_mfma_f32_16x16x32_bf16 v[88:91], v[186:189], v[210:213], v[88:91]
	v_mfma_f32_16x16x32_bf16 v[92:95], v[174:177], v[206:209], v[92:95]
	v_mfma_f32_16x16x32_bf16 v[92:95], v[178:181], v[210:213], v[92:95]
	v_mfma_f32_16x16x32_bf16 v[108:111], v[174:177], v[198:201], v[108:111]
	v_mfma_f32_16x16x32_bf16 v[108:111], v[178:181], v[202:205], v[108:111]
	v_mfma_f32_16x16x32_bf16 v[104:107], v[182:185], v[198:201], v[104:107]
	v_mfma_f32_16x16x32_bf16 v[104:107], v[186:189], v[202:205], v[104:107]
	v_mfma_f32_16x16x32_bf16 v[120:123], v[182:185], v[190:193], v[120:123]
	v_mfma_f32_16x16x32_bf16 v[120:123], v[186:189], v[194:197], v[120:123]
	v_mfma_f32_16x16x32_bf16 v[124:127], v[174:177], v[190:193], v[124:127]
	v_mfma_f32_16x16x32_bf16 v[124:127], v[178:181], v[194:197], v[124:127]
	s_barrier
	s_add_u32 s12, s46, 0x8000
	s_addc_u32 s13, s47, 0
	s_add_i32 s14, s14, s17
	s_mov_b32 m0, s14
	ds_read_b128 v[190:193], v155 offset:49152
	ds_read_b128 v[194:197], v155 offset:50176
	ds_read_b128 v[198:201], v155 offset:51200
	ds_read_b128 v[202:205], v155 offset:52224
	ds_read_b128 v[206:209], v155 offset:53248
	ds_read_b128 v[210:213], v155 offset:54272
	ds_read_b128 v[214:217], v155 offset:55296
	ds_read_b128 v[218:221], v155 offset:56320
	global_load_lds_dwordx4 v134, s[12:13]
	s_add_i32 m0, s14, 0x2000
	v_lshl_add_u64 v[224:225], s[12:13], 0, v[138:139]
	s_add_u32 s12, s46, 0xc000
	s_addc_u32 s13, s47, 0
	s_add_i32 s14, s64, s17
	global_load_lds_dwordx4 v[224:225], off
	s_mov_b32 m0, s14
	v_lshl_add_u64 v[144:145], v[144:145], 0, s[34:35]
	global_load_lds_dwordx4 v134, s[12:13]
	s_add_i32 m0, s14, 0x2000
	s_nop 0
	global_load_lds_dwordx4 v138, s[12:13]
	s_mov_b32 m0, s48
	s_nop 0
	global_load_lds_dwordx4 v[144:145], off
	s_mov_b32 m0, s49
	v_lshl_add_u64 v[144:145], v[222:223], 0, s[34:35]
	global_load_lds_dwordx4 v[144:145], off
	s_waitcnt vmcnt(8) lgkmcnt(0)
	s_barrier
	v_mfma_f32_16x16x32_bf16 v[76:79], v[158:161], v[190:193], v[76:79]
	v_mfma_f32_16x16x32_bf16 v[76:79], v[162:165], v[194:197], v[76:79]
	v_mfma_f32_16x16x32_bf16 v[52:55], v[166:169], v[190:193], v[52:55]
	v_mfma_f32_16x16x32_bf16 v[52:55], v[170:173], v[194:197], v[52:55]
	v_mfma_f32_16x16x32_bf16 v[36:39], v[166:169], v[198:201], v[36:39]
	v_mfma_f32_16x16x32_bf16 v[36:39], v[170:173], v[202:205], v[36:39]
	v_mfma_f32_16x16x32_bf16 v[48:51], v[158:161], v[198:201], v[48:51]
	v_mfma_f32_16x16x32_bf16 v[48:51], v[162:165], v[202:205], v[48:51]
	v_mfma_f32_16x16x32_bf16 v[32:35], v[158:161], v[206:209], v[32:35]
	v_mfma_f32_16x16x32_bf16 v[32:35], v[162:165], v[210:213], v[32:35]
	v_mfma_f32_16x16x32_bf16 v[20:23], v[166:169], v[206:209], v[20:23]
	v_mfma_f32_16x16x32_bf16 v[20:23], v[170:173], v[210:213], v[20:23]
	v_mfma_f32_16x16x32_bf16 v[4:7], v[166:169], v[214:217], v[4:7]
	v_mfma_f32_16x16x32_bf16 v[4:7], v[170:173], v[218:221], v[4:7]
	v_mfma_f32_16x16x32_bf16 v[16:19], v[158:161], v[214:217], v[16:19]
	v_mfma_f32_16x16x32_bf16 v[16:19], v[162:165], v[218:221], v[16:19]
	v_mfma_f32_16x16x32_bf16 v[12:15], v[174:177], v[214:217], v[12:15]
	v_mfma_f32_16x16x32_bf16 v[12:15], v[178:181], v[218:221], v[12:15]
	v_mfma_f32_16x16x32_bf16 v[8:11], v[182:185], v[214:217], v[8:11]
	v_mfma_f32_16x16x32_bf16 v[8:11], v[186:189], v[218:221], v[8:11]
	v_mfma_f32_16x16x32_bf16 v[24:27], v[182:185], v[206:209], v[24:27]
	v_mfma_f32_16x16x32_bf16 v[24:27], v[186:189], v[210:213], v[24:27]
	v_mfma_f32_16x16x32_bf16 v[28:31], v[174:177], v[206:209], v[28:31]
	v_mfma_f32_16x16x32_bf16 v[28:31], v[178:181], v[210:213], v[28:31]
	v_mfma_f32_16x16x32_bf16 v[44:47], v[174:177], v[198:201], v[44:47]
	v_mfma_f32_16x16x32_bf16 v[44:47], v[178:181], v[202:205], v[44:47]
	v_mfma_f32_16x16x32_bf16 v[40:43], v[182:185], v[198:201], v[40:43]
	v_mfma_f32_16x16x32_bf16 v[40:43], v[186:189], v[202:205], v[40:43]
	v_mfma_f32_16x16x32_bf16 v[56:59], v[182:185], v[190:193], v[56:59]
	v_mfma_f32_16x16x32_bf16 v[56:59], v[186:189], v[194:197], v[56:59]
	v_mfma_f32_16x16x32_bf16 v[60:63], v[174:177], v[190:193], v[60:63]
	v_mfma_f32_16x16x32_bf16 v[60:63], v[178:181], v[194:197], v[60:63]
	s_barrier
	s_add_i32 s0, s0, 2
	s_add_u32 s1, s1, 0x10000
	s_addc_u32 s59, s59, 0
	s_add_u32 s60, s60, 0x100
	s_addc_u32 s61, s61, 0
	s_add_u32 s44, s44, 0xffffff00
	s_addc_u32 s45, s45, -1
	v_lshl_add_u64 v[2:3], v[2:3], 0, s[38:39]
	s_cmpk_gt_u32 s0, 0xa9
	v_lshl_add_u64 v[148:149], v[148:149], 0, s[38:39]
	s_cbranch_scc0 .LBB0_1734
	s_and_b64 vcc, exec, s[36:37]
	s_cbranch_vccz .LBB0_1737
	s_barrier
